# core also in phase 1 (in_even, memK, memV): 10 GEMM mainloops now LDS-DMA 3-stage
# speedup vs baseline: 1.0672x; 1.0186x over previous
; DI bfr f2bf(float a) { return (bfr)(pack2(a, 0.f) & 0xffffu); }
; DI int crow(int reg, int h) { return (reg & 3) + 8 * (reg >> 2) + 4 * h; }
; template <int lda, class Epi>
; DI void gemm_tile(const bfr* __restrict__ A, const bfr* __restrict__ Bt, int NB, int K, int m0, int n0, char* smem, Epi epi) {
;     ...
;   int tid3 = threadIdx.x;
;   asm volatile("" : "+v"(tid3));
;   const int lane = tid3 & 63, wid = tid3 >> 6, wr = wid >> 1, wc = wid & 1, r = lane & 31, hl = lane >> 5;
; #pragma unroll
;   for (int i = 0; i < 2; ++i)
; #pragma unroll
;     for (int j = 0; j < 4; ++j)
; #pragma unroll
;       for (int q = 0; q < 16; ++q) {
;         int row = m0 + wr * 64 + i * 32 + crow(q, hl);
;         int col = n0 + wc * 128 + j * 32 + r;
;         epi(row, col, acc[i][j][q]);
;       }
; DI void phase_gemm_in_even(const Params& p, char* smem) {
;     ...
;       gemm_tile<1024>(p.H, p.WtInE, 3712, 1024, mt * 128, nt * 256, smem,
;                 [=](int row, int col, float v) { PB[(size_t)row * EINP + col] = f2bf(v); });
.LBB0_118:
	s_nop 0
	s_waitcnt vmcnt(1)
	s_nop 0
	s_nop 0
	s_nop 0
	s_waitcnt vmcnt(0)
	s_nop 0
	v_add_u32_e32 v160, v171, v173
	s_nop 0
	v_add_u32_e32 v194, v171, v172
	s_nop 0
	s_nop 0
	s_nop 0
	s_nop 0
	s_nop 0
	s_nop 0
	s_nop 0
	s_nop 0
	s_nop 0
	s_nop 0
	s_nop 0
	s_waitcnt lgkmcnt(0)
	s_nop 0
	s_nop 0
	s_nop 0
	s_nop 0
	s_nop 0
	s_nop 0
	s_nop 0
	s_nop 0
	s_nop 0
	s_nop 0
	s_nop 0
	s_nop 0
	s_nop 0
	s_nop 0
	v_mov_b32_e32 v160, v196
	s_nop 0
	s_nop 0
	s_nop 0
	s_nop 0
	s_waitcnt lgkmcnt(0)
	s_nop 0
	s_nop 0
	v_and_b32_e32 v194, 31, v160
	v_ashrrev_i32_e32 v195, 1, v160
	v_lshrrev_b32_e32 v197, 3, v160
	v_lshlrev_b32_e32 v160, 1, v160
	v_and_b32_e32 v195, 0xffffffc0, v195
	v_and_b32_e32 v160, 0x80, v160
	v_add_u32_e32 v195, s56, v195
	s_nop 0
	v_or3_b32 v194, v194, v160, s2
	v_and_or_b32 v197, v197, 4, v195
	v_ashrrev_i32_e32 v195, 31, v194
	v_lshl_add_u64 v[194:195], v[194:195], 1, s[18:19]
	s_nop 0
	s_nop 6
	v_cvt_pk_bf16_f32 v112, v112, s0
	v_mad_i64_i32 v[132:133], s[0:1], v197, s53, v[194:195]
	global_store_short v[132:133], v112, off
	v_or_b32_e32 v112, 1, v197
	v_cvt_pk_bf16_f32 v134, v113, s0
	v_mad_i64_i32 v[112:113], s[0:1], v112, s53, v[194:195]
	global_store_short v[112:113], v134, off
	v_or_b32_e32 v134, 2, v197
	v_cvt_pk_bf16_f32 v114, v114, s0
	v_mad_i64_i32 v[134:135], s[0:1], v134, s53, v[194:195]
	global_store_short v[134:135], v114, off
	v_or_b32_e32 v114, 3, v197
	s_nop 0
	v_cvt_pk_bf16_f32 v144, v115, s0
	v_mad_i64_i32 v[114:115], s[0:1], v114, s53, v[194:195]
	global_store_short v[114:115], v144, off
	v_or_b32_e32 v144, 8, v197
	v_cvt_pk_bf16_f32 v116, v116, s0
	v_mad_i64_i32 v[144:145], s[0:1], v144, s53, v[194:195]
	s_nop 0
	global_store_short v[144:145], v116, off
	v_or_b32_e32 v116, 9, v197
	v_cvt_pk_bf16_f32 v146, v117, s0
	v_mad_i64_i32 v[116:117], s[0:1], v116, s53, v[194:195]
	global_store_short v[116:117], v146, off
	v_or_b32_e32 v146, 10, v197
	s_nop 0
	v_cvt_pk_bf16_f32 v118, v118, s0
	v_mad_i64_i32 v[146:147], s[0:1], v146, s53, v[194:195]
	global_store_short v[146:147], v118, off
	v_or_b32_e32 v118, 11, v197
	s_nop 0
	v_or_b32_e32 v136, 18, v197
	s_nop 0
	v_cvt_pk_bf16_f32 v152, v119, s0
	v_mad_i64_i32 v[118:119], s[0:1], v118, s53, v[194:195]
	global_store_short v[118:119], v152, off
	v_or_b32_e32 v152, 16, v197
	v_cvt_pk_bf16_f32 v120, v120, s0
	v_mad_i64_i32 v[152:153], s[0:1], v152, s53, v[194:195]
	s_nop 0
	global_store_short v[152:153], v120, off
	v_or_b32_e32 v120, 17, v197
	v_cvt_pk_bf16_f32 v154, v121, s0
	v_mad_i64_i32 v[120:121], s[0:1], v120, s53, v[194:195]
	global_store_short v[120:121], v154, off
	s_nop 0
	v_cvt_pk_bf16_f32 v122, v122, s0
	s_nop 0
	v_mad_i64_i32 v[136:137], s[0:1], v136, s53, v[194:195]
	global_store_short v[136:137], v122, off
	v_or_b32_e32 v122, 19, v197
	v_cvt_pk_bf16_f32 v138, v123, s0
	v_mad_i64_i32 v[122:123], s[0:1], v122, s53, v[194:195]
	s_nop 0
	global_store_short v[122:123], v138, off
	v_or_b32_e32 v138, 24, v197
	v_cvt_pk_bf16_f32 v124, v124, s0
	v_mad_i64_i32 v[138:139], s[0:1], v138, s53, v[194:195]
	global_store_short v[138:139], v124, off
	v_or_b32_e32 v124, 25, v197
	s_nop 0
	s_nop 0
	v_cvt_pk_bf16_f32 v140, v125, s0
	v_mad_i64_i32 v[124:125], s[0:1], v124, s53, v[194:195]
	global_store_short v[124:125], v140, off
	v_or_b32_e32 v140, 26, v197
	v_cvt_pk_bf16_f32 v126, v126, s0
	v_mad_i64_i32 v[140:141], s[0:1], v140, s53, v[194:195]
	s_nop 0
	global_store_short v[140:141], v126, off
	v_or_b32_e32 v126, 27, v197
	v_cvt_pk_bf16_f32 v142, v127, s0
	v_mad_i64_i32 v[126:127], s[0:1], v126, s53, v[194:195]
	global_store_short v[126:127], v142, off
	s_nop 0
	v_cvt_pk_bf16_f32 v64, v64, s0
	s_nop 0
	global_store_short v[132:133], v64, off offset:192
	v_cvt_pk_bf16_f32 v64, v65, s0
	s_nop 1
	v_cvt_pk_bf16_f32 v96, v96, s0
	global_store_short v[112:113], v64, off offset:192
	v_cvt_pk_bf16_f32 v64, v66, s0
	global_store_short v[132:133], v96, off offset:64
	v_cvt_pk_bf16_f32 v96, v97, s0
	s_nop 0
	s_nop 1
	v_cvt_pk_bf16_f32 v80, v80, s0
	global_store_short v[132:133], v80, off offset:128
	v_cvt_pk_bf16_f32 v80, v81, s0
	global_store_short v[134:135], v64, off offset:192
	v_cvt_pk_bf16_f32 v64, v67, s0
	global_store_short v[112:113], v96, off offset:64
	v_cvt_pk_bf16_f32 v96, v98, s0
	global_store_short v[112:113], v80, off offset:128
	v_cvt_pk_bf16_f32 v80, v82, s0
	global_store_short v[114:115], v64, off offset:192
	v_cvt_pk_bf16_f32 v64, v68, s0
	global_store_short v[134:135], v96, off offset:64
	v_cvt_pk_bf16_f32 v96, v99, s0
	global_store_short v[134:135], v80, off offset:128
	v_cvt_pk_bf16_f32 v80, v83, s0
	global_store_short v[144:145], v64, off offset:192
	v_cvt_pk_bf16_f32 v64, v69, s0
	global_store_short v[114:115], v96, off offset:64
	v_cvt_pk_bf16_f32 v96, v100, s0
	global_store_short v[114:115], v80, off offset:128
	v_cvt_pk_bf16_f32 v80, v84, s0
	global_store_short v[116:117], v64, off offset:192
	v_cvt_pk_bf16_f32 v64, v70, s0
	global_store_short v[144:145], v96, off offset:64
	v_cvt_pk_bf16_f32 v96, v101, s0
	global_store_short v[144:145], v80, off offset:128
	v_cvt_pk_bf16_f32 v80, v85, s0
	global_store_short v[146:147], v64, off offset:192
	v_cvt_pk_bf16_f32 v64, v71, s0
	global_store_short v[116:117], v96, off offset:64
	v_cvt_pk_bf16_f32 v96, v102, s0
	global_store_short v[116:117], v80, off offset:128
	v_cvt_pk_bf16_f32 v80, v86, s0
	global_store_short v[118:119], v64, off offset:192
	v_cvt_pk_bf16_f32 v64, v72, s0
	global_store_short v[146:147], v96, off offset:64
	v_cvt_pk_bf16_f32 v96, v103, s0
	global_store_short v[146:147], v80, off offset:128
	v_cvt_pk_bf16_f32 v80, v87, s0
	s_nop 0
	global_store_short v[152:153], v64, off offset:192
; DI bfr f2bf(float a) { return (bfr)(pack2(a, 0.f) & 0xffffu); }
; DI int crow(int reg, int h) { return (reg & 3) + 8 * (reg >> 2) + 4 * h; }
; template <int lda, class Epi>
; DI void gemm_tile(const bfr* __restrict__ A, const bfr* __restrict__ Bt, int NB, int K, int m0, int n0, char* smem, Epi epi) {
;     ...
;   int tid3 = threadIdx.x;
;   asm volatile("" : "+v"(tid3));
;   const int lane = tid3 & 63, wid = tid3 >> 6, wr = wid >> 1, wc = wid & 1, r = lane & 31, hl = lane >> 5;
; #pragma unroll
;   for (int i = 0; i < 2; ++i)
; #pragma unroll
;     for (int j = 0; j < 4; ++j)
; #pragma unroll
;       for (int q = 0; q < 16; ++q) {
;         int row = m0 + wr * 64 + i * 32 + crow(q, hl);
;         int col = n0 + wc * 128 + j * 32 + r;
;         epi(row, col, acc[i][j][q]);
;       }
; DI void phase_gemm_in_even(const Params& p, char* smem) {
;     ...
;       gemm_tile<1024>(p.H, p.WtInE, 3712, 1024, mt * 128, nt * 256, smem,
;                 [=](int row, int col, float v) { PB[(size_t)row * EINP + col] = f2bf(v); });
	v_cvt_pk_bf16_f32 v64, v73, s0
	global_store_short v[118:119], v96, off offset:64
	v_cvt_pk_bf16_f32 v96, v104, s0
	global_store_short v[118:119], v80, off offset:128
	v_cvt_pk_bf16_f32 v80, v88, s0
	global_store_short v[120:121], v64, off offset:192
	v_cvt_pk_bf16_f32 v64, v74, s0
	global_store_short v[152:153], v96, off offset:64
	v_cvt_pk_bf16_f32 v96, v105, s0
	global_store_short v[152:153], v80, off offset:128
	v_cvt_pk_bf16_f32 v80, v89, s0
	global_store_short v[136:137], v64, off offset:192
	v_cvt_pk_bf16_f32 v64, v75, s0
	global_store_short v[120:121], v96, off offset:64
	v_cvt_pk_bf16_f32 v96, v106, s0
	global_store_short v[120:121], v80, off offset:128
	v_cvt_pk_bf16_f32 v80, v90, s0
	global_store_short v[122:123], v64, off offset:192
	v_cvt_pk_bf16_f32 v64, v76, s0
	global_store_short v[136:137], v96, off offset:64
	v_cvt_pk_bf16_f32 v96, v107, s0
	global_store_short v[136:137], v80, off offset:128
	v_cvt_pk_bf16_f32 v80, v91, s0
	global_store_short v[138:139], v64, off offset:192
	v_cvt_pk_bf16_f32 v64, v77, s0
	global_store_short v[122:123], v96, off offset:64
	v_cvt_pk_bf16_f32 v96, v108, s0
	global_store_short v[122:123], v80, off offset:128
	v_cvt_pk_bf16_f32 v80, v92, s0
	global_store_short v[124:125], v64, off offset:192
	v_cvt_pk_bf16_f32 v64, v78, s0
	global_store_short v[138:139], v96, off offset:64
	v_cvt_pk_bf16_f32 v96, v109, s0
	global_store_short v[138:139], v80, off offset:128
	v_cvt_pk_bf16_f32 v80, v93, s0
	global_store_short v[140:141], v64, off offset:192
	v_cvt_pk_bf16_f32 v64, v79, s0
	s_nop 0
	global_store_short v[124:125], v96, off offset:64
	v_cvt_pk_bf16_f32 v96, v110, s0
	global_store_short v[124:125], v80, off offset:128
	v_cvt_pk_bf16_f32 v80, v94, s0
	global_store_short v[126:127], v64, off offset:192
	v_or_b32_e32 v64, 32, v197
	global_store_short v[140:141], v96, off offset:64
	v_cvt_pk_bf16_f32 v96, v111, s0
	global_store_short v[140:141], v80, off offset:128
	v_cvt_pk_bf16_f32 v80, v95, s0
	v_cvt_pk_bf16_f32 v48, v48, s0
	v_mad_i64_i32 v[64:65], s[0:1], v64, s53, v[194:195]
	global_store_short v[64:65], v48, off
	v_or_b32_e32 v48, 33, v197
	v_cvt_pk_bf16_f32 v66, v49, s0
	v_mad_i64_i32 v[48:49], s[0:1], v48, s53, v[194:195]
	global_store_short v[48:49], v66, off
	v_or_b32_e32 v66, 34, v197
	v_cvt_pk_bf16_f32 v50, v50, s0
	v_mad_i64_i32 v[66:67], s[0:1], v66, s53, v[194:195]
	global_store_short v[66:67], v50, off
	v_or_b32_e32 v50, 35, v197
	v_cvt_pk_bf16_f32 v68, v51, s0
	v_mad_i64_i32 v[50:51], s[0:1], v50, s53, v[194:195]
	s_nop 0
	global_store_short v[50:51], v68, off
	v_or_b32_e32 v68, 40, v197
	v_cvt_pk_bf16_f32 v52, v52, s0
	v_mad_i64_i32 v[68:69], s[0:1], v68, s53, v[194:195]
	global_store_short v[68:69], v52, off
	v_or_b32_e32 v52, 41, v197
	s_nop 0
	v_cvt_pk_bf16_f32 v70, v53, s0
	v_mad_i64_i32 v[52:53], s[0:1], v52, s53, v[194:195]
	global_store_short v[52:53], v70, off
	v_or_b32_e32 v70, 42, v197
	v_cvt_pk_bf16_f32 v54, v54, s0
	v_mad_i64_i32 v[70:71], s[0:1], v70, s53, v[194:195]
	s_nop 0
	global_store_short v[70:71], v54, off
	v_or_b32_e32 v54, 43, v197
	v_cvt_pk_bf16_f32 v72, v55, s0
	v_mad_i64_i32 v[54:55], s[0:1], v54, s53, v[194:195]
	global_store_short v[54:55], v72, off
	v_or_b32_e32 v72, 48, v197
	s_nop 0
	v_cvt_pk_bf16_f32 v56, v56, s0
	v_mad_i64_i32 v[72:73], s[0:1], v72, s53, v[194:195]
	global_store_short v[72:73], v56, off
	v_or_b32_e32 v56, 49, v197
	v_cvt_pk_bf16_f32 v74, v57, s0
	v_mad_i64_i32 v[56:57], s[0:1], v56, s53, v[194:195]
	s_nop 0
	global_store_short v[56:57], v74, off
	v_or_b32_e32 v74, 50, v197
	v_cvt_pk_bf16_f32 v58, v58, s0
	v_mad_i64_i32 v[74:75], s[0:1], v74, s53, v[194:195]
	global_store_short v[74:75], v58, off
	v_or_b32_e32 v58, 51, v197
	s_nop 0
	v_cvt_pk_bf16_f32 v76, v59, s0
	v_mad_i64_i32 v[58:59], s[0:1], v58, s53, v[194:195]
	global_store_short v[58:59], v76, off
	v_or_b32_e32 v76, 56, v197
	v_cvt_pk_bf16_f32 v60, v60, s0
	v_mad_i64_i32 v[76:77], s[0:1], v76, s53, v[194:195]
	s_nop 0
	global_store_short v[76:77], v60, off
	v_or_b32_e32 v60, 57, v197
	v_cvt_pk_bf16_f32 v78, v61, s0
	v_mad_i64_i32 v[60:61], s[0:1], v60, s53, v[194:195]
	global_store_short v[60:61], v78, off
	v_or_b32_e32 v78, 58, v197
	s_nop 0
	v_cvt_pk_bf16_f32 v62, v62, s0
; DI bfr f2bf(float a) { return (bfr)(pack2(a, 0.f) & 0xffffu); }
; DI int crow(int reg, int h) { return (reg & 3) + 8 * (reg >> 2) + 4 * h; }
; template <int lda, class Epi>
; DI void gemm_tile(const bfr* __restrict__ A, const bfr* __restrict__ Bt, int NB, int K, int m0, int n0, char* smem, Epi epi) {
;     ...
;   int tid3 = threadIdx.x;
;   asm volatile("" : "+v"(tid3));
;   const int lane = tid3 & 63, wid = tid3 >> 6, wr = wid >> 1, wc = wid & 1, r = lane & 31, hl = lane >> 5;
; #pragma unroll
;   for (int i = 0; i < 2; ++i)
; #pragma unroll
;     for (int j = 0; j < 4; ++j)
; #pragma unroll
;       for (int q = 0; q < 16; ++q) {
;         int row = m0 + wr * 64 + i * 32 + crow(q, hl);
;         int col = n0 + wc * 128 + j * 32 + r;
;         epi(row, col, acc[i][j][q]);
;       }
; DI void phase_gemm_in_even(const Params& p, char* smem) {
;     ...
;       gemm_tile<1024>(p.H, p.WtInE, 3712, 1024, mt * 128, nt * 256, smem,
;                 [=](int row, int col, float v) { PB[(size_t)row * EINP + col] = f2bf(v); });
	v_mad_i64_i32 v[78:79], s[0:1], v78, s53, v[194:195]
	global_store_short v[78:79], v62, off
	v_or_b32_e32 v62, 59, v197
	global_store_short v[126:127], v80, off offset:128
	v_cvt_pk_bf16_f32 v80, v63, s0
	s_nop 0
	v_mad_i64_i32 v[62:63], s[0:1], v62, s53, v[194:195]
	global_store_short v[126:127], v96, off offset:64
	s_nop 0
	v_cvt_pk_bf16_f32 v32, v32, s0
	s_nop 0
	v_cvt_pk_bf16_f32 v16, v16, s0
	global_store_short v[64:65], v32, off offset:64
	v_cvt_pk_bf16_f32 v32, v33, s0
	s_nop 3
	v_cvt_pk_bf16_f32 v0, v0, s0
	global_store_short v[64:65], v16, off offset:128
	v_cvt_pk_bf16_f32 v16, v17, s0
	global_store_short v[64:65], v0, off offset:192
	v_cvt_pk_bf16_f32 v0, v1, s0
	global_store_short v[48:49], v32, off offset:64
	v_cvt_pk_bf16_f32 v32, v34, s0
	global_store_short v[48:49], v16, off offset:128
	v_cvt_pk_bf16_f32 v16, v18, s0
	global_store_short v[48:49], v0, off offset:192
	v_cvt_pk_bf16_f32 v0, v2, s0
	global_store_short v[66:67], v32, off offset:64
	v_cvt_pk_bf16_f32 v32, v35, s0
	global_store_short v[66:67], v16, off offset:128
	v_cvt_pk_bf16_f32 v16, v19, s0
	global_store_short v[66:67], v0, off offset:192
	v_cvt_pk_bf16_f32 v0, v3, s0
	global_store_short v[50:51], v32, off offset:64
	v_cvt_pk_bf16_f32 v32, v36, s0
	global_store_short v[50:51], v16, off offset:128
	v_cvt_pk_bf16_f32 v16, v20, s0
	global_store_short v[50:51], v0, off offset:192
	v_cvt_pk_bf16_f32 v0, v4, s0
	global_store_short v[68:69], v32, off offset:64
	v_cvt_pk_bf16_f32 v32, v37, s0
	global_store_short v[68:69], v16, off offset:128
	v_cvt_pk_bf16_f32 v16, v21, s0
	global_store_short v[68:69], v0, off offset:192
	v_cvt_pk_bf16_f32 v0, v5, s0
	global_store_short v[52:53], v32, off offset:64
	v_cvt_pk_bf16_f32 v32, v38, s0
	global_store_short v[52:53], v16, off offset:128
	v_cvt_pk_bf16_f32 v16, v22, s0
	global_store_short v[52:53], v0, off offset:192
	v_cvt_pk_bf16_f32 v0, v6, s0
	global_store_short v[70:71], v32, off offset:64
	v_cvt_pk_bf16_f32 v32, v39, s0
	global_store_short v[70:71], v16, off offset:128
	v_cvt_pk_bf16_f32 v16, v23, s0
	global_store_short v[70:71], v0, off offset:192
	v_cvt_pk_bf16_f32 v0, v7, s0
	global_store_short v[54:55], v32, off offset:64
	v_cvt_pk_bf16_f32 v32, v40, s0
	global_store_short v[54:55], v16, off offset:128
	v_cvt_pk_bf16_f32 v16, v24, s0
	global_store_short v[54:55], v0, off offset:192
	v_cvt_pk_bf16_f32 v0, v8, s0
	global_store_short v[72:73], v32, off offset:64
	v_cvt_pk_bf16_f32 v32, v41, s0
	global_store_short v[72:73], v16, off offset:128
	v_cvt_pk_bf16_f32 v16, v25, s0
	global_store_short v[72:73], v0, off offset:192
	v_cvt_pk_bf16_f32 v0, v9, s0
	global_store_short v[56:57], v32, off offset:64
	v_cvt_pk_bf16_f32 v32, v42, s0
	global_store_short v[56:57], v16, off offset:128
	v_cvt_pk_bf16_f32 v16, v26, s0
	global_store_short v[56:57], v0, off offset:192
	v_cvt_pk_bf16_f32 v0, v10, s0
	global_store_short v[74:75], v32, off offset:64
	v_cvt_pk_bf16_f32 v32, v43, s0
	global_store_short v[74:75], v16, off offset:128
	v_cvt_pk_bf16_f32 v16, v27, s0
	global_store_short v[74:75], v0, off offset:192
	v_cvt_pk_bf16_f32 v0, v11, s0
	global_store_short v[58:59], v32, off offset:64
	v_cvt_pk_bf16_f32 v32, v44, s0
	global_store_short v[58:59], v16, off offset:128
	v_cvt_pk_bf16_f32 v16, v28, s0
	global_store_short v[58:59], v0, off offset:192
	v_cvt_pk_bf16_f32 v0, v12, s0
	global_store_short v[76:77], v32, off offset:64
	v_cvt_pk_bf16_f32 v32, v45, s0
	global_store_short v[76:77], v16, off offset:128
	v_cvt_pk_bf16_f32 v16, v29, s0
	global_store_short v[76:77], v0, off offset:192
	v_cvt_pk_bf16_f32 v0, v13, s0
	global_store_short v[60:61], v32, off offset:64
	v_cvt_pk_bf16_f32 v32, v46, s0
	global_store_short v[60:61], v16, off offset:128
	v_cvt_pk_bf16_f32 v16, v30, s0
	global_store_short v[60:61], v0, off offset:192
	v_cvt_pk_bf16_f32 v0, v14, s0
	global_store_short v[78:79], v32, off offset:64
	v_cvt_pk_bf16_f32 v32, v47, s0
	global_store_short v[78:79], v16, off offset:128
	v_cvt_pk_bf16_f32 v16, v31, s0
	global_store_short v[78:79], v0, off offset:192
	v_cvt_pk_bf16_f32 v0, v15, s0
	global_store_short v[62:63], v80, off
	global_store_short v[62:63], v32, off offset:64
	global_store_short v[62:63], v16, off offset:128
	global_store_short v[62:63], v0, off offset:192

; DI bfr f2bf(float a) { return (bfr)(pack2(a, 0.f) & 0xffffu); }
; #define GA_LOAD(pr_) do { _Pragma("unroll") for (int i = 0; i < 4; ++i) ra[i] = *(const u32x4*)(Ab + (i * 32) * lda + (pr_) * 64); } while (0)
; #define GB_LOAD(kt_) do { const bfr* bk_ = Bb + (kt_) * NB * 32; \
;     _Pragma("unroll") for (int i = 0; i < 4; ++i) rb[i] = *(const u32x4*)(bk_ + (i * 64) * 32); } while (0)
; #define G_STORE(kt_) do { bfr* as_ = S0 + ((kt_) & 1) * GSTAGE; bfr* bs_ = as_ + 128 * 40; \
;     if (apar == ((kt_) & 1)) { _Pragma("unroll") for (int i = 0; i < 4; ++i) *(u32x4*)(as_ + asoff + i * 32 * 40) = ra[i]; } \
;     _Pragma("unroll") for (int i = 0; i < 4; ++i) *(u32x4*)(bs_ + bsoff + i * 64 * 40) = rb[i]; } while (0)
; template <int lda>
; DI void gemm_mainloop(const bfr* __restrict__ A, const bfr* __restrict__ Bt, int NB, int K, int m0, int n0, char* smem, f32x16 (&acc)[2][4]) {
;     ...
;   const int nk = K >> 5;
;   const int arow = tid >> 3, ac8 = tid & 7, apar = ac8 >> 2;
;   const bfr* Ab = A + (m0 + arow) * lda + ac8 * 8;
;   const int asoff = arow * 40 + (ac8 & 3) * 8;
;   const int brow = tid >> 2, bc4 = tid & 3;
;   const bfr* Bb = Bt + (n0 + brow) * 32 + bc4 * 8;
;   const int bsoff = brow * 40 + bc4 * 8;
;     ...
;   GA_LOAD(0);
;   GB_LOAD(0);
;   G_STORE(0);
;   GB_LOAD(1);
;   __syncthreads();
; DI void phase_gemm_in_even(const Params& p, char* smem) {
;     ...
;       int u = t - NT1, gsel = u >> 6, v = u & 63, mt = v >> 2, nt = v & 3;
;       int isv = gsel >> 1, l = gsel & 1;
;       if (!isv) {
;         float* o = p.out + O_MEMK + (size_t)l * 2097152;
;         bfr* kb = p.KB + (size_t)l * 2097152;
;         gemm_tile<1024>(p.MPB, p.WtXk + (size_t)l * 1048576, 1024, 1024, mt * 128, nt * 256, smem,
;                   [=](int row, int col, float v) {
;                     o[(size_t)row * 1024 + col] = v;
;                     kb[(size_t)row * 1024 + col] = f2bf(v);
;                   });
;       } else {
;         float* o = p.out + O_MEMV + (size_t)l * 2097152;
;         bfr* vt = p.VT + (size_t)l * 2097152;
;         gemm_tile<1024>(p.MPB, p.WtXv + (size_t)l * 1048576, 1024, 1024, mt * 128, nt * 256, smem,
.LBB0_123:
	s_lshl_b32 s1, s56, 15
	s_and_b32 s2, s1, 0x200000
	s_lshl_b32 s1, s56, 5
	s_and_b32 s58, s1, 0x780
	s_lshl_b32 s1, s56, 8
	s_and_b32 s0, s56, 0x7fffff80
	s_and_b32 s57, s1, 0x300
	s_cmpk_lg_i32 s0, 0x700
	s_mov_b64 s[0:1], -1
	s_cbranch_scc0 .LBB0_136
	s_add_u32 s0, s14, s2
	s_addc_u32 s1, s15, 0
	s_mov_b32 s59, 0
	s_mov_b64 s[30:31], 0
	s_lshl_b32 s98, s58, 11
	s_add_u32 s98, s8, s98
	s_addc_u32 s99, s9, 0
	s_lshl_b32 s100, s57, 6
	s_add_u32 s100, s0, s100
	s_addc_u32 s101, s1, 0
	v_writelane_b32 v188, s64, 0
	v_writelane_b32 v188, s65, 1
	v_writelane_b32 v188, s66, 2
	v_writelane_b32 v188, s67, 3
	v_writelane_b32 v188, s68, 4
	v_writelane_b32 v188, s69, 5
	v_writelane_b32 v188, s70, 6
	v_writelane_b32 v188, s71, 7
	v_writelane_b32 v188, s72, 8
	v_writelane_b32 v188, s73, 9
	v_writelane_b32 v188, s74, 10
	v_writelane_b32 v188, s75, 11
	v_writelane_b32 v188, s76, 12
	v_writelane_b32 v188, s77, 13
	v_writelane_b32 v188, s78, 14
	v_writelane_b32 v188, s79, 15
	v_lshrrev_b32_e32 v189, 6, v196
	v_and_b32_e32 v190, 63, v196
	v_readfirstlane_b32 s73, v189
	v_lshrrev_b32_e32 v191, 2, v190
	v_bfe_u32 v192, v190, 4, 2
	v_and_b32_e32 v189, 3, v190
	v_xor_b32_e32 v189, v189, v192
	v_lshlrev_b32_e32 v189, 4, v189
	v_lshl_add_u32 v160, v191, 11, v189
	v_add_u32_e32 v162, 0x8000, v160
	v_lshl_add_u32 v163, v191, 6, v189
	v_and_b32_e32 v191, 31, v190
	v_lshrrev_b32_e32 v192, 5, v190
	v_bfe_u32 v189, v190, 2, 2
	v_xor_b32_e32 v189, v189, v192
	v_lshlrev_b32_e32 v189, 4, v189
	v_lshl_add_u32 v180, v191, 6, v189
	s_lshr_b32 s74, s73, 1
	s_lshl_b32 s74, s74, 12
	s_and_b32 s75, s73, 1
	s_lshl_b32 s75, s75, 13
	v_add_u32_e32 v182, s75, v180
	v_add_u32_e32 v180, s74, v180
	v_xor_b32_e32 v183, 32, v182
	v_xor_b32_e32 v181, 32, v180
	s_lshl_b32 s74, s73, 16
	s_add_u32 s64, s98, s74
	s_addc_u32 s65, s99, 0
	s_lshl_b32 s74, s73, 12
	s_add_u32 s66, s100, s74
	s_addc_u32 s67, s101, 0
	s_lshl_b32 s68, s73, 11
	s_lshl_b32 s69, s73, 12
	s_mov_b32 s70, 0
	s_mov_b32 s71, 0
	s_mov_b32 s72, 0
	s_waitcnt lgkmcnt(0)
	s_barrier
	s_mul_i32 s74, s70, 0x6000
	s_add_u32 s75, s74, s68
	s_mov_b32 m0, s75
	s_add_u32 s76, s74, 0x2000
	s_cmp_eq_u32 s70, 2
	s_cselect_b32 s76, 0x10000, s76
	global_load_lds_dwordx4 v160, s[64:65]
	s_add_u32 m0, s75, 0x400
	s_add_u32 s76, s76, s69
	global_load_lds_dwordx4 v162, s[64:65]
	s_mov_b32 m0, s76
	s_add_u32 s64, s64, 64
	s_addc_u32 s65, s65, 0
	global_load_lds_dwordx4 v163, s[66:67]
	global_load_lds_dwordx4 v163, s[66:67] offset:1024
	global_load_lds_dwordx4 v163, s[66:67] offset:2048
	global_load_lds_dwordx4 v163, s[66:67] offset:3072
	s_add_u32 s66, s66, 0x10000
	s_addc_u32 s67, s67, 0
	s_add_u32 s70, s70, 1
	s_cmp_eq_u32 s70, 3
	s_cselect_b32 s70, 0, s70
	s_mul_i32 s74, s70, 0x6000
	s_add_u32 s75, s74, s68
	s_mov_b32 m0, s75
	s_add_u32 s76, s74, 0x2000
	s_cmp_eq_u32 s70, 2
	s_cselect_b32 s76, 0x10000, s76
	global_load_lds_dwordx4 v160, s[64:65]
	s_add_u32 m0, s75, 0x400
	s_add_u32 s76, s76, s69
	global_load_lds_dwordx4 v162, s[64:65]
	s_mov_b32 m0, s76
	s_add_u32 s64, s64, 64
	s_addc_u32 s65, s65, 0
	global_load_lds_dwordx4 v163, s[66:67]
	global_load_lds_dwordx4 v163, s[66:67] offset:1024
	global_load_lds_dwordx4 v163, s[66:67] offset:2048
	global_load_lds_dwordx4 v163, s[66:67] offset:3072
	s_add_u32 s66, s66, 0x10000
	s_addc_u32 s67, s67, 0
	s_add_u32 s70, s70, 1
	s_cmp_eq_u32 s70, 3
	s_cselect_b32 s70, 0, s70
	v_mov_b32_e32 v112, 0
	v_mov_b32_e32 v113, 0
	v_mov_b32_e32 v114, 0
	v_mov_b32_e32 v115, 0
	v_mov_b32_e32 v116, 0
	v_mov_b32_e32 v117, 0
	v_mov_b32_e32 v118, 0
	v_mov_b32_e32 v119, 0
	v_mov_b32_e32 v120, 0
	v_mov_b32_e32 v121, 0
	v_mov_b32_e32 v122, 0
	v_mov_b32_e32 v123, 0
	v_mov_b32_e32 v124, 0
	v_mov_b32_e32 v125, 0
	v_mov_b32_e32 v126, 0
	v_mov_b32_e32 v127, 0
	v_mov_b32_e32 v96, 0
	v_mov_b32_e32 v97, 0
	v_mov_b32_e32 v98, 0
	v_mov_b32_e32 v99, 0
	v_mov_b32_e32 v100, 0
	v_mov_b32_e32 v101, 0
	v_mov_b32_e32 v102, 0
	v_mov_b32_e32 v103, 0
	v_mov_b32_e32 v104, 0
	v_mov_b32_e32 v105, 0
	v_mov_b32_e32 v106, 0
	v_mov_b32_e32 v107, 0
	v_mov_b32_e32 v108, 0
	v_mov_b32_e32 v109, 0
	v_mov_b32_e32 v110, 0
	v_mov_b32_e32 v111, 0
	v_mov_b32_e32 v80, 0
	v_mov_b32_e32 v81, 0
	v_mov_b32_e32 v82, 0
	v_mov_b32_e32 v83, 0
	v_mov_b32_e32 v84, 0
	v_mov_b32_e32 v85, 0
	v_mov_b32_e32 v86, 0
	v_mov_b32_e32 v87, 0
	v_mov_b32_e32 v88, 0
	v_mov_b32_e32 v89, 0
	v_mov_b32_e32 v90, 0
	v_mov_b32_e32 v91, 0
	v_mov_b32_e32 v92, 0
	v_mov_b32_e32 v93, 0
	v_mov_b32_e32 v94, 0
	v_mov_b32_e32 v95, 0
	v_mov_b32_e32 v64, 0
	v_mov_b32_e32 v65, 0
	v_mov_b32_e32 v66, 0
	v_mov_b32_e32 v67, 0
	v_mov_b32_e32 v68, 0
	v_mov_b32_e32 v69, 0
	v_mov_b32_e32 v70, 0
	v_mov_b32_e32 v71, 0
	v_mov_b32_e32 v72, 0
	v_mov_b32_e32 v73, 0
	v_mov_b32_e32 v74, 0
	v_mov_b32_e32 v75, 0
	v_mov_b32_e32 v76, 0
	v_mov_b32_e32 v77, 0
	v_mov_b32_e32 v78, 0
	v_mov_b32_e32 v79, 0
	v_mov_b32_e32 v48, 0
	v_mov_b32_e32 v49, 0
	v_mov_b32_e32 v50, 0
	v_mov_b32_e32 v51, 0
	v_mov_b32_e32 v52, 0
	v_mov_b32_e32 v53, 0
	v_mov_b32_e32 v54, 0
	v_mov_b32_e32 v55, 0
	v_mov_b32_e32 v56, 0
	v_mov_b32_e32 v57, 0
	v_mov_b32_e32 v58, 0
	v_mov_b32_e32 v59, 0
	v_mov_b32_e32 v60, 0
	v_mov_b32_e32 v61, 0
	v_mov_b32_e32 v62, 0
	v_mov_b32_e32 v63, 0
	v_mov_b32_e32 v32, 0
	v_mov_b32_e32 v33, 0
	v_mov_b32_e32 v34, 0
	v_mov_b32_e32 v35, 0
	v_mov_b32_e32 v36, 0
	v_mov_b32_e32 v37, 0
	v_mov_b32_e32 v38, 0
	v_mov_b32_e32 v39, 0
	v_mov_b32_e32 v40, 0
	v_mov_b32_e32 v41, 0
	v_mov_b32_e32 v42, 0
	v_mov_b32_e32 v43, 0
	v_mov_b32_e32 v44, 0
	v_mov_b32_e32 v45, 0
	v_mov_b32_e32 v46, 0
	v_mov_b32_e32 v47, 0
	v_mov_b32_e32 v16, 0
	v_mov_b32_e32 v17, 0
	v_mov_b32_e32 v18, 0
	v_mov_b32_e32 v19, 0
	v_mov_b32_e32 v20, 0
	v_mov_b32_e32 v21, 0
	v_mov_b32_e32 v22, 0
	v_mov_b32_e32 v23, 0
	v_mov_b32_e32 v24, 0
	v_mov_b32_e32 v25, 0
	v_mov_b32_e32 v26, 0
	v_mov_b32_e32 v27, 0
	v_mov_b32_e32 v28, 0
	v_mov_b32_e32 v29, 0
	v_mov_b32_e32 v30, 0
	v_mov_b32_e32 v31, 0
	v_mov_b32_e32 v0, 0
	v_mov_b32_e32 v1, 0
	v_mov_b32_e32 v2, 0
	v_mov_b32_e32 v3, 0
	v_mov_b32_e32 v4, 0
	v_mov_b32_e32 v5, 0
	v_mov_b32_e32 v6, 0
	v_mov_b32_e32 v7, 0
	v_mov_b32_e32 v8, 0
	v_mov_b32_e32 v9, 0
	v_mov_b32_e32 v10, 0
	v_mov_b32_e32 v11, 0
	v_mov_b32_e32 v12, 0
	v_mov_b32_e32 v13, 0
	v_mov_b32_e32 v14, 0
	v_mov_b32_e32 v15, 0
; #define MFMA32(a, b, c) __builtin_amdgcn_mfma_f32_32x32x16_bf16((a), (b), (c), 0, 0, 0)
; #define GA_LOAD(pr_) do { _Pragma("unroll") for (int i = 0; i < 4; ++i) ra[i] = *(const u32x4*)(Ab + (i * 32) * lda + (pr_) * 64); } while (0)
; #define GB_LOAD(kt_) do { const bfr* bk_ = Bb + (kt_) * NB * 32; \
;     _Pragma("unroll") for (int i = 0; i < 4; ++i) rb[i] = *(const u32x4*)(bk_ + (i * 64) * 32); } while (0)
; #define G_STORE(kt_) do { bfr* as_ = S0 + ((kt_) & 1) * GSTAGE; bfr* bs_ = as_ + 128 * 40; \
;     if (apar == ((kt_) & 1)) { _Pragma("unroll") for (int i = 0; i < 4; ++i) *(u32x4*)(as_ + asoff + i * 32 * 40) = ra[i]; } \
;     _Pragma("unroll") for (int i = 0; i < 4; ++i) *(u32x4*)(bs_ + bsoff + i * 64 * 40) = rb[i]; } while (0)
; template <int lda>
; DI void gemm_mainloop(const bfr* __restrict__ A, const bfr* __restrict__ Bt, int NB, int K, int m0, int n0, char* smem, f32x16 (&acc)[2][4]) {
;     ...
;   for (int kt = 0; kt < nk; ++kt) {
;     if (kt + 1 < nk) G_STORE(kt + 1);
;     if (kt + 2 < nk) {
;       GB_LOAD(kt + 2);
;       if ((kt & 1) == 0) GA_LOAD((kt >> 1) + 1);
;     }
;     const bfr* As = S0 + (kt & 1) * GSTAGE;
;     const bfr* Bs = As + 128 * 40;
; #pragma unroll
;     for (int ks = 0; ks < 2; ++ks) {
;       bf16x8 af[2], bfg[4];
; #pragma unroll
;       for (int i = 0; i < 2; ++i) af[i] = *(const bf16x8*)(As + (wr * 64 + i * 32 + r) * 40 + ks * 16 + hl * 8);
; #pragma unroll
;       for (int j = 0; j < 4; ++j) bfg[j] = *(const bf16x8*)(Bs + (wc * 128 + j * 32 + r) * 40 + ks * 16 + hl * 8);
; #pragma unroll
;       for (int i = 0; i < 2; ++i)
; #pragma unroll
;         for (int j = 0; j < 4; ++j) acc[i][j] = MFMA32(af[i], bfg[j], acc[i][j]);
;     }
;     __syncthreads();
;   }
.Lp1v_loop:
	s_waitcnt vmcnt(6)
	s_barrier
	s_mul_i32 s74, s70, 0x6000
	s_add_u32 s75, s74, s68
	s_mov_b32 m0, s75
	s_add_u32 s76, s74, 0x2000
	s_cmp_eq_u32 s70, 2
	s_cselect_b32 s76, 0x10000, s76
	global_load_lds_dwordx4 v160, s[64:65]
	s_add_u32 m0, s75, 0x400
	s_add_u32 s76, s76, s69
	global_load_lds_dwordx4 v162, s[64:65]
	s_mov_b32 m0, s76
	s_add_u32 s64, s64, 64
	s_addc_u32 s65, s65, 0
	global_load_lds_dwordx4 v163, s[66:67]
	global_load_lds_dwordx4 v163, s[66:67] offset:1024
	global_load_lds_dwordx4 v163, s[66:67] offset:2048
	global_load_lds_dwordx4 v163, s[66:67] offset:3072
	s_add_u32 s66, s66, 0x10000
	s_addc_u32 s67, s67, 0
	s_add_u32 s70, s70, 1
	s_cmp_eq_u32 s70, 3
	s_cselect_b32 s70, 0, s70
	s_mul_i32 s74, s71, 0x6000
	s_add_u32 s75, s74, 0x2000
	s_cmp_eq_u32 s71, 2
	s_cselect_b32 s75, 0x10000, s75
	v_add_u32_e32 v184, s74, v180
	v_add_u32_e32 v186, s75, v182
	v_add_u32_e32 v185, s74, v181
	v_add_u32_e32 v187, s75, v183
	ds_read_b128 v[128:131], v184
	ds_read_b128 v[144:147], v186
	ds_read_b128 v[148:151], v186 offset:2048
	ds_read_b128 v[152:155], v186 offset:4096
	ds_read_b128 v[156:159], v186 offset:6144
	ds_read_b128 v[132:135], v184 offset:2048
	ds_read_b128 v[136:139], v185
	ds_read_b128 v[164:167], v187
	ds_read_b128 v[168:171], v187 offset:2048
	ds_read_b128 v[172:175], v187 offset:4096
	ds_read_b128 v[176:179], v187 offset:6144
	ds_read_b128 v[140:143], v185 offset:2048
	s_add_u32 s71, s71, 1
	s_cmp_eq_u32 s71, 3
	s_cselect_b32 s71, 0, s71
	s_waitcnt lgkmcnt(10)
	v_mfma_f32_32x32x16_bf16 v[112:127], v[128:131], v[144:147], v[112:127]
	s_waitcnt lgkmcnt(9)
	v_mfma_f32_32x32x16_bf16 v[96:111], v[128:131], v[148:151], v[96:111]
	s_waitcnt lgkmcnt(8)
	v_mfma_f32_32x32x16_bf16 v[80:95], v[128:131], v[152:155], v[80:95]
	s_waitcnt lgkmcnt(7)
	v_mfma_f32_32x32x16_bf16 v[64:79], v[128:131], v[156:159], v[64:79]
	s_waitcnt lgkmcnt(6)
	v_mfma_f32_32x32x16_bf16 v[48:63], v[132:135], v[144:147], v[48:63]
	v_mfma_f32_32x32x16_bf16 v[32:47], v[132:135], v[148:151], v[32:47]
	v_mfma_f32_32x32x16_bf16 v[16:31], v[132:135], v[152:155], v[16:31]
	v_mfma_f32_32x32x16_bf16 v[0:15], v[132:135], v[156:159], v[0:15]
	s_waitcnt lgkmcnt(4)
	v_mfma_f32_32x32x16_bf16 v[112:127], v[136:139], v[164:167], v[112:127]
	s_waitcnt lgkmcnt(3)
	v_mfma_f32_32x32x16_bf16 v[96:111], v[136:139], v[168:171], v[96:111]
	s_waitcnt lgkmcnt(2)
	v_mfma_f32_32x32x16_bf16 v[80:95], v[136:139], v[172:175], v[80:95]
	s_waitcnt lgkmcnt(1)
	v_mfma_f32_32x32x16_bf16 v[64:79], v[136:139], v[176:179], v[64:79]
	s_waitcnt lgkmcnt(0)
	v_mfma_f32_32x32x16_bf16 v[48:63], v[140:143], v[164:167], v[48:63]
	v_mfma_f32_32x32x16_bf16 v[32:47], v[140:143], v[168:171], v[32:47]
	v_mfma_f32_32x32x16_bf16 v[16:31], v[140:143], v[172:175], v[16:31]
	v_mfma_f32_32x32x16_bf16 v[0:15], v[140:143], v[176:179], v[0:15]
	s_add_u32 s72, s72, 1
	s_cmp_lt_u32 s72, 30
	s_cbranch_scc1 .Lp1v_loop
	s_waitcnt vmcnt(6)
	s_barrier
	s_mul_i32 s74, s71, 0x6000
	s_add_u32 s75, s74, 0x2000
	s_cmp_eq_u32 s71, 2
	s_cselect_b32 s75, 0x10000, s75
	v_add_u32_e32 v184, s74, v180
	v_add_u32_e32 v186, s75, v182
	v_add_u32_e32 v185, s74, v181
	v_add_u32_e32 v187, s75, v183
	ds_read_b128 v[128:131], v184
	ds_read_b128 v[144:147], v186
	ds_read_b128 v[148:151], v186 offset:2048
	ds_read_b128 v[152:155], v186 offset:4096
	ds_read_b128 v[156:159], v186 offset:6144
	ds_read_b128 v[132:135], v184 offset:2048
	ds_read_b128 v[136:139], v185
	ds_read_b128 v[164:167], v187
	ds_read_b128 v[168:171], v187 offset:2048
	ds_read_b128 v[172:175], v187 offset:4096
	ds_read_b128 v[176:179], v187 offset:6144
	ds_read_b128 v[140:143], v185 offset:2048
	s_add_u32 s71, s71, 1
	s_cmp_eq_u32 s71, 3
	s_cselect_b32 s71, 0, s71
	s_waitcnt lgkmcnt(10)
	v_mfma_f32_32x32x16_bf16 v[112:127], v[128:131], v[144:147], v[112:127]
	s_waitcnt lgkmcnt(9)
	v_mfma_f32_32x32x16_bf16 v[96:111], v[128:131], v[148:151], v[96:111]
	s_waitcnt lgkmcnt(8)
	v_mfma_f32_32x32x16_bf16 v[80:95], v[128:131], v[152:155], v[80:95]
	s_waitcnt lgkmcnt(7)
	v_mfma_f32_32x32x16_bf16 v[64:79], v[128:131], v[156:159], v[64:79]
	s_waitcnt lgkmcnt(6)
	v_mfma_f32_32x32x16_bf16 v[48:63], v[132:135], v[144:147], v[48:63]
	v_mfma_f32_32x32x16_bf16 v[32:47], v[132:135], v[148:151], v[32:47]
	v_mfma_f32_32x32x16_bf16 v[16:31], v[132:135], v[152:155], v[16:31]
	v_mfma_f32_32x32x16_bf16 v[0:15], v[132:135], v[156:159], v[0:15]
	s_waitcnt lgkmcnt(4)
	v_mfma_f32_32x32x16_bf16 v[112:127], v[136:139], v[164:167], v[112:127]
	s_waitcnt lgkmcnt(3)
	v_mfma_f32_32x32x16_bf16 v[96:111], v[136:139], v[168:171], v[96:111]
	s_waitcnt lgkmcnt(2)
	v_mfma_f32_32x32x16_bf16 v[80:95], v[136:139], v[172:175], v[80:95]
	s_waitcnt lgkmcnt(1)
	v_mfma_f32_32x32x16_bf16 v[64:79], v[136:139], v[176:179], v[64:79]
	s_waitcnt lgkmcnt(0)
	v_mfma_f32_32x32x16_bf16 v[48:63], v[140:143], v[164:167], v[48:63]
	v_mfma_f32_32x32x16_bf16 v[32:47], v[140:143], v[168:171], v[32:47]
	v_mfma_f32_32x32x16_bf16 v[16:31], v[140:143], v[172:175], v[16:31]
	v_mfma_f32_32x32x16_bf16 v[0:15], v[140:143], v[176:179], v[0:15]
	s_waitcnt vmcnt(0)
	s_barrier
; #define MFMA32(a, b, c) __builtin_amdgcn_mfma_f32_32x32x16_bf16((a), (b), (c), 0, 0, 0)
; DI bfr f2bf(float a) { return (bfr)(pack2(a, 0.f) & 0xffffu); }
; template <int lda>
; DI void gemm_mainloop(const bfr* __restrict__ A, const bfr* __restrict__ Bt, int NB, int K, int m0, int n0, char* smem, f32x16 (&acc)[2][4]) {
;     ...
;     const bfr* As = S0 + (kt & 1) * GSTAGE;
;     const bfr* Bs = As + 128 * 40;
; #pragma unroll
;     for (int ks = 0; ks < 2; ++ks) {
;       bf16x8 af[2], bfg[4];
; #pragma unroll
;       for (int i = 0; i < 2; ++i) af[i] = *(const bf16x8*)(As + (wr * 64 + i * 32 + r) * 40 + ks * 16 + hl * 8);
; #pragma unroll
;       for (int j = 0; j < 4; ++j) bfg[j] = *(const bf16x8*)(Bs + (wc * 128 + j * 32 + r) * 40 + ks * 16 + hl * 8);
; #pragma unroll
;       for (int i = 0; i < 2; ++i)
; #pragma unroll
;         for (int j = 0; j < 4; ++j) acc[i][j] = MFMA32(af[i], bfg[j], acc[i][j]);
;     }
;     __syncthreads();
; DI void phase_gemm_in_even(const Params& p, char* smem) {
;     ...
;         float* o = p.out + O_MEMV + (size_t)l * 2097152;
;         bfr* vt = p.VT + (size_t)l * 2097152;
;         gemm_tile<1024>(p.MPB, p.WtXv + (size_t)l * 1048576, 1024, 1024, mt * 128, nt * 256, smem,
;                   [=](int row, int col, float v) {
;                     o[(size_t)row * 1024 + col] = v;
;                     const int ml = row & 15;
;                     const int rowpart = (row >> 8) * 262144 + ((row & 255) >> 4) * 512 + ((ml >> 2) & 1) * 256 + (((ml >> 3) << 2) | (ml & 3));
;                     const int colpart = (col >> 8) * 65536 + ((col & 255) >> 5) * 8192 + (col & 31) * 8;
;                     vt[rowpart + colpart] = f2bf(v);
;                   });
	s_mul_i32 s74, s71, 0x6000
	s_add_u32 s75, s74, 0x2000
	s_cmp_eq_u32 s71, 2
	s_cselect_b32 s75, 0x10000, s75
	v_add_u32_e32 v184, s74, v180
	v_add_u32_e32 v186, s75, v182
	v_add_u32_e32 v185, s74, v181
	v_add_u32_e32 v187, s75, v183
	ds_read_b128 v[128:131], v184
	ds_read_b128 v[144:147], v186
	ds_read_b128 v[148:151], v186 offset:2048
	ds_read_b128 v[152:155], v186 offset:4096
	ds_read_b128 v[156:159], v186 offset:6144
	ds_read_b128 v[132:135], v184 offset:2048
	ds_read_b128 v[136:139], v185
	ds_read_b128 v[164:167], v187
	ds_read_b128 v[168:171], v187 offset:2048
	ds_read_b128 v[172:175], v187 offset:4096
	ds_read_b128 v[176:179], v187 offset:6144
	ds_read_b128 v[140:143], v185 offset:2048
	s_add_u32 s71, s71, 1
	s_cmp_eq_u32 s71, 3
	s_cselect_b32 s71, 0, s71
	s_waitcnt lgkmcnt(10)
	v_mfma_f32_32x32x16_bf16 v[112:127], v[128:131], v[144:147], v[112:127]
	s_waitcnt lgkmcnt(9)
	v_mfma_f32_32x32x16_bf16 v[96:111], v[128:131], v[148:151], v[96:111]
	s_waitcnt lgkmcnt(8)
	v_mfma_f32_32x32x16_bf16 v[80:95], v[128:131], v[152:155], v[80:95]
	s_waitcnt lgkmcnt(7)
	v_mfma_f32_32x32x16_bf16 v[64:79], v[128:131], v[156:159], v[64:79]
	s_waitcnt lgkmcnt(6)
	v_mfma_f32_32x32x16_bf16 v[48:63], v[132:135], v[144:147], v[48:63]
	v_mfma_f32_32x32x16_bf16 v[32:47], v[132:135], v[148:151], v[32:47]
	v_mfma_f32_32x32x16_bf16 v[16:31], v[132:135], v[152:155], v[16:31]
	v_mfma_f32_32x32x16_bf16 v[0:15], v[132:135], v[156:159], v[0:15]
	s_waitcnt lgkmcnt(4)
	v_mfma_f32_32x32x16_bf16 v[112:127], v[136:139], v[164:167], v[112:127]
	s_waitcnt lgkmcnt(3)
	v_mfma_f32_32x32x16_bf16 v[96:111], v[136:139], v[168:171], v[96:111]
	s_waitcnt lgkmcnt(2)
	v_mfma_f32_32x32x16_bf16 v[80:95], v[136:139], v[172:175], v[80:95]
	s_waitcnt lgkmcnt(1)
	v_mfma_f32_32x32x16_bf16 v[64:79], v[136:139], v[176:179], v[64:79]
	s_waitcnt lgkmcnt(0)
	v_mfma_f32_32x32x16_bf16 v[48:63], v[140:143], v[164:167], v[48:63]
	v_mfma_f32_32x32x16_bf16 v[32:47], v[140:143], v[168:171], v[32:47]
	v_mfma_f32_32x32x16_bf16 v[16:31], v[140:143], v[172:175], v[16:31]
	v_mfma_f32_32x32x16_bf16 v[0:15], v[140:143], v[176:179], v[0:15]
	s_nop 7
	v_readlane_b32 s64, v188, 0
	v_readlane_b32 s65, v188, 1
	v_readlane_b32 s66, v188, 2
	v_readlane_b32 s67, v188, 3
	v_readlane_b32 s68, v188, 4
	v_readlane_b32 s69, v188, 5
	v_readlane_b32 s70, v188, 6
	v_readlane_b32 s71, v188, 7
	v_readlane_b32 s72, v188, 8
	v_readlane_b32 s73, v188, 9
	v_readlane_b32 s74, v188, 10
	v_readlane_b32 s75, v188, 11
	v_readlane_b32 s76, v188, 12
	v_readlane_b32 s77, v188, 13
	v_readlane_b32 s78, v188, 14
	v_readlane_b32 s79, v188, 15
	s_nop 7
	s_waitcnt vmcnt(1)
	s_nop 0
	s_nop 0
	s_nop 0
	s_waitcnt vmcnt(0)
	s_nop 0
	v_add_u32_e32 v140, v171, v173
	s_nop 0
	v_add_u32_e32 v160, v171, v172
	s_nop 0
	s_nop 0
	s_nop 0
	s_nop 0
	s_nop 0
	s_nop 0
	s_nop 0
	s_nop 0
	s_nop 0
	s_nop 0
	s_nop 0
	s_waitcnt lgkmcnt(0)
	s_nop 0
	s_nop 0
	s_lshl_b32 s0, s2, 2
	s_add_u32 s30, s33, s0
	s_addc_u32 s31, s38, 0
	s_lshl_b32 s0, s2, 1
	s_add_u32 s0, s6, s0
	s_nop 0
	s_addc_u32 s1, s7, 0
	s_nop 0
	s_nop 0
	s_nop 0
	s_nop 0
	s_nop 0
	s_nop 0
	s_nop 0
	s_nop 0
	s_nop 0
	s_waitcnt lgkmcnt(3)
	s_nop 0
	s_nop 0
	v_mov_b32_e32 v152, v196
	s_nop 0
	s_nop 0
	s_nop 0
	s_nop 0
	s_nop 0
	s_nop 0
	s_nop 0
	s_waitcnt lgkmcnt(0)
	s_nop 0
	s_nop 0
	v_ashrrev_i32_e32 v153, 1, v152
	v_and_b32_e32 v153, 0xffffffc0, v153
	v_and_b32_e32 v155, 31, v152
	v_add_u32_e32 v173, s58, v153
	v_lshrrev_b32_e32 v153, 3, v152
	v_lshlrev_b32_e32 v152, 1, v152
	v_and_b32_e32 v152, 0x80, v152
	v_or_b32_e32 v170, s57, v152
	v_or_b32_e32 v152, v170, v155
	v_lshlrev_b32_e32 v175, 8, v170
	s_nop 0
	v_lshlrev_b32_e32 v170, 10, v173
	v_and_b32_e32 v174, 4, v153
	v_and_b32_e32 v172, 0xfffc0000, v170
	v_lshlrev_b32_e32 v170, 5, v173
	v_lshlrev_b32_e32 v160, 2, v152
	v_lshlrev_b32_e32 v197, 3, v155
	v_and_b32_e32 v170, 0x1800, v170
	v_lshlrev_b32_e32 v228, 6, v174
	v_lshl_add_u64 v[152:153], s[30:31], 0, v[160:161]
	v_or_b32_e32 v160, v175, v197
	s_nop 0
	v_or3_b32 v229, v228, v170, v172
	v_or_b32_e32 v231, 10, v174
	v_or_b32_e32 v156, v229, v160
	v_ashrrev_i32_e32 v157, 31, v156
	v_or_b32_e32 v230, 1, v174
	v_or_b32_e32 v154, v173, v174
	v_lshl_add_u64 v[226:227], v[156:157], 1, s[0:1]
	s_nop 0
	v_or_b32_e32 v188, 2, v174
	v_or_b32_e32 v191, 9, v174
	v_or_b32_e32 v158, v173, v188
	v_or_b32_e32 v189, 3, v174
	v_ashrrev_i32_e32 v159, 31, v158
	v_or_b32_e32 v162, v173, v189
	v_or_b32_e32 v190, 8, v174
	s_nop 0
	v_or_b32_e32 v178, 11, v174
	v_or_b32_e32 v170, v173, v178
	v_ashrrev_i32_e32 v171, 31, v170
	v_or_b32_e32 v156, v173, v230
	v_lshlrev_b64 v[158:159], 12, v[158:159]
	v_ashrrev_i32_e32 v163, 31, v162
	v_or_b32_e32 v164, v173, v190
	s_nop 0
	v_lshlrev_b64 v[170:171], 12, v[170:171]
	v_ashrrev_i32_e32 v155, 31, v154
	v_ashrrev_i32_e32 v157, 31, v156
	v_lshl_add_u64 v[158:159], v[152:153], 0, v[158:159]
	v_lshlrev_b64 v[162:163], 12, v[162:163]
	v_ashrrev_i32_e32 v165, 31, v164
	v_lshl_add_u64 v[170:171], v[152:153], 0, v[170:171]
	s_nop 0
	v_or_b32_e32 v179, 16, v174
	v_lshlrev_b64 v[154:155], 12, v[154:155]
	v_lshlrev_b64 v[156:157], 12, v[156:157]
	global_store_dword v[158:159], v114, off
	v_lshl_add_u64 v[162:163], v[152:153], 0, v[162:163]
	v_lshlrev_b64 v[164:165], 12, v[164:165]
	global_store_dword v[170:171], v119, off
	s_nop 0
	v_or_b32_e32 v166, v173, v191
	v_or_b32_e32 v168, v173, v231
	v_ashrrev_i32_e32 v167, 31, v166
	v_ashrrev_i32_e32 v169, 31, v168
	v_lshlrev_b64 v[166:167], 12, v[166:167]
	v_lshlrev_b64 v[168:169], 12, v[168:169]
	v_lshl_add_u64 v[166:167], v[152:153], 0, v[166:167]
	v_lshl_add_u64 v[168:169], v[152:153], 0, v[168:169]
	global_store_dword v[166:167], v117, off
; DI bfr f2bf(float a) { return (bfr)(pack2(a, 0.f) & 0xffffu); }
; DI int crow(int reg, int h) { return (reg & 3) + 8 * (reg >> 2) + 4 * h; }
; template <int lda, class Epi>
; DI void gemm_tile(const bfr* __restrict__ A, const bfr* __restrict__ Bt, int NB, int K, int m0, int n0, char* smem, Epi epi) {
;     ...
;   int tid3 = threadIdx.x;
;   asm volatile("" : "+v"(tid3));
;   const int lane = tid3 & 63, wid = tid3 >> 6, wr = wid >> 1, wc = wid & 1, r = lane & 31, hl = lane >> 5;
; #pragma unroll
;   for (int i = 0; i < 2; ++i)
; #pragma unroll
;     for (int j = 0; j < 4; ++j)
; #pragma unroll
;       for (int q = 0; q < 16; ++q) {
;         int row = m0 + wr * 64 + i * 32 + crow(q, hl);
;         int col = n0 + wc * 128 + j * 32 + r;
;         epi(row, col, acc[i][j][q]);
;       }
; DI void phase_gemm_in_even(const Params& p, char* smem) {
;     ...
;                   [=](int row, int col, float v) {
;                     o[(size_t)row * 1024 + col] = v;
;                     const int ml = row & 15;
;                     const int rowpart = (row >> 8) * 262144 + ((row & 255) >> 4) * 512 + ((ml >> 2) & 1) * 256 + (((ml >> 3) << 2) | (ml & 3));
;                     const int colpart = (col >> 8) * 65536 + ((col & 255) >> 5) * 8192 + (col & 31) * 8;
;                     vt[rowpart + colpart] = f2bf(v);
;                   });
	global_store_dword v[168:169], v118, off
	v_cvt_pk_bf16_f32 v119, v118, v119
	v_cvt_pk_bf16_f32 v118, v116, v117
	v_cvt_pk_bf16_f32 v117, v114, v115
	v_or_b32_e32 v114, v173, v179
	v_lshl_add_u64 v[154:155], v[152:153], 0, v[154:155]
	v_lshl_add_u64 v[156:157], v[152:153], 0, v[156:157]
	global_store_dword v[162:163], v115, off
	v_lshl_add_u64 v[164:165], v[152:153], 0, v[164:165]
	v_ashrrev_i32_e32 v115, 31, v114
	global_store_dword v[154:155], v112, off
	global_store_dword v[156:157], v113, off
	global_store_dword v[164:165], v116, off
	v_cvt_pk_bf16_f32 v116, v112, v113
	v_lshlrev_b64 v[112:113], 12, v[114:115]
	v_lshlrev_b32_e32 v114, 5, v114
	v_or_b32_e32 v172, v172, v228
	s_nop 0
	v_and_or_b32 v180, v114, s49, v172
	v_or_b32_e32 v114, v180, v160
	v_ashrrev_i32_e32 v115, 31, v114
	global_store_dwordx4 v[226:227], v[116:119], off
	v_lshl_add_u64 v[114:115], v[114:115], 1, s[0:1]
	v_or_b32_e32 v181, 17, v174
	v_cvt_pk_bf16_f32 v116, v120, s0
	global_store_short v[114:115], v116, off
	v_or_b32_e32 v116, v173, v181
	v_ashrrev_i32_e32 v117, 31, v116
	v_lshlrev_b64 v[114:115], 12, v[116:117]
	v_lshlrev_b32_e32 v116, 5, v116
	v_and_or_b32 v182, v116, s49, v172
	v_or_b32_e32 v116, v182, v160
	v_ashrrev_i32_e32 v117, 31, v116
	v_cvt_pk_bf16_f32 v118, v121, s0
	v_lshl_add_u64 v[116:117], v[116:117], 1, s[0:1]
	v_or_b32_e32 v183, 18, v174
	global_store_short v[116:117], v118, off offset:2
	v_or_b32_e32 v118, v173, v183
	v_ashrrev_i32_e32 v119, 31, v118
	v_lshlrev_b64 v[116:117], 12, v[118:119]
	v_lshlrev_b32_e32 v118, 5, v118
	s_nop 0
	v_and_or_b32 v184, v118, s49, v172
	v_or_b32_e32 v118, v184, v160
	v_lshl_add_u64 v[112:113], v[152:153], 0, v[112:113]
	v_ashrrev_i32_e32 v119, 31, v118
	global_store_dword v[112:113], v120, off
	v_cvt_pk_bf16_f32 v120, v122, s0
	v_lshl_add_u64 v[118:119], v[118:119], 1, s[0:1]
	v_or_b32_e32 v185, 19, v174
	v_lshl_add_u64 v[114:115], v[152:153], 0, v[114:115]
	global_store_short v[118:119], v120, off offset:4
	v_or_b32_e32 v120, v173, v185
	global_store_dword v[114:115], v121, off
	v_ashrrev_i32_e32 v121, 31, v120
	v_lshlrev_b64 v[118:119], 12, v[120:121]
	v_lshlrev_b32_e32 v120, 5, v120
	v_and_or_b32 v186, v120, s49, v172
	v_or_b32_e32 v120, v186, v160
	v_lshl_add_u64 v[116:117], v[152:153], 0, v[116:117]
	v_ashrrev_i32_e32 v121, 31, v120
	global_store_dword v[116:117], v122, off
	v_cvt_pk_bf16_f32 v122, v123, s0
	v_lshl_add_u64 v[120:121], v[120:121], 1, s[0:1]
	v_or_b32_e32 v187, 24, v174
	v_lshl_add_u64 v[118:119], v[152:153], 0, v[118:119]
	global_store_short v[120:121], v122, off offset:6
	v_or_b32_e32 v122, v173, v187
	s_nop 0
	global_store_dword v[118:119], v123, off
	v_ashrrev_i32_e32 v123, 31, v122
	v_lshlrev_b64 v[120:121], 12, v[122:123]
	v_lshlrev_b32_e32 v122, 5, v122
	v_lshl_add_u64 v[120:121], v[152:153], 0, v[120:121]
	global_store_dword v[120:121], v124, off
	v_cvt_pk_bf16_f32 v124, v124, s0
	s_nop 0
	s_nop 0
	s_nop 0
	v_and_or_b32 v192, v122, s49, v172
	v_or_b32_e32 v122, v192, v160
	v_ashrrev_i32_e32 v123, 31, v122
	v_or_b32_e32 v193, 25, v174
	v_lshl_add_u64 v[122:123], v[122:123], 1, s[0:1]
	v_or_b32_e32 v176, v173, v193
	global_store_short v[122:123], v124, off offset:8
	s_nop 0
	v_ashrrev_i32_e32 v177, 31, v176
	v_lshlrev_b32_e32 v124, 5, v176
	v_lshlrev_b64 v[122:123], 12, v[176:177]
	v_and_or_b32 v177, v124, s49, v172
	v_lshl_add_u64 v[122:123], v[152:153], 0, v[122:123]
	v_or_b32_e32 v124, v177, v160
	global_store_dword v[122:123], v125, off
	s_nop 0
	v_cvt_pk_bf16_f32 v176, v125, s0
	v_ashrrev_i32_e32 v125, 31, v124
	v_lshl_add_u64 v[124:125], v[124:125], 1, s[0:1]
	global_store_short v[124:125], v176, off offset:10
	s_nop 0
	s_nop 6
	global_store_dword v[154:155], v96, off offset:128
	s_nop 0
	v_or_b32_e32 v146, 26, v174
	v_or_b32_e32 v144, v173, v146
	v_ashrrev_i32_e32 v145, 31, v144
	v_lshlrev_b64 v[124:125], 12, v[144:145]
	v_lshl_add_u64 v[124:125], v[152:153], 0, v[124:125]
	v_or_b32_e32 v145, 27, v174
	global_store_dword v[124:125], v126, off
	s_nop 0
	v_lshlrev_b32_e32 v136, 5, v144
	v_and_or_b32 v144, v136, s49, v172
	v_or_b32_e32 v136, v144, v160
	v_ashrrev_i32_e32 v137, 31, v136
	v_cvt_pk_bf16_f32 v126, v126, s0
	v_lshl_add_u64 v[136:137], v[136:137], 1, s[0:1]
	v_or_b32_e32 v138, v173, v145
	s_nop 0
	global_store_short v[136:137], v126, off offset:12
	v_ashrrev_i32_e32 v139, 31, v138
	v_lshlrev_b32_e32 v126, 5, v138
	v_lshlrev_b64 v[136:137], 12, v[138:139]
	v_and_or_b32 v139, v126, s49, v172
	v_lshl_add_u64 v[136:137], v[152:153], 0, v[136:137]
	v_or_b32_e32 v126, v139, v160
	s_nop 0
	global_store_dword v[136:137], v127, off
	v_cvt_pk_bf16_f32 v138, v127, s0
	v_ashrrev_i32_e32 v127, 31, v126
	v_lshl_add_u64 v[126:127], v[126:127], 1, s[0:1]
	global_store_short v[126:127], v138, off offset:14
	v_or_b32_e32 v126, 0x2000, v175
	v_and_or_b32 v126, v126, s50, v197
	s_nop 0
	global_store_dword v[156:157], v97, off offset:128
	global_store_dword v[158:159], v98, off offset:128
	global_store_dword v[162:163], v99, off offset:128
	global_store_dword v[164:165], v100, off offset:128
	global_store_dword v[166:167], v101, off offset:128
	global_store_dword v[168:169], v102, off offset:128
	global_store_dword v[170:171], v103, off offset:128
	v_cvt_pk_bf16_f32 v103, v102, v103
	v_cvt_pk_bf16_f32 v102, v100, v101
	v_cvt_pk_bf16_f32 v100, v96, v97
	v_or_b32_e32 v96, v126, v180
	v_ashrrev_i32_e32 v97, 31, v96
	v_cvt_pk_bf16_f32 v101, v98, v99
	s_nop 0
	v_cvt_pk_bf16_f32 v98, v104, s0
	v_lshl_add_u64 v[96:97], v[96:97], 1, s[0:1]
	s_nop 0
	s_nop 0
	v_or_b32_e32 v128, v126, v229
	v_ashrrev_i32_e32 v129, 31, v128
	v_lshl_add_u64 v[128:129], v[128:129], 1, s[0:1]
; DI bfr f2bf(float a) { return (bfr)(pack2(a, 0.f) & 0xffffu); }
; DI int crow(int reg, int h) { return (reg & 3) + 8 * (reg >> 2) + 4 * h; }
; template <int lda, class Epi>
; DI void gemm_tile(const bfr* __restrict__ A, const bfr* __restrict__ Bt, int NB, int K, int m0, int n0, char* smem, Epi epi) {
;     ...
;   int tid3 = threadIdx.x;
;   asm volatile("" : "+v"(tid3));
;   const int lane = tid3 & 63, wid = tid3 >> 6, wr = wid >> 1, wc = wid & 1, r = lane & 31, hl = lane >> 5;
; #pragma unroll
;   for (int i = 0; i < 2; ++i)
; #pragma unroll
;     for (int j = 0; j < 4; ++j)
; #pragma unroll
;       for (int q = 0; q < 16; ++q) {
;         int row = m0 + wr * 64 + i * 32 + crow(q, hl);
;         int col = n0 + wc * 128 + j * 32 + r;
;         epi(row, col, acc[i][j][q]);
;       }
; DI void phase_gemm_in_even(const Params& p, char* smem) {
;     ...
;                   [=](int row, int col, float v) {
;                     o[(size_t)row * 1024 + col] = v;
;                     const int ml = row & 15;
;                     const int rowpart = (row >> 8) * 262144 + ((row & 255) >> 4) * 512 + ((ml >> 2) & 1) * 256 + (((ml >> 3) << 2) | (ml & 3));
;                     const int colpart = (col >> 8) * 65536 + ((col & 255) >> 5) * 8192 + (col & 31) * 8;
;                     vt[rowpart + colpart] = f2bf(v);
;                   });
	global_store_dwordx4 v[128:129], v[100:103], off
	global_store_dword v[112:113], v104, off offset:128
	global_store_short v[96:97], v98, off
	global_store_dword v[114:115], v105, off offset:128
	v_or_b32_e32 v96, v126, v182
	v_ashrrev_i32_e32 v97, 31, v96
	v_cvt_pk_bf16_f32 v98, v105, s0
	v_lshl_add_u64 v[96:97], v[96:97], 1, s[0:1]
	global_store_short v[96:97], v98, off offset:2
	global_store_dword v[116:117], v106, off offset:128
	v_or_b32_e32 v96, v126, v184
	v_ashrrev_i32_e32 v97, 31, v96
	v_cvt_pk_bf16_f32 v98, v106, s0
	v_lshl_add_u64 v[96:97], v[96:97], 1, s[0:1]
	global_store_short v[96:97], v98, off offset:4
	global_store_dword v[118:119], v107, off offset:128
	v_or_b32_e32 v96, v126, v186
	v_ashrrev_i32_e32 v97, 31, v96
	v_cvt_pk_bf16_f32 v98, v107, s0
	v_lshl_add_u64 v[96:97], v[96:97], 1, s[0:1]
	global_store_short v[96:97], v98, off offset:6
	global_store_dword v[120:121], v108, off offset:128
	v_or_b32_e32 v96, v126, v192
	v_ashrrev_i32_e32 v97, 31, v96
	v_cvt_pk_bf16_f32 v98, v108, s0
	v_lshl_add_u64 v[96:97], v[96:97], 1, s[0:1]
	global_store_short v[96:97], v98, off offset:8
	global_store_dword v[122:123], v109, off offset:128
	v_or_b32_e32 v96, v126, v177
	v_ashrrev_i32_e32 v97, 31, v96
	v_cvt_pk_bf16_f32 v98, v109, s0
	v_lshl_add_u64 v[96:97], v[96:97], 1, s[0:1]
	global_store_short v[96:97], v98, off offset:10
	global_store_dword v[124:125], v110, off offset:128
	v_or_b32_e32 v96, v126, v144
	v_ashrrev_i32_e32 v97, 31, v96
	v_cvt_pk_bf16_f32 v98, v110, s0
	v_lshl_add_u64 v[96:97], v[96:97], 1, s[0:1]
	global_store_short v[96:97], v98, off offset:12
	global_store_dword v[136:137], v111, off offset:128
	v_or_b32_e32 v96, v126, v139
	v_ashrrev_i32_e32 v97, 31, v96
	v_cvt_pk_bf16_f32 v98, v111, s0
	v_lshl_add_u64 v[96:97], v[96:97], 1, s[0:1]
	global_store_short v[96:97], v98, off offset:14
	v_or_b32_e32 v96, 0x4000, v175
	v_and_or_b32 v96, v96, s51, v197
	global_store_dword v[154:155], v80, off offset:256
	v_or_b32_e32 v98, v96, v229
	global_store_dword v[156:157], v81, off offset:256
	global_store_dword v[158:159], v82, off offset:256
	global_store_dword v[162:163], v83, off offset:256
	global_store_dword v[164:165], v84, off offset:256
	global_store_dword v[166:167], v85, off offset:256
	global_store_dword v[168:169], v86, off offset:256
	global_store_dword v[170:171], v87, off offset:256
	v_cvt_pk_bf16_f32 v87, v86, v87
	v_cvt_pk_bf16_f32 v86, v84, v85
	v_cvt_pk_bf16_f32 v84, v80, v81
	v_or_b32_e32 v80, v96, v180
	v_ashrrev_i32_e32 v99, 31, v98
	v_ashrrev_i32_e32 v81, 31, v80
	v_lshl_add_u64 v[98:99], v[98:99], 1, s[0:1]
	v_cvt_pk_bf16_f32 v85, v82, v83
	v_cvt_pk_bf16_f32 v82, v88, s0
	v_lshl_add_u64 v[80:81], v[80:81], 1, s[0:1]
	global_store_dwordx4 v[98:99], v[84:87], off
	global_store_dword v[112:113], v88, off offset:256
	global_store_short v[80:81], v82, off
	global_store_dword v[114:115], v89, off offset:256
	v_or_b32_e32 v80, v96, v182
	v_ashrrev_i32_e32 v81, 31, v80
	v_cvt_pk_bf16_f32 v82, v89, s0
	v_lshl_add_u64 v[80:81], v[80:81], 1, s[0:1]
	global_store_short v[80:81], v82, off offset:2
	global_store_dword v[116:117], v90, off offset:256
	v_or_b32_e32 v80, v96, v184
	v_ashrrev_i32_e32 v81, 31, v80
	v_cvt_pk_bf16_f32 v82, v90, s0
	v_lshl_add_u64 v[80:81], v[80:81], 1, s[0:1]
	global_store_short v[80:81], v82, off offset:4
	global_store_dword v[118:119], v91, off offset:256
	v_or_b32_e32 v80, v96, v186
	v_ashrrev_i32_e32 v81, 31, v80
	v_cvt_pk_bf16_f32 v82, v91, s0
	v_lshl_add_u64 v[80:81], v[80:81], 1, s[0:1]
	global_store_short v[80:81], v82, off offset:6
	global_store_dword v[120:121], v92, off offset:256
	v_or_b32_e32 v80, v96, v192
	v_ashrrev_i32_e32 v81, 31, v80
	v_cvt_pk_bf16_f32 v82, v92, s0
	v_lshl_add_u64 v[80:81], v[80:81], 1, s[0:1]
	global_store_short v[80:81], v82, off offset:8
	global_store_dword v[122:123], v93, off offset:256
	v_or_b32_e32 v80, v96, v177
	v_ashrrev_i32_e32 v81, 31, v80
	v_cvt_pk_bf16_f32 v82, v93, s0
	v_lshl_add_u64 v[80:81], v[80:81], 1, s[0:1]
	global_store_short v[80:81], v82, off offset:10
	global_store_dword v[124:125], v94, off offset:256
	v_or_b32_e32 v80, v96, v144
	v_ashrrev_i32_e32 v81, 31, v80
	v_cvt_pk_bf16_f32 v82, v94, s0
	v_lshl_add_u64 v[80:81], v[80:81], 1, s[0:1]
	global_store_short v[80:81], v82, off offset:12
	global_store_dword v[136:137], v95, off offset:256
	v_or_b32_e32 v80, v96, v139
	v_ashrrev_i32_e32 v81, 31, v80
	v_cvt_pk_bf16_f32 v82, v95, s0
	v_lshl_add_u64 v[80:81], v[80:81], 1, s[0:1]
	global_store_short v[80:81], v82, off offset:14
	v_or_b32_e32 v80, 0x6000, v175
	v_and_or_b32 v82, v80, s52, v197
	global_store_dword v[154:155], v64, off offset:384
	v_or_b32_e32 v80, v82, v229
	global_store_dword v[156:157], v65, off offset:384
	global_store_dword v[158:159], v66, off offset:384
	global_store_dword v[162:163], v67, off offset:384
	global_store_dword v[164:165], v68, off offset:384
	global_store_dword v[166:167], v69, off offset:384
	global_store_dword v[168:169], v70, off offset:384
	global_store_dword v[170:171], v71, off offset:384
	v_cvt_pk_bf16_f32 v71, v70, v71
	v_cvt_pk_bf16_f32 v70, v68, v69
	v_cvt_pk_bf16_f32 v68, v64, v65
	v_or_b32_e32 v64, v82, v180
	v_ashrrev_i32_e32 v81, 31, v80
	v_ashrrev_i32_e32 v65, 31, v64
	v_lshl_add_u64 v[80:81], v[80:81], 1, s[0:1]
	v_cvt_pk_bf16_f32 v69, v66, v67
	v_cvt_pk_bf16_f32 v66, v72, s0
	v_lshl_add_u64 v[64:65], v[64:65], 1, s[0:1]
	global_store_dwordx4 v[80:81], v[68:71], off
	global_store_dword v[112:113], v72, off offset:384
	global_store_short v[64:65], v66, off
	global_store_dword v[114:115], v73, off offset:384
	v_or_b32_e32 v64, v82, v182
	v_ashrrev_i32_e32 v65, 31, v64
	v_cvt_pk_bf16_f32 v66, v73, s0
; DI bfr f2bf(float a) { return (bfr)(pack2(a, 0.f) & 0xffffu); }
; DI int crow(int reg, int h) { return (reg & 3) + 8 * (reg >> 2) + 4 * h; }
; template <int lda, class Epi>
; DI void gemm_tile(const bfr* __restrict__ A, const bfr* __restrict__ Bt, int NB, int K, int m0, int n0, char* smem, Epi epi) {
;     ...
;   int tid3 = threadIdx.x;
;   asm volatile("" : "+v"(tid3));
;   const int lane = tid3 & 63, wid = tid3 >> 6, wr = wid >> 1, wc = wid & 1, r = lane & 31, hl = lane >> 5;
; #pragma unroll
;   for (int i = 0; i < 2; ++i)
; #pragma unroll
;     for (int j = 0; j < 4; ++j)
; #pragma unroll
;       for (int q = 0; q < 16; ++q) {
;         int row = m0 + wr * 64 + i * 32 + crow(q, hl);
;         int col = n0 + wc * 128 + j * 32 + r;
;         epi(row, col, acc[i][j][q]);
;       }
; DI void phase_gemm_in_even(const Params& p, char* smem) {
;     ...
;                   [=](int row, int col, float v) {
;                     o[(size_t)row * 1024 + col] = v;
;                     const int ml = row & 15;
;                     const int rowpart = (row >> 8) * 262144 + ((row & 255) >> 4) * 512 + ((ml >> 2) & 1) * 256 + (((ml >> 3) << 2) | (ml & 3));
;                     const int colpart = (col >> 8) * 65536 + ((col & 255) >> 5) * 8192 + (col & 31) * 8;
;                     vt[rowpart + colpart] = f2bf(v);
;                   });
	v_lshl_add_u64 v[64:65], v[64:65], 1, s[0:1]
	global_store_short v[64:65], v66, off offset:2
	global_store_dword v[116:117], v74, off offset:384
	v_or_b32_e32 v64, v82, v184
	v_ashrrev_i32_e32 v65, 31, v64
	v_cvt_pk_bf16_f32 v66, v74, s0
	v_lshl_add_u64 v[64:65], v[64:65], 1, s[0:1]
	global_store_short v[64:65], v66, off offset:4
	global_store_dword v[118:119], v75, off offset:384
	v_or_b32_e32 v64, v82, v186
	v_ashrrev_i32_e32 v65, 31, v64
	v_cvt_pk_bf16_f32 v66, v75, s0
	v_lshl_add_u64 v[64:65], v[64:65], 1, s[0:1]
	global_store_short v[64:65], v66, off offset:6
	global_store_dword v[120:121], v76, off offset:384
	v_or_b32_e32 v64, v82, v192
	v_ashrrev_i32_e32 v65, 31, v64
	v_cvt_pk_bf16_f32 v66, v76, s0
	v_lshl_add_u64 v[64:65], v[64:65], 1, s[0:1]
	global_store_short v[64:65], v66, off offset:8
	global_store_dword v[122:123], v77, off offset:384
	v_or_b32_e32 v64, v82, v177
	v_ashrrev_i32_e32 v65, 31, v64
	v_cvt_pk_bf16_f32 v66, v77, s0
	v_lshl_add_u64 v[64:65], v[64:65], 1, s[0:1]
	global_store_short v[64:65], v66, off offset:10
	global_store_dword v[124:125], v78, off offset:384
	v_or_b32_e32 v64, v82, v144
	v_ashrrev_i32_e32 v65, 31, v64
	v_cvt_pk_bf16_f32 v66, v78, s0
	v_lshl_add_u64 v[64:65], v[64:65], 1, s[0:1]
	global_store_short v[64:65], v66, off offset:12
	global_store_dword v[136:137], v79, off offset:384
	v_or_b32_e32 v64, v82, v139
	v_ashrrev_i32_e32 v65, 31, v64
	v_cvt_pk_bf16_f32 v66, v79, s0
	v_lshl_add_u64 v[64:65], v[64:65], 1, s[0:1]
	v_or_b32_e32 v83, 32, v173
	global_store_short v[64:65], v66, off offset:14
	v_lshlrev_b32_e32 v66, 5, v83
	v_and_or_b32 v86, v66, s53, v172
	v_or_b32_e32 v66, v86, v160
	v_or_b32_e32 v68, v83, v188
	v_or_b32_e32 v74, v83, v191
	v_or_b32_e32 v76, v83, v231
	v_or_b32_e32 v78, v83, v178
	v_ashrrev_i32_e32 v67, 31, v66
	v_ashrrev_i32_e32 v69, 31, v68
	v_or_b32_e32 v70, v83, v189
	v_ashrrev_i32_e32 v75, 31, v74
	v_ashrrev_i32_e32 v77, 31, v76
	v_ashrrev_i32_e32 v79, 31, v78
	v_or_b32_e32 v64, v83, v174
	v_lshl_add_u64 v[80:81], v[66:67], 1, s[0:1]
	v_or_b32_e32 v66, v83, v230
	v_lshlrev_b64 v[68:69], 12, v[68:69]
	v_ashrrev_i32_e32 v71, 31, v70
	v_or_b32_e32 v72, v83, v190
	v_lshlrev_b64 v[74:75], 12, v[74:75]
	v_lshlrev_b64 v[76:77], 12, v[76:77]
	v_lshlrev_b64 v[78:79], 12, v[78:79]
	v_ashrrev_i32_e32 v65, 31, v64
	v_ashrrev_i32_e32 v67, 31, v66
	v_lshl_add_u64 v[68:69], v[152:153], 0, v[68:69]
	v_lshlrev_b64 v[70:71], 12, v[70:71]
	v_ashrrev_i32_e32 v73, 31, v72
	v_lshl_add_u64 v[74:75], v[152:153], 0, v[74:75]
	v_lshl_add_u64 v[76:77], v[152:153], 0, v[76:77]
	v_lshl_add_u64 v[78:79], v[152:153], 0, v[78:79]
	v_lshlrev_b64 v[64:65], 12, v[64:65]
	v_lshlrev_b64 v[66:67], 12, v[66:67]
	global_store_dword v[68:69], v50, off
	v_lshl_add_u64 v[70:71], v[152:153], 0, v[70:71]
	v_lshlrev_b64 v[72:73], 12, v[72:73]
	global_store_dword v[74:75], v53, off
	global_store_dword v[76:77], v54, off
	global_store_dword v[78:79], v55, off
	v_cvt_pk_bf16_f32 v55, v54, v55
	v_cvt_pk_bf16_f32 v54, v52, v53
	v_cvt_pk_bf16_f32 v53, v50, v51
	v_or_b32_e32 v50, v83, v179
	v_lshl_add_u64 v[64:65], v[152:153], 0, v[64:65]
	v_lshl_add_u64 v[66:67], v[152:153], 0, v[66:67]
	global_store_dword v[70:71], v51, off
	v_lshl_add_u64 v[72:73], v[152:153], 0, v[72:73]
	v_ashrrev_i32_e32 v51, 31, v50
	global_store_dword v[64:65], v48, off
	global_store_dword v[66:67], v49, off
	global_store_dword v[72:73], v52, off
	v_cvt_pk_bf16_f32 v52, v48, v49
	v_lshlrev_b64 v[48:49], 12, v[50:51]
	v_lshlrev_b32_e32 v50, 5, v50
	v_and_or_b32 v87, v50, s54, v172
	v_or_b32_e32 v50, v87, v160
	v_ashrrev_i32_e32 v51, 31, v50
	global_store_dwordx4 v[80:81], v[52:55], off
	v_lshl_add_u64 v[50:51], v[50:51], 1, s[0:1]
	v_lshl_add_u64 v[48:49], v[152:153], 0, v[48:49]
	v_cvt_pk_bf16_f32 v52, v56, s0
	global_store_short v[50:51], v52, off
	v_or_b32_e32 v52, v83, v181
	v_ashrrev_i32_e32 v53, 31, v52
	v_lshlrev_b64 v[50:51], 12, v[52:53]
	v_lshlrev_b32_e32 v52, 5, v52
	v_and_or_b32 v88, v52, s54, v172
	v_or_b32_e32 v52, v88, v160
	v_ashrrev_i32_e32 v53, 31, v52
	v_cvt_pk_bf16_f32 v54, v57, s0
	v_lshl_add_u64 v[52:53], v[52:53], 1, s[0:1]
	global_store_short v[52:53], v54, off offset:2
	v_or_b32_e32 v54, v83, v183
	v_ashrrev_i32_e32 v55, 31, v54
	v_lshlrev_b64 v[52:53], 12, v[54:55]
	v_lshlrev_b32_e32 v54, 5, v54
	v_and_or_b32 v89, v54, s54, v172
	v_or_b32_e32 v54, v89, v160
	v_ashrrev_i32_e32 v55, 31, v54
	global_store_dword v[48:49], v56, off
	v_cvt_pk_bf16_f32 v56, v58, s0
	v_lshl_add_u64 v[54:55], v[54:55], 1, s[0:1]
	v_lshl_add_u64 v[50:51], v[152:153], 0, v[50:51]
	global_store_short v[54:55], v56, off offset:4
	v_or_b32_e32 v56, v83, v185
	global_store_dword v[50:51], v57, off
	v_ashrrev_i32_e32 v57, 31, v56
	v_lshlrev_b64 v[54:55], 12, v[56:57]
	v_lshlrev_b32_e32 v56, 5, v56
	v_and_or_b32 v90, v56, s54, v172
	v_or_b32_e32 v56, v90, v160
	v_lshl_add_u64 v[52:53], v[152:153], 0, v[52:53]
	v_ashrrev_i32_e32 v57, 31, v56
	global_store_dword v[52:53], v58, off
	v_cvt_pk_bf16_f32 v58, v59, s0
	v_lshl_add_u64 v[56:57], v[56:57], 1, s[0:1]
	v_lshl_add_u64 v[54:55], v[152:153], 0, v[54:55]
	global_store_short v[56:57], v58, off offset:6
	v_or_b32_e32 v58, v83, v187
	global_store_dword v[54:55], v59, off
	v_ashrrev_i32_e32 v59, 31, v58
	v_lshlrev_b64 v[56:57], 12, v[58:59]
	v_lshlrev_b32_e32 v58, 5, v58
	v_and_or_b32 v91, v58, s54, v172
	v_or_b32_e32 v58, v91, v160
	v_lshl_add_u64 v[56:57], v[152:153], 0, v[56:57]
	v_ashrrev_i32_e32 v59, 31, v58
	global_store_dword v[56:57], v60, off
	v_cvt_pk_bf16_f32 v60, v60, s0
	v_lshl_add_u64 v[58:59], v[58:59], 1, s[0:1]
	v_or_b32_e32 v80, v83, v193
	global_store_short v[58:59], v60, off offset:8
; DI bfr f2bf(float a) { return (bfr)(pack2(a, 0.f) & 0xffffu); }
; DI int crow(int reg, int h) { return (reg & 3) + 8 * (reg >> 2) + 4 * h; }
; template <int lda, class Epi>
; DI void gemm_tile(const bfr* __restrict__ A, const bfr* __restrict__ Bt, int NB, int K, int m0, int n0, char* smem, Epi epi) {
;     ...
;   int tid3 = threadIdx.x;
;   asm volatile("" : "+v"(tid3));
;   const int lane = tid3 & 63, wid = tid3 >> 6, wr = wid >> 1, wc = wid & 1, r = lane & 31, hl = lane >> 5;
; #pragma unroll
;   for (int i = 0; i < 2; ++i)
; #pragma unroll
;     for (int j = 0; j < 4; ++j)
; #pragma unroll
;       for (int q = 0; q < 16; ++q) {
;         int row = m0 + wr * 64 + i * 32 + crow(q, hl);
;         int col = n0 + wc * 128 + j * 32 + r;
;         epi(row, col, acc[i][j][q]);
;       }
; DI void phase_gemm_in_even(const Params& p, char* smem) {
;     ...
;                   [=](int row, int col, float v) {
;                     o[(size_t)row * 1024 + col] = v;
;                     const int ml = row & 15;
;                     const int rowpart = (row >> 8) * 262144 + ((row & 255) >> 4) * 512 + ((ml >> 2) & 1) * 256 + (((ml >> 3) << 2) | (ml & 3));
;                     const int colpart = (col >> 8) * 65536 + ((col & 255) >> 5) * 8192 + (col & 31) * 8;
;                     vt[rowpart + colpart] = f2bf(v);
;                   });
	v_ashrrev_i32_e32 v81, 31, v80
	v_lshlrev_b32_e32 v60, 5, v80
	v_lshlrev_b64 v[58:59], 12, v[80:81]
	v_and_or_b32 v92, v60, s54, v172
	v_lshl_add_u64 v[58:59], v[152:153], 0, v[58:59]
	v_or_b32_e32 v60, v92, v160
	global_store_dword v[58:59], v61, off
	v_cvt_pk_bf16_f32 v80, v61, s0
	v_ashrrev_i32_e32 v61, 31, v60
	v_lshl_add_u64 v[60:61], v[60:61], 1, s[0:1]
	global_store_short v[60:61], v80, off offset:10
	v_or_b32_e32 v80, v83, v146
	v_ashrrev_i32_e32 v81, 31, v80
	v_lshlrev_b64 v[60:61], 12, v[80:81]
	v_lshlrev_b32_e32 v80, 5, v80
	v_and_or_b32 v93, v80, s54, v172
	v_or_b32_e32 v80, v93, v160
	v_lshl_add_u64 v[60:61], v[152:153], 0, v[60:61]
	v_ashrrev_i32_e32 v81, 31, v80
	global_store_dword v[60:61], v62, off
	v_cvt_pk_bf16_f32 v62, v62, s0
	v_lshl_add_u64 v[80:81], v[80:81], 1, s[0:1]
	v_or_b32_e32 v84, v83, v145
	global_store_short v[80:81], v62, off offset:12
	v_ashrrev_i32_e32 v85, 31, v84
	v_lshlrev_b32_e32 v62, 5, v84
	v_lshlrev_b64 v[80:81], 12, v[84:85]
	v_and_or_b32 v84, v62, s54, v172
	v_lshl_add_u64 v[80:81], v[152:153], 0, v[80:81]
	v_or_b32_e32 v62, v84, v160
	global_store_dword v[80:81], v63, off
	v_cvt_pk_bf16_f32 v83, v63, s0
	v_ashrrev_i32_e32 v63, 31, v62
	v_lshl_add_u64 v[62:63], v[62:63], 1, s[0:1]
	global_store_short v[62:63], v83, off offset:14
	global_store_dword v[64:65], v32, off offset:128
	v_or_b32_e32 v62, v126, v86
	global_store_dword v[66:67], v33, off offset:128
	global_store_dword v[68:69], v34, off offset:128
	global_store_dword v[70:71], v35, off offset:128
	global_store_dword v[72:73], v36, off offset:128
	global_store_dword v[74:75], v37, off offset:128
	global_store_dword v[76:77], v38, off offset:128
	global_store_dword v[78:79], v39, off offset:128
	v_cvt_pk_bf16_f32 v39, v38, v39
	v_cvt_pk_bf16_f32 v38, v36, v37
	v_cvt_pk_bf16_f32 v36, v32, v33
	v_or_b32_e32 v32, v87, v126
	v_ashrrev_i32_e32 v63, 31, v62
	v_ashrrev_i32_e32 v33, 31, v32
	v_lshl_add_u64 v[62:63], v[62:63], 1, s[0:1]
	v_cvt_pk_bf16_f32 v37, v34, v35
	v_cvt_pk_bf16_f32 v34, v40, s0
	v_lshl_add_u64 v[32:33], v[32:33], 1, s[0:1]
	global_store_dwordx4 v[62:63], v[36:39], off
	global_store_dword v[48:49], v40, off offset:128
	global_store_short v[32:33], v34, off
	global_store_dword v[50:51], v41, off offset:128
	v_or_b32_e32 v32, v88, v126
	v_ashrrev_i32_e32 v33, 31, v32
	v_cvt_pk_bf16_f32 v34, v41, s0
	v_lshl_add_u64 v[32:33], v[32:33], 1, s[0:1]
	global_store_short v[32:33], v34, off offset:2
	global_store_dword v[52:53], v42, off offset:128
	v_or_b32_e32 v32, v89, v126
	v_ashrrev_i32_e32 v33, 31, v32
	v_cvt_pk_bf16_f32 v34, v42, s0
	v_lshl_add_u64 v[32:33], v[32:33], 1, s[0:1]
	global_store_short v[32:33], v34, off offset:4
	global_store_dword v[54:55], v43, off offset:128
	v_or_b32_e32 v32, v90, v126
	v_ashrrev_i32_e32 v33, 31, v32
	v_cvt_pk_bf16_f32 v34, v43, s0
	v_lshl_add_u64 v[32:33], v[32:33], 1, s[0:1]
	global_store_short v[32:33], v34, off offset:6
	global_store_dword v[56:57], v44, off offset:128
	v_or_b32_e32 v32, v91, v126
	v_ashrrev_i32_e32 v33, 31, v32
	v_cvt_pk_bf16_f32 v34, v44, s0
	v_lshl_add_u64 v[32:33], v[32:33], 1, s[0:1]
	global_store_short v[32:33], v34, off offset:8
	global_store_dword v[58:59], v45, off offset:128
	v_or_b32_e32 v32, v92, v126
	v_ashrrev_i32_e32 v33, 31, v32
	v_cvt_pk_bf16_f32 v34, v45, s0
	v_lshl_add_u64 v[32:33], v[32:33], 1, s[0:1]
	global_store_short v[32:33], v34, off offset:10
	global_store_dword v[60:61], v46, off offset:128
	v_or_b32_e32 v32, v93, v126
	v_ashrrev_i32_e32 v33, 31, v32
	v_cvt_pk_bf16_f32 v34, v46, s0
	v_lshl_add_u64 v[32:33], v[32:33], 1, s[0:1]
	global_store_short v[32:33], v34, off offset:12
	global_store_dword v[80:81], v47, off offset:128
	v_or_b32_e32 v32, v84, v126
	v_ashrrev_i32_e32 v33, 31, v32
	v_cvt_pk_bf16_f32 v34, v47, s0
	v_lshl_add_u64 v[32:33], v[32:33], 1, s[0:1]
	global_store_short v[32:33], v34, off offset:14
	global_store_dword v[64:65], v16, off offset:256
	v_or_b32_e32 v32, v96, v86
	global_store_dword v[66:67], v17, off offset:256
	global_store_dword v[68:69], v18, off offset:256
	global_store_dword v[70:71], v19, off offset:256
	global_store_dword v[72:73], v20, off offset:256
	global_store_dword v[74:75], v21, off offset:256
	global_store_dword v[76:77], v22, off offset:256
	global_store_dword v[78:79], v23, off offset:256
	v_cvt_pk_bf16_f32 v23, v22, v23
	v_cvt_pk_bf16_f32 v22, v20, v21
	v_cvt_pk_bf16_f32 v20, v16, v17
	v_or_b32_e32 v16, v87, v96
	v_ashrrev_i32_e32 v33, 31, v32
	v_ashrrev_i32_e32 v17, 31, v16
	v_lshl_add_u64 v[32:33], v[32:33], 1, s[0:1]
	v_cvt_pk_bf16_f32 v21, v18, v19
	v_cvt_pk_bf16_f32 v18, v24, s0
	v_lshl_add_u64 v[16:17], v[16:17], 1, s[0:1]
	global_store_dwordx4 v[32:33], v[20:23], off
	global_store_dword v[48:49], v24, off offset:256
	global_store_short v[16:17], v18, off
	global_store_dword v[50:51], v25, off offset:256
	v_or_b32_e32 v16, v88, v96
	v_ashrrev_i32_e32 v17, 31, v16
	v_cvt_pk_bf16_f32 v18, v25, s0
	v_lshl_add_u64 v[16:17], v[16:17], 1, s[0:1]
	global_store_short v[16:17], v18, off offset:2
	global_store_dword v[52:53], v26, off offset:256
	v_or_b32_e32 v16, v89, v96
	v_ashrrev_i32_e32 v17, 31, v16
	v_cvt_pk_bf16_f32 v18, v26, s0
	v_lshl_add_u64 v[16:17], v[16:17], 1, s[0:1]
	global_store_short v[16:17], v18, off offset:4
	global_store_dword v[54:55], v27, off offset:256
	v_or_b32_e32 v16, v90, v96
	v_ashrrev_i32_e32 v17, 31, v16
	v_cvt_pk_bf16_f32 v18, v27, s0
	v_lshl_add_u64 v[16:17], v[16:17], 1, s[0:1]
	global_store_short v[16:17], v18, off offset:6
	global_store_dword v[56:57], v28, off offset:256
	v_or_b32_e32 v16, v91, v96
	v_ashrrev_i32_e32 v17, 31, v16
	v_cvt_pk_bf16_f32 v18, v28, s0
; DI bfr f2bf(float a) { return (bfr)(pack2(a, 0.f) & 0xffffu); }
; #define GA_LOAD(pr_) do { _Pragma("unroll") for (int i = 0; i < 4; ++i) ra[i] = *(const u32x4*)(Ab + (i * 32) * lda + (pr_) * 64); } while (0)
; #define GB_LOAD(kt_) do { const bfr* bk_ = Bb + (kt_) * NB * 32; \
;     _Pragma("unroll") for (int i = 0; i < 4; ++i) rb[i] = *(const u32x4*)(bk_ + (i * 64) * 32); } while (0)
; #define G_STORE(kt_) do { bfr* as_ = S0 + ((kt_) & 1) * GSTAGE; bfr* bs_ = as_ + 128 * 40; \
;     if (apar == ((kt_) & 1)) { _Pragma("unroll") for (int i = 0; i < 4; ++i) *(u32x4*)(as_ + asoff + i * 32 * 40) = ra[i]; } \
;     _Pragma("unroll") for (int i = 0; i < 4; ++i) *(u32x4*)(bs_ + bsoff + i * 64 * 40) = rb[i]; } while (0)
; template <int lda>
; DI void gemm_mainloop(const bfr* __restrict__ A, const bfr* __restrict__ Bt, int NB, int K, int m0, int n0, char* smem, f32x16 (&acc)[2][4]) {
;     ...
;   const int nk = K >> 5;
;   const int arow = tid >> 3, ac8 = tid & 7, apar = ac8 >> 2;
;   const bfr* Ab = A + (m0 + arow) * lda + ac8 * 8;
;   const int asoff = arow * 40 + (ac8 & 3) * 8;
;   const int brow = tid >> 2, bc4 = tid & 3;
;   const bfr* Bb = Bt + (n0 + brow) * 32 + bc4 * 8;
;   const int bsoff = brow * 40 + bc4 * 8;
;     ...
;   GA_LOAD(0);
;   GB_LOAD(0);
;   G_STORE(0);
;   GB_LOAD(1);
;   __syncthreads();
; DI void phase_gemm_in_even(const Params& p, char* smem) {
;     ...
;                   [=](int row, int col, float v) {
;                     o[(size_t)row * 1024 + col] = v;
;                     const int ml = row & 15;
;                     const int rowpart = (row >> 8) * 262144 + ((row & 255) >> 4) * 512 + ((ml >> 2) & 1) * 256 + (((ml >> 3) << 2) | (ml & 3));
;                     const int colpart = (col >> 8) * 65536 + ((col & 255) >> 5) * 8192 + (col & 31) * 8;
;                     vt[rowpart + colpart] = f2bf(v);
;                   });
	v_lshl_add_u64 v[16:17], v[16:17], 1, s[0:1]
	global_store_short v[16:17], v18, off offset:8
	global_store_dword v[58:59], v29, off offset:256
	v_or_b32_e32 v16, v92, v96
	v_ashrrev_i32_e32 v17, 31, v16
	v_cvt_pk_bf16_f32 v18, v29, s0
	v_lshl_add_u64 v[16:17], v[16:17], 1, s[0:1]
	global_store_short v[16:17], v18, off offset:10
	global_store_dword v[60:61], v30, off offset:256
	v_or_b32_e32 v16, v93, v96
	v_ashrrev_i32_e32 v17, 31, v16
	v_cvt_pk_bf16_f32 v18, v30, s0
	v_lshl_add_u64 v[16:17], v[16:17], 1, s[0:1]
	global_store_short v[16:17], v18, off offset:12
	global_store_dword v[80:81], v31, off offset:256
	v_or_b32_e32 v16, v84, v96
	v_ashrrev_i32_e32 v17, 31, v16
	v_cvt_pk_bf16_f32 v18, v31, s0
	v_lshl_add_u64 v[16:17], v[16:17], 1, s[0:1]
	global_store_short v[16:17], v18, off offset:14
	global_store_dword v[64:65], v0, off offset:384
	v_or_b32_e32 v16, v82, v86
	global_store_dword v[66:67], v1, off offset:384
	global_store_dword v[68:69], v2, off offset:384
	global_store_dword v[70:71], v3, off offset:384
	global_store_dword v[72:73], v4, off offset:384
	global_store_dword v[74:75], v5, off offset:384
	global_store_dword v[76:77], v6, off offset:384
	global_store_dword v[78:79], v7, off offset:384
	v_cvt_pk_bf16_f32 v7, v6, v7
	v_cvt_pk_bf16_f32 v6, v4, v5
	v_cvt_pk_bf16_f32 v4, v0, v1
	v_or_b32_e32 v0, v87, v82
	v_ashrrev_i32_e32 v17, 31, v16
	v_ashrrev_i32_e32 v1, 31, v0
	v_lshl_add_u64 v[16:17], v[16:17], 1, s[0:1]
	v_cvt_pk_bf16_f32 v5, v2, v3
	v_cvt_pk_bf16_f32 v2, v8, s0
	v_lshl_add_u64 v[0:1], v[0:1], 1, s[0:1]
	global_store_dwordx4 v[16:17], v[4:7], off
	global_store_dword v[48:49], v8, off offset:384
	global_store_short v[0:1], v2, off
	global_store_dword v[50:51], v9, off offset:384
	v_or_b32_e32 v0, v88, v82
	v_ashrrev_i32_e32 v1, 31, v0
	v_cvt_pk_bf16_f32 v2, v9, s0
	v_lshl_add_u64 v[0:1], v[0:1], 1, s[0:1]
	global_store_short v[0:1], v2, off offset:2
	global_store_dword v[52:53], v10, off offset:384
	v_or_b32_e32 v0, v89, v82
	v_ashrrev_i32_e32 v1, 31, v0
	v_cvt_pk_bf16_f32 v2, v10, s0
	v_lshl_add_u64 v[0:1], v[0:1], 1, s[0:1]
	global_store_short v[0:1], v2, off offset:4
	global_store_dword v[54:55], v11, off offset:384
	v_or_b32_e32 v0, v90, v82
	v_ashrrev_i32_e32 v1, 31, v0
	v_cvt_pk_bf16_f32 v2, v11, s0
	v_lshl_add_u64 v[0:1], v[0:1], 1, s[0:1]
	global_store_short v[0:1], v2, off offset:6
	global_store_dword v[56:57], v12, off offset:384
	v_or_b32_e32 v0, v91, v82
	v_ashrrev_i32_e32 v1, 31, v0
	v_cvt_pk_bf16_f32 v2, v12, s0
	v_lshl_add_u64 v[0:1], v[0:1], 1, s[0:1]
	global_store_short v[0:1], v2, off offset:8
	global_store_dword v[58:59], v13, off offset:384
	v_or_b32_e32 v0, v92, v82
	v_ashrrev_i32_e32 v1, 31, v0
	v_cvt_pk_bf16_f32 v2, v13, s0
	v_lshl_add_u64 v[0:1], v[0:1], 1, s[0:1]
	global_store_short v[0:1], v2, off offset:10
	global_store_dword v[60:61], v14, off offset:384
	v_or_b32_e32 v0, v93, v82
	v_ashrrev_i32_e32 v1, 31, v0
	v_cvt_pk_bf16_f32 v2, v14, s0
	v_lshl_add_u64 v[0:1], v[0:1], 1, s[0:1]
	global_store_short v[0:1], v2, off offset:12
	global_store_dword v[80:81], v15, off offset:384
	v_or_b32_e32 v0, v84, v82
	v_ashrrev_i32_e32 v1, 31, v0
	v_cvt_pk_bf16_f32 v2, v15, s0
	v_lshl_add_u64 v[0:1], v[0:1], 1, s[0:1]
	global_store_short v[0:1], v2, off offset:14
	s_mov_b64 s[0:1], 0
.LBB0_136:
	s_and_b64 vcc, exec, s[0:1]
	s_cbranch_vccz .LBB0_146
	s_add_u32 s0, s12, s2
	s_addc_u32 s1, s13, 0
	s_mov_b32 s59, 0
	s_mov_b64 s[30:31], 0
	s_lshl_b32 s98, s58, 11
	s_add_u32 s98, s8, s98
	s_addc_u32 s99, s9, 0
	s_lshl_b32 s100, s57, 6
	s_add_u32 s100, s0, s100
	s_addc_u32 s101, s1, 0
	v_writelane_b32 v188, s64, 0
	v_writelane_b32 v188, s65, 1
	v_writelane_b32 v188, s66, 2
	v_writelane_b32 v188, s67, 3
	v_writelane_b32 v188, s68, 4
	v_writelane_b32 v188, s69, 5
	v_writelane_b32 v188, s70, 6
	v_writelane_b32 v188, s71, 7
	v_writelane_b32 v188, s72, 8
	v_writelane_b32 v188, s73, 9
	v_writelane_b32 v188, s74, 10
	v_writelane_b32 v188, s75, 11
	v_writelane_b32 v188, s76, 12
	v_writelane_b32 v188, s77, 13
	v_writelane_b32 v188, s78, 14
	v_writelane_b32 v188, s79, 15
	v_lshrrev_b32_e32 v189, 6, v196
	v_and_b32_e32 v190, 63, v196
	v_readfirstlane_b32 s73, v189
	v_lshrrev_b32_e32 v191, 2, v190
	v_bfe_u32 v192, v190, 4, 2
	v_and_b32_e32 v189, 3, v190
	v_xor_b32_e32 v189, v189, v192
	v_lshlrev_b32_e32 v189, 4, v189
	v_lshl_add_u32 v160, v191, 11, v189
	v_add_u32_e32 v162, 0x8000, v160
	v_lshl_add_u32 v163, v191, 6, v189
	v_and_b32_e32 v191, 31, v190
	v_lshrrev_b32_e32 v192, 5, v190
	v_bfe_u32 v189, v190, 2, 2
	v_xor_b32_e32 v189, v189, v192
	v_lshlrev_b32_e32 v189, 4, v189
	v_lshl_add_u32 v180, v191, 6, v189
	s_lshr_b32 s74, s73, 1
	s_lshl_b32 s74, s74, 12
	s_and_b32 s75, s73, 1
	s_lshl_b32 s75, s75, 13
	v_add_u32_e32 v182, s75, v180
	v_add_u32_e32 v180, s74, v180
	v_xor_b32_e32 v183, 32, v182
	v_xor_b32_e32 v181, 32, v180
	s_lshl_b32 s74, s73, 16
	s_add_u32 s64, s98, s74
	s_addc_u32 s65, s99, 0
	s_lshl_b32 s74, s73, 12
	s_add_u32 s66, s100, s74
	s_addc_u32 s67, s101, 0
	s_lshl_b32 s68, s73, 11
	s_lshl_b32 s69, s73, 12
	s_mov_b32 s70, 0
	s_mov_b32 s71, 0
	s_mov_b32 s72, 0
	s_waitcnt lgkmcnt(0)
	s_barrier
; #define GA_LOAD(pr_) do { _Pragma("unroll") for (int i = 0; i < 4; ++i) ra[i] = *(const u32x4*)(Ab + (i * 32) * lda + (pr_) * 64); } while (0)
; #define GB_LOAD(kt_) do { const bfr* bk_ = Bb + (kt_) * NB * 32; \
;     _Pragma("unroll") for (int i = 0; i < 4; ++i) rb[i] = *(const u32x4*)(bk_ + (i * 64) * 32); } while (0)
; #define G_STORE(kt_) do { bfr* as_ = S0 + ((kt_) & 1) * GSTAGE; bfr* bs_ = as_ + 128 * 40; \
;     if (apar == ((kt_) & 1)) { _Pragma("unroll") for (int i = 0; i < 4; ++i) *(u32x4*)(as_ + asoff + i * 32 * 40) = ra[i]; } \
;     _Pragma("unroll") for (int i = 0; i < 4; ++i) *(u32x4*)(bs_ + bsoff + i * 64 * 40) = rb[i]; } while (0)
; template <int lda>
; DI void gemm_mainloop(const bfr* __restrict__ A, const bfr* __restrict__ Bt, int NB, int K, int m0, int n0, char* smem, f32x16 (&acc)[2][4]) {
;     ...
; #pragma unroll
;   for (int i = 0; i < 2; ++i)
; #pragma unroll
;     for (int j = 0; j < 4; ++j)
; #pragma unroll
;       for (int q = 0; q < 16; ++q) acc[i][j][q] = 0.f;
;   u32x4 ra[4], rb[4];
;   const int nk = K >> 5;
;   const int arow = tid >> 3, ac8 = tid & 7, apar = ac8 >> 2;
;   const bfr* Ab = A + (m0 + arow) * lda + ac8 * 8;
;   const int asoff = arow * 40 + (ac8 & 3) * 8;
;   const int brow = tid >> 2, bc4 = tid & 3;
;   const bfr* Bb = Bt + (n0 + brow) * 32 + bc4 * 8;
;   const int bsoff = brow * 40 + bc4 * 8;
;     ...
;   GA_LOAD(0);
;   GB_LOAD(0);
;   G_STORE(0);
;   GB_LOAD(1);
;   __syncthreads();
;   for (int kt = 0; kt < nk; ++kt) {
;     if (kt + 1 < nk) G_STORE(kt + 1);
;     if (kt + 2 < nk) {
;       GB_LOAD(kt + 2);
;       if ((kt & 1) == 0) GA_LOAD((kt >> 1) + 1);
	s_mul_i32 s74, s70, 0x6000
	s_add_u32 s75, s74, s68
	s_mov_b32 m0, s75
	s_add_u32 s76, s74, 0x2000
	s_cmp_eq_u32 s70, 2
	s_cselect_b32 s76, 0x10000, s76
	global_load_lds_dwordx4 v160, s[64:65]
	s_add_u32 m0, s75, 0x400
	s_add_u32 s76, s76, s69
	global_load_lds_dwordx4 v162, s[64:65]
	s_mov_b32 m0, s76
	s_add_u32 s64, s64, 64
	s_addc_u32 s65, s65, 0
	global_load_lds_dwordx4 v163, s[66:67]
	global_load_lds_dwordx4 v163, s[66:67] offset:1024
	global_load_lds_dwordx4 v163, s[66:67] offset:2048
	global_load_lds_dwordx4 v163, s[66:67] offset:3072
	s_add_u32 s66, s66, 0x10000
	s_addc_u32 s67, s67, 0
	s_add_u32 s70, s70, 1
	s_cmp_eq_u32 s70, 3
	s_cselect_b32 s70, 0, s70
	s_mul_i32 s74, s70, 0x6000
	s_add_u32 s75, s74, s68
	s_mov_b32 m0, s75
	s_add_u32 s76, s74, 0x2000
	s_cmp_eq_u32 s70, 2
	s_cselect_b32 s76, 0x10000, s76
	global_load_lds_dwordx4 v160, s[64:65]
	s_add_u32 m0, s75, 0x400
	s_add_u32 s76, s76, s69
	global_load_lds_dwordx4 v162, s[64:65]
	s_mov_b32 m0, s76
	s_add_u32 s64, s64, 64
	s_addc_u32 s65, s65, 0
	global_load_lds_dwordx4 v163, s[66:67]
	global_load_lds_dwordx4 v163, s[66:67] offset:1024
	global_load_lds_dwordx4 v163, s[66:67] offset:2048
	global_load_lds_dwordx4 v163, s[66:67] offset:3072
	s_add_u32 s66, s66, 0x10000
	s_addc_u32 s67, s67, 0
	s_add_u32 s70, s70, 1
	s_cmp_eq_u32 s70, 3
	s_cselect_b32 s70, 0, s70
	v_mov_b32_e32 v112, 0
	v_mov_b32_e32 v113, 0
	v_mov_b32_e32 v114, 0
	v_mov_b32_e32 v115, 0
	v_mov_b32_e32 v116, 0
	v_mov_b32_e32 v117, 0
	v_mov_b32_e32 v118, 0
	v_mov_b32_e32 v119, 0
	v_mov_b32_e32 v120, 0
	v_mov_b32_e32 v121, 0
	v_mov_b32_e32 v122, 0
	v_mov_b32_e32 v123, 0
	v_mov_b32_e32 v124, 0
	v_mov_b32_e32 v125, 0
	v_mov_b32_e32 v126, 0
	v_mov_b32_e32 v127, 0
	v_mov_b32_e32 v96, 0
	v_mov_b32_e32 v97, 0
	v_mov_b32_e32 v98, 0
	v_mov_b32_e32 v99, 0
	v_mov_b32_e32 v100, 0
	v_mov_b32_e32 v101, 0
	v_mov_b32_e32 v102, 0
	v_mov_b32_e32 v103, 0
	v_mov_b32_e32 v104, 0
	v_mov_b32_e32 v105, 0
	v_mov_b32_e32 v106, 0
	v_mov_b32_e32 v107, 0
	v_mov_b32_e32 v108, 0
	v_mov_b32_e32 v109, 0
	v_mov_b32_e32 v110, 0
	v_mov_b32_e32 v111, 0
	v_mov_b32_e32 v80, 0
	v_mov_b32_e32 v81, 0
	v_mov_b32_e32 v82, 0
	v_mov_b32_e32 v83, 0
	v_mov_b32_e32 v84, 0
	v_mov_b32_e32 v85, 0
	v_mov_b32_e32 v86, 0
	v_mov_b32_e32 v87, 0
	v_mov_b32_e32 v88, 0
	v_mov_b32_e32 v89, 0
	v_mov_b32_e32 v90, 0
	v_mov_b32_e32 v91, 0
	v_mov_b32_e32 v92, 0
	v_mov_b32_e32 v93, 0
	v_mov_b32_e32 v94, 0
	v_mov_b32_e32 v95, 0
	v_mov_b32_e32 v64, 0
	v_mov_b32_e32 v65, 0
	v_mov_b32_e32 v66, 0
	v_mov_b32_e32 v67, 0
	v_mov_b32_e32 v68, 0
	v_mov_b32_e32 v69, 0
	v_mov_b32_e32 v70, 0
	v_mov_b32_e32 v71, 0
	v_mov_b32_e32 v72, 0
	v_mov_b32_e32 v73, 0
	v_mov_b32_e32 v74, 0
	v_mov_b32_e32 v75, 0
	v_mov_b32_e32 v76, 0
	v_mov_b32_e32 v77, 0
	v_mov_b32_e32 v78, 0
	v_mov_b32_e32 v79, 0
	v_mov_b32_e32 v48, 0
	v_mov_b32_e32 v49, 0
	v_mov_b32_e32 v50, 0
	v_mov_b32_e32 v51, 0
	v_mov_b32_e32 v52, 0
	v_mov_b32_e32 v53, 0
	v_mov_b32_e32 v54, 0
	v_mov_b32_e32 v55, 0
	v_mov_b32_e32 v56, 0
	v_mov_b32_e32 v57, 0
	v_mov_b32_e32 v58, 0
	v_mov_b32_e32 v59, 0
	v_mov_b32_e32 v60, 0
	v_mov_b32_e32 v61, 0
	v_mov_b32_e32 v62, 0
	v_mov_b32_e32 v63, 0
	v_mov_b32_e32 v32, 0
	v_mov_b32_e32 v33, 0
	v_mov_b32_e32 v34, 0
	v_mov_b32_e32 v35, 0
	v_mov_b32_e32 v36, 0
	v_mov_b32_e32 v37, 0
	v_mov_b32_e32 v38, 0
	v_mov_b32_e32 v39, 0
	v_mov_b32_e32 v40, 0
	v_mov_b32_e32 v41, 0
	v_mov_b32_e32 v42, 0
	v_mov_b32_e32 v43, 0
	v_mov_b32_e32 v44, 0
	v_mov_b32_e32 v45, 0
	v_mov_b32_e32 v46, 0
	v_mov_b32_e32 v47, 0
	v_mov_b32_e32 v16, 0
	v_mov_b32_e32 v17, 0
	v_mov_b32_e32 v18, 0
	v_mov_b32_e32 v19, 0
	v_mov_b32_e32 v20, 0
	v_mov_b32_e32 v21, 0
	v_mov_b32_e32 v22, 0
	v_mov_b32_e32 v23, 0
	v_mov_b32_e32 v24, 0
	v_mov_b32_e32 v25, 0
	v_mov_b32_e32 v26, 0
	v_mov_b32_e32 v27, 0
	v_mov_b32_e32 v28, 0
	v_mov_b32_e32 v29, 0
	v_mov_b32_e32 v30, 0
	v_mov_b32_e32 v31, 0
	v_mov_b32_e32 v0, 0
	v_mov_b32_e32 v1, 0
	v_mov_b32_e32 v2, 0
	v_mov_b32_e32 v3, 0
	v_mov_b32_e32 v4, 0
	v_mov_b32_e32 v5, 0
	v_mov_b32_e32 v6, 0
	v_mov_b32_e32 v7, 0
	v_mov_b32_e32 v8, 0
	v_mov_b32_e32 v9, 0
	v_mov_b32_e32 v10, 0
	v_mov_b32_e32 v11, 0
	v_mov_b32_e32 v12, 0
	v_mov_b32_e32 v13, 0
	v_mov_b32_e32 v14, 0
	v_mov_b32_e32 v15, 0
.Lp1k_loop:
	s_waitcnt vmcnt(6)
	s_barrier
	s_mul_i32 s74, s70, 0x6000
	s_add_u32 s75, s74, s68
	s_mov_b32 m0, s75
	s_add_u32 s76, s74, 0x2000
	s_cmp_eq_u32 s70, 2
	s_cselect_b32 s76, 0x10000, s76
	global_load_lds_dwordx4 v160, s[64:65]
	s_add_u32 m0, s75, 0x400
	s_add_u32 s76, s76, s69
	global_load_lds_dwordx4 v162, s[64:65]
	s_mov_b32 m0, s76
	s_add_u32 s64, s64, 64
	s_addc_u32 s65, s65, 0
	global_load_lds_dwordx4 v163, s[66:67]
	global_load_lds_dwordx4 v163, s[66:67] offset:1024
	global_load_lds_dwordx4 v163, s[66:67] offset:2048
	global_load_lds_dwordx4 v163, s[66:67] offset:3072
	s_add_u32 s66, s66, 0x10000
	s_addc_u32 s67, s67, 0
	s_add_u32 s70, s70, 1
	s_cmp_eq_u32 s70, 3
	s_cselect_b32 s70, 0, s70
	s_mul_i32 s74, s71, 0x6000
	s_add_u32 s75, s74, 0x2000
	s_cmp_eq_u32 s71, 2
	s_cselect_b32 s75, 0x10000, s75
	v_add_u32_e32 v184, s74, v180
	v_add_u32_e32 v186, s75, v182
	v_add_u32_e32 v185, s74, v181
	v_add_u32_e32 v187, s75, v183
	ds_read_b128 v[128:131], v184
	ds_read_b128 v[144:147], v186
	ds_read_b128 v[148:151], v186 offset:2048
	ds_read_b128 v[152:155], v186 offset:4096
	ds_read_b128 v[156:159], v186 offset:6144
	ds_read_b128 v[132:135], v184 offset:2048
	ds_read_b128 v[136:139], v185
	ds_read_b128 v[164:167], v187
	ds_read_b128 v[168:171], v187 offset:2048
	ds_read_b128 v[172:175], v187 offset:4096
	ds_read_b128 v[176:179], v187 offset:6144
	ds_read_b128 v[140:143], v185 offset:2048
	s_add_u32 s71, s71, 1
	s_cmp_eq_u32 s71, 3
	s_cselect_b32 s71, 0, s71
	s_waitcnt lgkmcnt(10)
; #define MFMA32(a, b, c) __builtin_amdgcn_mfma_f32_32x32x16_bf16((a), (b), (c), 0, 0, 0)
; #define GA_LOAD(pr_) do { _Pragma("unroll") for (int i = 0; i < 4; ++i) ra[i] = *(const u32x4*)(Ab + (i * 32) * lda + (pr_) * 64); } while (0)
; #define GB_LOAD(kt_) do { const bfr* bk_ = Bb + (kt_) * NB * 32; \
;     _Pragma("unroll") for (int i = 0; i < 4; ++i) rb[i] = *(const u32x4*)(bk_ + (i * 64) * 32); } while (0)
; #define G_STORE(kt_) do { bfr* as_ = S0 + ((kt_) & 1) * GSTAGE; bfr* bs_ = as_ + 128 * 40; \
;     if (apar == ((kt_) & 1)) { _Pragma("unroll") for (int i = 0; i < 4; ++i) *(u32x4*)(as_ + asoff + i * 32 * 40) = ra[i]; } \
;     _Pragma("unroll") for (int i = 0; i < 4; ++i) *(u32x4*)(bs_ + bsoff + i * 64 * 40) = rb[i]; } while (0)
; template <int lda>
; DI void gemm_mainloop(const bfr* __restrict__ A, const bfr* __restrict__ Bt, int NB, int K, int m0, int n0, char* smem, f32x16 (&acc)[2][4]) {
;     ...
;   for (int kt = 0; kt < nk; ++kt) {
;     if (kt + 1 < nk) G_STORE(kt + 1);
;     if (kt + 2 < nk) {
;       GB_LOAD(kt + 2);
;       if ((kt & 1) == 0) GA_LOAD((kt >> 1) + 1);
;     }
;     const bfr* As = S0 + (kt & 1) * GSTAGE;
;     const bfr* Bs = As + 128 * 40;
; #pragma unroll
;     for (int ks = 0; ks < 2; ++ks) {
;       bf16x8 af[2], bfg[4];
; #pragma unroll
;       for (int i = 0; i < 2; ++i) af[i] = *(const bf16x8*)(As + (wr * 64 + i * 32 + r) * 40 + ks * 16 + hl * 8);
; #pragma unroll
;       for (int j = 0; j < 4; ++j) bfg[j] = *(const bf16x8*)(Bs + (wc * 128 + j * 32 + r) * 40 + ks * 16 + hl * 8);
; #pragma unroll
;       for (int i = 0; i < 2; ++i)
; #pragma unroll
;         for (int j = 0; j < 4; ++j) acc[i][j] = MFMA32(af[i], bfg[j], acc[i][j]);
;     }
;     __syncthreads();
;   }
	v_mfma_f32_32x32x16_bf16 v[112:127], v[128:131], v[144:147], v[112:127]
	s_waitcnt lgkmcnt(9)
	v_mfma_f32_32x32x16_bf16 v[96:111], v[128:131], v[148:151], v[96:111]
	s_waitcnt lgkmcnt(8)
	v_mfma_f32_32x32x16_bf16 v[80:95], v[128:131], v[152:155], v[80:95]
	s_waitcnt lgkmcnt(7)
	v_mfma_f32_32x32x16_bf16 v[64:79], v[128:131], v[156:159], v[64:79]
	s_waitcnt lgkmcnt(6)
	v_mfma_f32_32x32x16_bf16 v[48:63], v[132:135], v[144:147], v[48:63]
	v_mfma_f32_32x32x16_bf16 v[32:47], v[132:135], v[148:151], v[32:47]
	v_mfma_f32_32x32x16_bf16 v[16:31], v[132:135], v[152:155], v[16:31]
	v_mfma_f32_32x32x16_bf16 v[0:15], v[132:135], v[156:159], v[0:15]
	s_waitcnt lgkmcnt(4)
	v_mfma_f32_32x32x16_bf16 v[112:127], v[136:139], v[164:167], v[112:127]
	s_waitcnt lgkmcnt(3)
	v_mfma_f32_32x32x16_bf16 v[96:111], v[136:139], v[168:171], v[96:111]
	s_waitcnt lgkmcnt(2)
	v_mfma_f32_32x32x16_bf16 v[80:95], v[136:139], v[172:175], v[80:95]
	s_waitcnt lgkmcnt(1)
	v_mfma_f32_32x32x16_bf16 v[64:79], v[136:139], v[176:179], v[64:79]
	s_waitcnt lgkmcnt(0)
	v_mfma_f32_32x32x16_bf16 v[48:63], v[140:143], v[164:167], v[48:63]
	v_mfma_f32_32x32x16_bf16 v[32:47], v[140:143], v[168:171], v[32:47]
	v_mfma_f32_32x32x16_bf16 v[16:31], v[140:143], v[172:175], v[16:31]
	v_mfma_f32_32x32x16_bf16 v[0:15], v[140:143], v[176:179], v[0:15]
	s_add_u32 s72, s72, 1
	s_cmp_lt_u32 s72, 30
	s_cbranch_scc1 .Lp1k_loop
	s_waitcnt vmcnt(6)
	s_barrier
	s_mul_i32 s74, s71, 0x6000
	s_add_u32 s75, s74, 0x2000
	s_cmp_eq_u32 s71, 2
	s_cselect_b32 s75, 0x10000, s75
	v_add_u32_e32 v184, s74, v180
	v_add_u32_e32 v186, s75, v182
	v_add_u32_e32 v185, s74, v181
	v_add_u32_e32 v187, s75, v183
	ds_read_b128 v[128:131], v184
	ds_read_b128 v[144:147], v186
	ds_read_b128 v[148:151], v186 offset:2048
	ds_read_b128 v[152:155], v186 offset:4096
	ds_read_b128 v[156:159], v186 offset:6144
	ds_read_b128 v[132:135], v184 offset:2048
	ds_read_b128 v[136:139], v185
	ds_read_b128 v[164:167], v187
	ds_read_b128 v[168:171], v187 offset:2048
	ds_read_b128 v[172:175], v187 offset:4096
	ds_read_b128 v[176:179], v187 offset:6144
	ds_read_b128 v[140:143], v185 offset:2048
	s_add_u32 s71, s71, 1
	s_cmp_eq_u32 s71, 3
	s_cselect_b32 s71, 0, s71
	s_waitcnt lgkmcnt(10)
	v_mfma_f32_32x32x16_bf16 v[112:127], v[128:131], v[144:147], v[112:127]
	s_waitcnt lgkmcnt(9)
	v_mfma_f32_32x32x16_bf16 v[96:111], v[128:131], v[148:151], v[96:111]
	s_waitcnt lgkmcnt(8)
	v_mfma_f32_32x32x16_bf16 v[80:95], v[128:131], v[152:155], v[80:95]
	s_waitcnt lgkmcnt(7)
	v_mfma_f32_32x32x16_bf16 v[64:79], v[128:131], v[156:159], v[64:79]
	s_waitcnt lgkmcnt(6)
	v_mfma_f32_32x32x16_bf16 v[48:63], v[132:135], v[144:147], v[48:63]
	v_mfma_f32_32x32x16_bf16 v[32:47], v[132:135], v[148:151], v[32:47]
	v_mfma_f32_32x32x16_bf16 v[16:31], v[132:135], v[152:155], v[16:31]
	v_mfma_f32_32x32x16_bf16 v[0:15], v[132:135], v[156:159], v[0:15]
	s_waitcnt lgkmcnt(4)
	v_mfma_f32_32x32x16_bf16 v[112:127], v[136:139], v[164:167], v[112:127]
	s_waitcnt lgkmcnt(3)
	v_mfma_f32_32x32x16_bf16 v[96:111], v[136:139], v[168:171], v[96:111]
	s_waitcnt lgkmcnt(2)
	v_mfma_f32_32x32x16_bf16 v[80:95], v[136:139], v[172:175], v[80:95]
	s_waitcnt lgkmcnt(1)
	v_mfma_f32_32x32x16_bf16 v[64:79], v[136:139], v[176:179], v[64:79]
	s_waitcnt lgkmcnt(0)
	v_mfma_f32_32x32x16_bf16 v[48:63], v[140:143], v[164:167], v[48:63]
	v_mfma_f32_32x32x16_bf16 v[32:47], v[140:143], v[168:171], v[32:47]
	v_mfma_f32_32x32x16_bf16 v[16:31], v[140:143], v[172:175], v[16:31]
	v_mfma_f32_32x32x16_bf16 v[0:15], v[140:143], v[176:179], v[0:15]
	s_waitcnt vmcnt(0)
	s_barrier
	s_mul_i32 s74, s71, 0x6000
	s_add_u32 s75, s74, 0x2000
	s_cmp_eq_u32 s71, 2
	s_cselect_b32 s75, 0x10000, s75
	v_add_u32_e32 v184, s74, v180
	v_add_u32_e32 v186, s75, v182
	v_add_u32_e32 v185, s74, v181
	v_add_u32_e32 v187, s75, v183
	ds_read_b128 v[128:131], v184
	ds_read_b128 v[144:147], v186
	ds_read_b128 v[148:151], v186 offset:2048
	ds_read_b128 v[152:155], v186 offset:4096
	ds_read_b128 v[156:159], v186 offset:6144
	ds_read_b128 v[132:135], v184 offset:2048
	ds_read_b128 v[136:139], v185
	ds_read_b128 v[164:167], v187
	ds_read_b128 v[168:171], v187 offset:2048
	ds_read_b128 v[172:175], v187 offset:4096
	ds_read_b128 v[176:179], v187 offset:6144
	ds_read_b128 v[140:143], v185 offset:2048
	s_add_u32 s71, s71, 1
	s_cmp_eq_u32 s71, 3
	s_cselect_b32 s71, 0, s71
	s_waitcnt lgkmcnt(10)
	v_mfma_f32_32x32x16_bf16 v[112:127], v[128:131], v[144:147], v[112:127]
	s_waitcnt lgkmcnt(9)
	v_mfma_f32_32x32x16_bf16 v[96:111], v[128:131], v[148:151], v[96:111]
	s_waitcnt lgkmcnt(8)
	v_mfma_f32_32x32x16_bf16 v[80:95], v[128:131], v[152:155], v[80:95]
	s_waitcnt lgkmcnt(7)
	v_mfma_f32_32x32x16_bf16 v[64:79], v[128:131], v[156:159], v[64:79]
	s_waitcnt lgkmcnt(6)
	v_mfma_f32_32x32x16_bf16 v[48:63], v[132:135], v[144:147], v[48:63]
	v_mfma_f32_32x32x16_bf16 v[32:47], v[132:135], v[148:151], v[32:47]
	v_mfma_f32_32x32x16_bf16 v[16:31], v[132:135], v[152:155], v[16:31]
	v_mfma_f32_32x32x16_bf16 v[0:15], v[132:135], v[156:159], v[0:15]
	s_waitcnt lgkmcnt(4)
	v_mfma_f32_32x32x16_bf16 v[112:127], v[136:139], v[164:167], v[112:127]
	s_waitcnt lgkmcnt(3)
	v_mfma_f32_32x32x16_bf16 v[96:111], v[136:139], v[168:171], v[96:111]
	s_waitcnt lgkmcnt(2)
	v_mfma_f32_32x32x16_bf16 v[80:95], v[136:139], v[172:175], v[80:95]
	s_waitcnt lgkmcnt(1)
	v_mfma_f32_32x32x16_bf16 v[64:79], v[136:139], v[176:179], v[64:79]
	s_waitcnt lgkmcnt(0)
	v_mfma_f32_32x32x16_bf16 v[48:63], v[140:143], v[164:167], v[48:63]
	v_mfma_f32_32x32x16_bf16 v[32:47], v[140:143], v[168:171], v[32:47]
	v_mfma_f32_32x32x16_bf16 v[16:31], v[140:143], v[172:175], v[16:31]
	v_mfma_f32_32x32x16_bf16 v[0:15], v[140:143], v[176:179], v[0:15]
	s_nop 7
	v_readlane_b32 s64, v188, 0
	v_readlane_b32 s65, v188, 1
	v_readlane_b32 s66, v188, 2
	v_readlane_b32 s67, v188, 3
	v_readlane_b32 s68, v188, 4
	v_readlane_b32 s69, v188, 5
	v_readlane_b32 s70, v188, 6
	v_readlane_b32 s71, v188, 7
	v_readlane_b32 s72, v188, 8
	v_readlane_b32 s73, v188, 9
	v_readlane_b32 s74, v188, 10
	v_readlane_b32 s75, v188, 11
	v_readlane_b32 s76, v188, 12
	v_readlane_b32 s77, v188, 13
	v_readlane_b32 s78, v188, 14
	v_readlane_b32 s79, v188, 15
	s_nop 7
	s_branch .Lp1k_tail

; DI bfr f2bf(float a) { return (bfr)(pack2(a, 0.f) & 0xffffu); }
; DI int crow(int reg, int h) { return (reg & 3) + 8 * (reg >> 2) + 4 * h; }
; template <int lda, class Epi>
; DI void gemm_tile(const bfr* __restrict__ A, const bfr* __restrict__ Bt, int NB, int K, int m0, int n0, char* smem, Epi epi) {
;     ...
;   int tid3 = threadIdx.x;
;   asm volatile("" : "+v"(tid3));
;   const int lane = tid3 & 63, wid = tid3 >> 6, wr = wid >> 1, wc = wid & 1, r = lane & 31, hl = lane >> 5;
; #pragma unroll
;   for (int i = 0; i < 2; ++i)
; #pragma unroll
;     for (int j = 0; j < 4; ++j)
; #pragma unroll
;       for (int q = 0; q < 16; ++q) {
;         int row = m0 + wr * 64 + i * 32 + crow(q, hl);
;         int col = n0 + wc * 128 + j * 32 + r;
;         epi(row, col, acc[i][j][q]);
;       }
; DI void phase_gemm_in_even(const Params& p, char* smem) {
;     ...
;         float* o = p.out + O_MEMK + (size_t)l * 2097152;
;         bfr* kb = p.KB + (size_t)l * 2097152;
;         gemm_tile<1024>(p.MPB, p.WtXk + (size_t)l * 1048576, 1024, 1024, mt * 128, nt * 256, smem,
;                   [=](int row, int col, float v) {
;                     o[(size_t)row * 1024 + col] = v;
;                     kb[(size_t)row * 1024 + col] = f2bf(v);
;                   });
.Lp1k_tail:
	s_waitcnt vmcnt(1)
	s_nop 0
	s_nop 0
	s_nop 0
	s_waitcnt vmcnt(0)
	s_nop 0
	v_add_u32_e32 v144, v171, v173
	s_nop 0
	v_add_u32_e32 v152, v171, v172
	s_nop 0
	s_nop 0
	s_nop 0
	s_nop 0
	s_nop 0
	s_nop 0
	s_nop 0
	s_nop 0
	s_nop 0
	s_nop 0
	s_nop 0
	s_waitcnt lgkmcnt(0)
	s_nop 0
	s_nop 0
	v_mov_b32_e32 v153, v196
	s_lshl_b32 s0, s2, 2
	s_add_u32 s0, s39, s0
	s_addc_u32 s1, s40, 0
	s_lshl_b32 s2, s2, 1
	s_nop 0
	s_add_u32 s30, s4, s2
	s_addc_u32 s31, s5, 0
	s_nop 0
	s_nop 0
	s_nop 0
	s_nop 0
	s_nop 0
	s_nop 0
	s_nop 0
	s_nop 0
	s_nop 0
	s_waitcnt lgkmcnt(3)
	s_nop 0
	s_nop 0
	s_nop 0
	s_nop 0
	s_nop 0
	s_nop 0
	s_nop 0
	s_nop 0
	s_waitcnt lgkmcnt(0)
	s_nop 0
	s_nop 0
	v_ashrrev_i32_e32 v152, 1, v153
	s_nop 0
	v_and_b32_e32 v152, 0xffffffc0, v152
	v_and_b32_e32 v154, 31, v153
	v_lshrrev_b32_e32 v155, 3, v153
	v_add_u32_e32 v152, s58, v152
	v_lshlrev_b32_e32 v153, 1, v153
	v_and_or_b32 v152, v155, 4, v152
	v_and_b32_e32 v153, 0x80, v153
	v_or3_b32 v160, v154, v153, s57
	v_ashrrev_i32_e32 v153, 31, v152
	v_or_b32_e32 v158, 1, v152
	v_lshlrev_b64 v[156:157], 10, v[152:153]
	v_ashrrev_i32_e32 v159, 31, v158
	v_or_b32_e32 v156, v156, v160
	s_nop 0
	v_lshlrev_b64 v[162:163], 10, v[158:159]
	v_lshl_add_u64 v[154:155], v[156:157], 2, s[0:1]
	v_or_b32_e32 v162, v162, v160
	global_store_dword v[154:155], v112, off
	v_cvt_pk_bf16_f32 v112, v112, s0
	v_lshl_add_u64 v[156:157], v[156:157], 1, s[30:31]
	v_lshl_add_u64 v[158:159], v[162:163], 2, s[0:1]
	global_store_short v[156:157], v112, off
	global_store_dword v[158:159], v113, off
	v_cvt_pk_bf16_f32 v153, v113, s0
	v_lshl_add_u64 v[112:113], v[162:163], 1, s[30:31]
	v_or_b32_e32 v162, 2, v152
	s_nop 0
	v_ashrrev_i32_e32 v163, 31, v162
	v_or_b32_e32 v166, 3, v152
	v_lshlrev_b64 v[164:165], 10, v[162:163]
	v_ashrrev_i32_e32 v167, 31, v166
	v_or_b32_e32 v164, v164, v160
	v_lshlrev_b64 v[168:169], 10, v[166:167]
	v_lshl_add_u64 v[162:163], v[164:165], 2, s[0:1]
	v_or_b32_e32 v168, v168, v160
	global_store_dword v[162:163], v114, off
	v_cvt_pk_bf16_f32 v114, v114, s0
	v_lshl_add_u64 v[164:165], v[164:165], 1, s[30:31]
	v_lshl_add_u64 v[166:167], v[168:169], 2, s[0:1]
	global_store_short v[112:113], v153, off
	global_store_short v[164:165], v114, off
	global_store_dword v[166:167], v115, off
	v_cvt_pk_bf16_f32 v153, v115, s0
	v_lshl_add_u64 v[114:115], v[168:169], 1, s[30:31]
	v_or_b32_e32 v168, 8, v152
	s_nop 0
	v_ashrrev_i32_e32 v169, 31, v168
	v_lshlrev_b64 v[170:171], 10, v[168:169]
	v_or_b32_e32 v170, v170, v160
	v_lshl_add_u64 v[168:169], v[170:171], 2, s[0:1]
	global_store_dword v[168:169], v116, off
	v_cvt_pk_bf16_f32 v116, v116, s0
	v_lshl_add_u64 v[170:171], v[170:171], 1, s[30:31]
	s_nop 0
	global_store_short v[114:115], v153, off
	global_store_short v[170:171], v116, off
	v_cvt_pk_bf16_f32 v153, v117, s0
	s_nop 0
	v_or_b32_e32 v172, 9, v152
	v_ashrrev_i32_e32 v173, 31, v172
	v_lshlrev_b64 v[174:175], 10, v[172:173]
	v_or_b32_e32 v174, v174, v160
	v_lshl_add_u64 v[172:173], v[174:175], 2, s[0:1]
	global_store_dword v[172:173], v117, off
	v_lshl_add_u64 v[116:117], v[174:175], 1, s[30:31]
	v_or_b32_e32 v174, 10, v152
	s_nop 0
	v_ashrrev_i32_e32 v175, 31, v174
	v_or_b32_e32 v178, 11, v152
	v_lshlrev_b64 v[174:175], 10, v[174:175]
	v_ashrrev_i32_e32 v179, 31, v178
	v_or_b32_e32 v174, v174, v160
	v_lshlrev_b64 v[178:179], 10, v[178:179]
	v_lshl_add_u64 v[176:177], v[174:175], 2, s[0:1]
	v_or_b32_e32 v178, v178, v160
	s_nop 0
	global_store_dword v[176:177], v118, off
	v_cvt_pk_bf16_f32 v118, v118, s0
	v_lshl_add_u64 v[174:175], v[174:175], 1, s[30:31]
	v_lshl_add_u64 v[180:181], v[178:179], 2, s[0:1]
	global_store_short v[116:117], v153, off
	global_store_short v[174:175], v118, off
	global_store_dword v[180:181], v119, off
	v_cvt_pk_bf16_f32 v153, v119, s0
	v_lshl_add_u64 v[118:119], v[178:179], 1, s[30:31]
	v_or_b32_e32 v178, 16, v152
	s_nop 0
	v_ashrrev_i32_e32 v179, 31, v178
	v_or_b32_e32 v184, 17, v152
	v_lshlrev_b64 v[178:179], 10, v[178:179]
	v_ashrrev_i32_e32 v185, 31, v184
	v_or_b32_e32 v178, v178, v160
	v_lshlrev_b64 v[184:185], 10, v[184:185]
	v_lshl_add_u64 v[182:183], v[178:179], 2, s[0:1]
	v_or_b32_e32 v184, v184, v160
	s_nop 0
	global_store_dword v[182:183], v120, off
	v_cvt_pk_bf16_f32 v120, v120, s0
	v_lshl_add_u64 v[178:179], v[178:179], 1, s[30:31]
	v_lshl_add_u64 v[186:187], v[184:185], 2, s[0:1]
	global_store_short v[118:119], v153, off
	global_store_short v[178:179], v120, off
	global_store_dword v[186:187], v121, off
	v_cvt_pk_bf16_f32 v153, v121, s0
	v_lshl_add_u64 v[120:121], v[184:185], 1, s[30:31]
	v_or_b32_e32 v184, 18, v152
	v_ashrrev_i32_e32 v185, 31, v184
	v_or_b32_e32 v190, 19, v152
	v_lshlrev_b64 v[184:185], 10, v[184:185]
	v_ashrrev_i32_e32 v191, 31, v190
	s_nop 0
	v_or_b32_e32 v184, v184, v160
	v_lshlrev_b64 v[190:191], 10, v[190:191]
	v_lshl_add_u64 v[188:189], v[184:185], 2, s[0:1]
	v_or_b32_e32 v190, v190, v160
	global_store_dword v[188:189], v122, off
	v_cvt_pk_bf16_f32 v122, v122, s0
	v_lshl_add_u64 v[184:185], v[184:185], 1, s[30:31]
	v_lshl_add_u64 v[192:193], v[190:191], 2, s[0:1]
	global_store_short v[120:121], v153, off
	global_store_short v[184:185], v122, off
	global_store_dword v[192:193], v123, off
	v_cvt_pk_bf16_f32 v153, v123, s0
	v_lshl_add_u64 v[122:123], v[190:191], 1, s[30:31]
	v_or_b32_e32 v190, 24, v152
	s_nop 0
	v_ashrrev_i32_e32 v191, 31, v190
	v_or_b32_e32 v198, 25, v152
	v_lshlrev_b64 v[190:191], 10, v[190:191]
	v_ashrrev_i32_e32 v199, 31, v198
	v_or_b32_e32 v190, v190, v160
	v_lshlrev_b64 v[198:199], 10, v[198:199]
	v_lshl_add_u64 v[194:195], v[190:191], 2, s[0:1]
	v_or_b32_e32 v198, v198, v160
	global_store_dword v[194:195], v124, off
; DI bfr f2bf(float a) { return (bfr)(pack2(a, 0.f) & 0xffffu); }
; DI int crow(int reg, int h) { return (reg & 3) + 8 * (reg >> 2) + 4 * h; }
; template <int lda, class Epi>
; DI void gemm_tile(const bfr* __restrict__ A, const bfr* __restrict__ Bt, int NB, int K, int m0, int n0, char* smem, Epi epi) {
;     ...
;   int tid3 = threadIdx.x;
;   asm volatile("" : "+v"(tid3));
;   const int lane = tid3 & 63, wid = tid3 >> 6, wr = wid >> 1, wc = wid & 1, r = lane & 31, hl = lane >> 5;
; #pragma unroll
;   for (int i = 0; i < 2; ++i)
; #pragma unroll
;     for (int j = 0; j < 4; ++j)
; #pragma unroll
;       for (int q = 0; q < 16; ++q) {
;         int row = m0 + wr * 64 + i * 32 + crow(q, hl);
;         int col = n0 + wc * 128 + j * 32 + r;
;         epi(row, col, acc[i][j][q]);
;       }
; DI void phase_gemm_in_even(const Params& p, char* smem) {
;     ...
;                   [=](int row, int col, float v) {
;                     o[(size_t)row * 1024 + col] = v;
;                     kb[(size_t)row * 1024 + col] = f2bf(v);
;                   });
	v_cvt_pk_bf16_f32 v124, v124, s0
	v_lshl_add_u64 v[190:191], v[190:191], 1, s[30:31]
	v_lshl_add_u64 v[200:201], v[198:199], 2, s[0:1]
	s_nop 0
	global_store_short v[122:123], v153, off
	global_store_short v[190:191], v124, off
	global_store_dword v[200:201], v125, off
	v_cvt_pk_bf16_f32 v153, v125, s0
	v_lshl_add_u64 v[124:125], v[198:199], 1, s[30:31]
	v_or_b32_e32 v198, 26, v152
	v_ashrrev_i32_e32 v199, 31, v198
	v_or_b32_e32 v204, 27, v152
	v_lshlrev_b64 v[198:199], 10, v[198:199]
	v_ashrrev_i32_e32 v205, 31, v204
	v_or_b32_e32 v198, v198, v160
	v_lshlrev_b64 v[204:205], 10, v[204:205]
	v_lshl_add_u64 v[202:203], v[198:199], 2, s[0:1]
	v_or_b32_e32 v204, v204, v160
	s_nop 0
	global_store_dword v[202:203], v126, off
	v_cvt_pk_bf16_f32 v126, v126, s0
	v_lshl_add_u64 v[198:199], v[198:199], 1, s[30:31]
	global_store_short v[124:125], v153, off
	global_store_short v[198:199], v126, off
	v_cvt_pk_bf16_f32 v153, v127, s0
	s_nop 0
	v_lshl_add_u64 v[206:207], v[204:205], 2, s[0:1]
	global_store_dword v[206:207], v127, off
	v_lshl_add_u64 v[126:127], v[204:205], 1, s[30:31]
	global_store_short v[126:127], v153, off
	global_store_dword v[154:155], v96, off offset:128
	v_cvt_pk_bf16_f32 v96, v96, s0
	global_store_short v[156:157], v96, off offset:64
	global_store_dword v[158:159], v97, off offset:128
	v_cvt_pk_bf16_f32 v96, v97, s0
	global_store_short v[112:113], v96, off offset:64
	v_cvt_pk_bf16_f32 v96, v98, s0
	global_store_dword v[162:163], v98, off offset:128
	global_store_short v[164:165], v96, off offset:64
	global_store_dword v[166:167], v99, off offset:128
	v_cvt_pk_bf16_f32 v96, v99, s0
	global_store_short v[114:115], v96, off offset:64
	global_store_dword v[168:169], v100, off offset:128
	v_cvt_pk_bf16_f32 v96, v100, s0
	global_store_short v[170:171], v96, off offset:64
	global_store_dword v[172:173], v101, off offset:128
	v_cvt_pk_bf16_f32 v96, v101, s0
	global_store_short v[116:117], v96, off offset:64
	global_store_dword v[176:177], v102, off offset:128
	v_cvt_pk_bf16_f32 v96, v102, s0
	global_store_short v[174:175], v96, off offset:64
	global_store_dword v[180:181], v103, off offset:128
	v_cvt_pk_bf16_f32 v96, v103, s0
	s_nop 0
	global_store_short v[118:119], v96, off offset:64
	global_store_dword v[182:183], v104, off offset:128
	v_cvt_pk_bf16_f32 v96, v104, s0
	global_store_short v[178:179], v96, off offset:64
	v_cvt_pk_bf16_f32 v96, v105, s0
	global_store_dword v[186:187], v105, off offset:128
	global_store_short v[120:121], v96, off offset:64
	global_store_dword v[188:189], v106, off offset:128
	v_cvt_pk_bf16_f32 v96, v106, s0
	global_store_short v[184:185], v96, off offset:64
	global_store_dword v[192:193], v107, off offset:128
	v_cvt_pk_bf16_f32 v96, v107, s0
	global_store_short v[122:123], v96, off offset:64
	global_store_dword v[194:195], v108, off offset:128
	v_cvt_pk_bf16_f32 v96, v108, s0
	global_store_short v[190:191], v96, off offset:64
	global_store_dword v[200:201], v109, off offset:128
	v_cvt_pk_bf16_f32 v96, v109, s0
	global_store_short v[124:125], v96, off offset:64
	global_store_dword v[202:203], v110, off offset:128
	v_cvt_pk_bf16_f32 v96, v110, s0
	global_store_short v[198:199], v96, off offset:64
	global_store_dword v[206:207], v111, off offset:128
	v_cvt_pk_bf16_f32 v96, v111, s0
	global_store_short v[126:127], v96, off offset:64
	global_store_dword v[154:155], v80, off offset:256
	v_cvt_pk_bf16_f32 v80, v80, s0
	global_store_short v[156:157], v80, off offset:128
	global_store_dword v[158:159], v81, off offset:256
	v_cvt_pk_bf16_f32 v80, v81, s0
	global_store_short v[112:113], v80, off offset:128
	global_store_dword v[162:163], v82, off offset:256
	v_cvt_pk_bf16_f32 v80, v82, s0
	global_store_short v[164:165], v80, off offset:128
	global_store_dword v[166:167], v83, off offset:256
	v_cvt_pk_bf16_f32 v80, v83, s0
	global_store_short v[114:115], v80, off offset:128
	global_store_dword v[168:169], v84, off offset:256
	v_cvt_pk_bf16_f32 v80, v84, s0
	global_store_short v[170:171], v80, off offset:128
	global_store_dword v[172:173], v85, off offset:256
	v_cvt_pk_bf16_f32 v80, v85, s0
	global_store_short v[116:117], v80, off offset:128
	global_store_dword v[176:177], v86, off offset:256
	v_cvt_pk_bf16_f32 v80, v86, s0
	global_store_short v[174:175], v80, off offset:128
	global_store_dword v[180:181], v87, off offset:256
	v_cvt_pk_bf16_f32 v80, v87, s0
	s_nop 0
	global_store_short v[118:119], v80, off offset:128
	global_store_dword v[182:183], v88, off offset:256
	v_cvt_pk_bf16_f32 v80, v88, s0
	global_store_short v[178:179], v80, off offset:128
	global_store_dword v[186:187], v89, off offset:256
	v_cvt_pk_bf16_f32 v80, v89, s0
	global_store_short v[120:121], v80, off offset:128
	global_store_dword v[188:189], v90, off offset:256
	v_cvt_pk_bf16_f32 v80, v90, s0
	global_store_short v[184:185], v80, off offset:128
	global_store_dword v[192:193], v91, off offset:256
	v_cvt_pk_bf16_f32 v80, v91, s0
	global_store_short v[122:123], v80, off offset:128
	global_store_dword v[194:195], v92, off offset:256
	v_cvt_pk_bf16_f32 v80, v92, s0
	global_store_short v[190:191], v80, off offset:128
	global_store_dword v[200:201], v93, off offset:256
	v_cvt_pk_bf16_f32 v80, v93, s0
	global_store_short v[124:125], v80, off offset:128
	global_store_dword v[202:203], v94, off offset:256
	v_cvt_pk_bf16_f32 v80, v94, s0
	global_store_short v[198:199], v80, off offset:128
	global_store_dword v[206:207], v95, off offset:256
	v_cvt_pk_bf16_f32 v80, v95, s0
	global_store_short v[126:127], v80, off offset:128
	global_store_dword v[154:155], v64, off offset:384
	v_cvt_pk_bf16_f32 v64, v64, s0
	global_store_short v[156:157], v64, off offset:192
; DI bfr f2bf(float a) { return (bfr)(pack2(a, 0.f) & 0xffffu); }
; DI int crow(int reg, int h) { return (reg & 3) + 8 * (reg >> 2) + 4 * h; }
; template <int lda, class Epi>
; DI void gemm_tile(const bfr* __restrict__ A, const bfr* __restrict__ Bt, int NB, int K, int m0, int n0, char* smem, Epi epi) {
;     ...
;   int tid3 = threadIdx.x;
;   asm volatile("" : "+v"(tid3));
;   const int lane = tid3 & 63, wid = tid3 >> 6, wr = wid >> 1, wc = wid & 1, r = lane & 31, hl = lane >> 5;
; #pragma unroll
;   for (int i = 0; i < 2; ++i)
; #pragma unroll
;     for (int j = 0; j < 4; ++j)
; #pragma unroll
;       for (int q = 0; q < 16; ++q) {
;         int row = m0 + wr * 64 + i * 32 + crow(q, hl);
;         int col = n0 + wc * 128 + j * 32 + r;
;         epi(row, col, acc[i][j][q]);
;       }
; DI void phase_gemm_in_even(const Params& p, char* smem) {
;     ...
;                   [=](int row, int col, float v) {
;                     o[(size_t)row * 1024 + col] = v;
;                     kb[(size_t)row * 1024 + col] = f2bf(v);
;                   });
	global_store_dword v[158:159], v65, off offset:384
	v_cvt_pk_bf16_f32 v64, v65, s0
	global_store_short v[112:113], v64, off offset:192
	global_store_dword v[162:163], v66, off offset:384
	v_cvt_pk_bf16_f32 v64, v66, s0
	global_store_short v[164:165], v64, off offset:192
	global_store_dword v[166:167], v67, off offset:384
	v_cvt_pk_bf16_f32 v64, v67, s0
	global_store_short v[114:115], v64, off offset:192
	global_store_dword v[168:169], v68, off offset:384
	v_cvt_pk_bf16_f32 v64, v68, s0
	s_nop 0
	global_store_short v[170:171], v64, off offset:192
	global_store_dword v[172:173], v69, off offset:384
	v_cvt_pk_bf16_f32 v64, v69, s0
	global_store_short v[116:117], v64, off offset:192
	global_store_dword v[176:177], v70, off offset:384
	v_cvt_pk_bf16_f32 v64, v70, s0
	global_store_short v[174:175], v64, off offset:192
	global_store_dword v[180:181], v71, off offset:384
	v_cvt_pk_bf16_f32 v64, v71, s0
	global_store_short v[118:119], v64, off offset:192
	global_store_dword v[182:183], v72, off offset:384
	v_cvt_pk_bf16_f32 v64, v72, s0
	global_store_short v[178:179], v64, off offset:192
	global_store_dword v[186:187], v73, off offset:384
	v_cvt_pk_bf16_f32 v64, v73, s0
	global_store_short v[120:121], v64, off offset:192
	global_store_dword v[188:189], v74, off offset:384
	v_cvt_pk_bf16_f32 v64, v74, s0
	global_store_short v[184:185], v64, off offset:192
	global_store_dword v[192:193], v75, off offset:384
	v_cvt_pk_bf16_f32 v64, v75, s0
	global_store_short v[122:123], v64, off offset:192
	global_store_dword v[194:195], v76, off offset:384
	v_cvt_pk_bf16_f32 v64, v76, s0
	s_nop 0
	global_store_short v[190:191], v64, off offset:192
	global_store_dword v[200:201], v77, off offset:384
	v_cvt_pk_bf16_f32 v64, v77, s0
	global_store_short v[124:125], v64, off offset:192
	global_store_dword v[202:203], v78, off offset:384
	v_cvt_pk_bf16_f32 v64, v78, s0
	global_store_short v[198:199], v64, off offset:192
	global_store_dword v[206:207], v79, off offset:384
	v_cvt_pk_bf16_f32 v64, v79, s0
	global_store_short v[126:127], v64, off offset:192
	v_or_b32_e32 v64, 32, v152
	v_ashrrev_i32_e32 v65, 31, v64
	v_or_b32_e32 v68, 33, v152
	v_lshlrev_b64 v[66:67], 10, v[64:65]
	v_ashrrev_i32_e32 v69, 31, v68
	v_or_b32_e32 v66, v66, v160
	v_lshlrev_b64 v[70:71], 10, v[68:69]
	v_lshl_add_u64 v[64:65], v[66:67], 2, s[0:1]
	v_or_b32_e32 v70, v70, v160
	global_store_dword v[64:65], v48, off
	v_cvt_pk_bf16_f32 v48, v48, s0
	v_lshl_add_u64 v[66:67], v[66:67], 1, s[30:31]
	v_lshl_add_u64 v[68:69], v[70:71], 2, s[0:1]
	global_store_short v[66:67], v48, off
	global_store_dword v[68:69], v49, off
	v_cvt_pk_bf16_f32 v72, v49, s0
	v_lshl_add_u64 v[48:49], v[70:71], 1, s[30:31]
	v_or_b32_e32 v70, 34, v152
	v_ashrrev_i32_e32 v71, 31, v70
	v_or_b32_e32 v74, 35, v152
	global_store_short v[48:49], v72, off
	v_lshlrev_b64 v[72:73], 10, v[70:71]
	v_ashrrev_i32_e32 v75, 31, v74
	v_or_b32_e32 v72, v72, v160
	v_lshlrev_b64 v[76:77], 10, v[74:75]
	v_lshl_add_u64 v[70:71], v[72:73], 2, s[0:1]
	v_or_b32_e32 v76, v76, v160
	global_store_dword v[70:71], v50, off
	v_cvt_pk_bf16_f32 v50, v50, s0
	v_lshl_add_u64 v[72:73], v[72:73], 1, s[30:31]
	v_lshl_add_u64 v[74:75], v[76:77], 2, s[0:1]
	global_store_short v[72:73], v50, off
	global_store_dword v[74:75], v51, off
	v_cvt_pk_bf16_f32 v78, v51, s0
	v_lshl_add_u64 v[50:51], v[76:77], 1, s[30:31]
	v_or_b32_e32 v76, 40, v152
	v_ashrrev_i32_e32 v77, 31, v76
	v_or_b32_e32 v80, 41, v152
	global_store_short v[50:51], v78, off
	v_lshlrev_b64 v[78:79], 10, v[76:77]
	v_ashrrev_i32_e32 v81, 31, v80
	v_or_b32_e32 v78, v78, v160
	v_lshlrev_b64 v[80:81], 10, v[80:81]
	v_lshl_add_u64 v[76:77], v[78:79], 2, s[0:1]
	v_or_b32_e32 v80, v80, v160
	global_store_dword v[76:77], v52, off
	v_cvt_pk_bf16_f32 v52, v52, s0
	v_lshl_add_u64 v[78:79], v[78:79], 1, s[30:31]
	v_lshl_add_u64 v[82:83], v[80:81], 2, s[0:1]
	global_store_short v[78:79], v52, off
	global_store_dword v[82:83], v53, off
	v_cvt_pk_bf16_f32 v84, v53, s0
	v_lshl_add_u64 v[52:53], v[80:81], 1, s[30:31]
	v_or_b32_e32 v80, 42, v152
	v_ashrrev_i32_e32 v81, 31, v80
	v_or_b32_e32 v86, 43, v152
	v_lshlrev_b64 v[80:81], 10, v[80:81]
	v_ashrrev_i32_e32 v87, 31, v86
	v_or_b32_e32 v80, v80, v160
	v_lshlrev_b64 v[86:87], 10, v[86:87]
	global_store_short v[52:53], v84, off
	v_lshl_add_u64 v[84:85], v[80:81], 2, s[0:1]
	v_or_b32_e32 v86, v86, v160
	global_store_dword v[84:85], v54, off
	v_cvt_pk_bf16_f32 v54, v54, s0
	v_lshl_add_u64 v[80:81], v[80:81], 1, s[30:31]
	v_lshl_add_u64 v[88:89], v[86:87], 2, s[0:1]
	global_store_short v[80:81], v54, off
	global_store_dword v[88:89], v55, off
	v_cvt_pk_bf16_f32 v90, v55, s0
	v_lshl_add_u64 v[54:55], v[86:87], 1, s[30:31]
	v_or_b32_e32 v86, 48, v152
	v_ashrrev_i32_e32 v87, 31, v86
	v_or_b32_e32 v92, 49, v152
	v_lshlrev_b64 v[86:87], 10, v[86:87]
	v_ashrrev_i32_e32 v93, 31, v92
	v_or_b32_e32 v86, v86, v160
	v_lshlrev_b64 v[92:93], 10, v[92:93]
	global_store_short v[54:55], v90, off
	v_lshl_add_u64 v[90:91], v[86:87], 2, s[0:1]
	v_or_b32_e32 v92, v92, v160
	global_store_dword v[90:91], v56, off
	v_cvt_pk_bf16_f32 v56, v56, s0
	v_lshl_add_u64 v[86:87], v[86:87], 1, s[30:31]
	v_lshl_add_u64 v[94:95], v[92:93], 2, s[0:1]
	global_store_short v[86:87], v56, off
	global_store_dword v[94:95], v57, off
	v_cvt_pk_bf16_f32 v96, v57, s0
	v_lshl_add_u64 v[56:57], v[92:93], 1, s[30:31]
	v_or_b32_e32 v92, 50, v152
	v_ashrrev_i32_e32 v93, 31, v92
	v_or_b32_e32 v98, 51, v152
	v_lshlrev_b64 v[92:93], 10, v[92:93]
	v_ashrrev_i32_e32 v99, 31, v98
	s_nop 0
	v_or_b32_e32 v92, v92, v160
	v_lshlrev_b64 v[98:99], 10, v[98:99]
	global_store_short v[56:57], v96, off
	v_lshl_add_u64 v[96:97], v[92:93], 2, s[0:1]
; DI bfr f2bf(float a) { return (bfr)(pack2(a, 0.f) & 0xffffu); }
; DI int crow(int reg, int h) { return (reg & 3) + 8 * (reg >> 2) + 4 * h; }
; template <int lda, class Epi>
; DI void gemm_tile(const bfr* __restrict__ A, const bfr* __restrict__ Bt, int NB, int K, int m0, int n0, char* smem, Epi epi) {
;     ...
;   int tid3 = threadIdx.x;
;   asm volatile("" : "+v"(tid3));
;   const int lane = tid3 & 63, wid = tid3 >> 6, wr = wid >> 1, wc = wid & 1, r = lane & 31, hl = lane >> 5;
; #pragma unroll
;   for (int i = 0; i < 2; ++i)
; #pragma unroll
;     for (int j = 0; j < 4; ++j)
; #pragma unroll
;       for (int q = 0; q < 16; ++q) {
;         int row = m0 + wr * 64 + i * 32 + crow(q, hl);
;         int col = n0 + wc * 128 + j * 32 + r;
;         epi(row, col, acc[i][j][q]);
;       }
; DI void phase_gemm_in_even(const Params& p, char* smem) {
;     ...
;                   [=](int row, int col, float v) {
;                     o[(size_t)row * 1024 + col] = v;
;                     kb[(size_t)row * 1024 + col] = f2bf(v);
;                   });
	v_or_b32_e32 v98, v98, v160
	global_store_dword v[96:97], v58, off
	v_cvt_pk_bf16_f32 v58, v58, s0
	v_lshl_add_u64 v[92:93], v[92:93], 1, s[30:31]
	v_lshl_add_u64 v[100:101], v[98:99], 2, s[0:1]
	global_store_short v[92:93], v58, off
	global_store_dword v[100:101], v59, off
	v_cvt_pk_bf16_f32 v102, v59, s0
	v_lshl_add_u64 v[58:59], v[98:99], 1, s[30:31]
	v_or_b32_e32 v98, 56, v152
	v_ashrrev_i32_e32 v99, 31, v98
	v_or_b32_e32 v104, 57, v152
	v_lshlrev_b64 v[98:99], 10, v[98:99]
	v_ashrrev_i32_e32 v105, 31, v104
	v_or_b32_e32 v98, v98, v160
	v_lshlrev_b64 v[104:105], 10, v[104:105]
	global_store_short v[58:59], v102, off
	v_lshl_add_u64 v[102:103], v[98:99], 2, s[0:1]
	v_or_b32_e32 v104, v104, v160
	s_nop 0
	global_store_dword v[102:103], v60, off
	v_cvt_pk_bf16_f32 v60, v60, s0
	v_lshl_add_u64 v[98:99], v[98:99], 1, s[30:31]
	v_lshl_add_u64 v[106:107], v[104:105], 2, s[0:1]
	global_store_short v[98:99], v60, off
	global_store_dword v[106:107], v61, off
	v_cvt_pk_bf16_f32 v108, v61, s0
	v_lshl_add_u64 v[60:61], v[104:105], 1, s[30:31]
	v_or_b32_e32 v104, 58, v152
	v_ashrrev_i32_e32 v105, 31, v104
	v_or_b32_e32 v110, 59, v152
	v_lshlrev_b64 v[104:105], 10, v[104:105]
	v_ashrrev_i32_e32 v111, 31, v110
	v_or_b32_e32 v104, v104, v160
	v_lshlrev_b64 v[110:111], 10, v[110:111]
	global_store_short v[60:61], v108, off
	v_lshl_add_u64 v[108:109], v[104:105], 2, s[0:1]
	v_or_b32_e32 v110, v110, v160
	global_store_dword v[108:109], v62, off
	v_cvt_pk_bf16_f32 v62, v62, s0
	v_lshl_add_u64 v[104:105], v[104:105], 1, s[30:31]
	v_lshl_add_u64 v[112:113], v[110:111], 2, s[0:1]
	global_store_short v[104:105], v62, off
	global_store_dword v[112:113], v63, off
	v_cvt_pk_bf16_f32 v114, v63, s0
	v_lshl_add_u64 v[62:63], v[110:111], 1, s[30:31]
	s_nop 0
	global_store_short v[62:63], v114, off
	global_store_dword v[64:65], v32, off offset:128
	v_cvt_pk_bf16_f32 v32, v32, s0
	global_store_short v[66:67], v32, off offset:64
	global_store_dword v[68:69], v33, off offset:128
	v_cvt_pk_bf16_f32 v32, v33, s0
	global_store_short v[48:49], v32, off offset:64
	global_store_dword v[70:71], v34, off offset:128
	v_cvt_pk_bf16_f32 v32, v34, s0
	global_store_short v[72:73], v32, off offset:64
	global_store_dword v[74:75], v35, off offset:128
	v_cvt_pk_bf16_f32 v32, v35, s0
	global_store_short v[50:51], v32, off offset:64
	global_store_dword v[76:77], v36, off offset:128
	v_cvt_pk_bf16_f32 v32, v36, s0
	global_store_short v[78:79], v32, off offset:64
	global_store_dword v[82:83], v37, off offset:128
	v_cvt_pk_bf16_f32 v32, v37, s0
	global_store_short v[52:53], v32, off offset:64
	global_store_dword v[84:85], v38, off offset:128
	v_cvt_pk_bf16_f32 v32, v38, s0
	global_store_short v[80:81], v32, off offset:64
	global_store_dword v[88:89], v39, off offset:128
	v_cvt_pk_bf16_f32 v32, v39, s0
	s_nop 0
	global_store_short v[54:55], v32, off offset:64
	global_store_dword v[90:91], v40, off offset:128
	v_cvt_pk_bf16_f32 v32, v40, s0
	global_store_short v[86:87], v32, off offset:64
	global_store_dword v[94:95], v41, off offset:128
	v_cvt_pk_bf16_f32 v32, v41, s0
	global_store_short v[56:57], v32, off offset:64
	global_store_dword v[96:97], v42, off offset:128
	v_cvt_pk_bf16_f32 v32, v42, s0
	global_store_short v[92:93], v32, off offset:64
	global_store_dword v[100:101], v43, off offset:128
	v_cvt_pk_bf16_f32 v32, v43, s0
	global_store_short v[58:59], v32, off offset:64
	global_store_dword v[102:103], v44, off offset:128
	v_cvt_pk_bf16_f32 v32, v44, s0
	global_store_short v[98:99], v32, off offset:64
	global_store_dword v[106:107], v45, off offset:128
	v_cvt_pk_bf16_f32 v32, v45, s0
	global_store_short v[60:61], v32, off offset:64
	global_store_dword v[108:109], v46, off offset:128
	v_cvt_pk_bf16_f32 v32, v46, s0
	global_store_short v[104:105], v32, off offset:64
	global_store_dword v[112:113], v47, off offset:128
	v_cvt_pk_bf16_f32 v32, v47, s0
	s_nop 0
	global_store_short v[62:63], v32, off offset:64
	global_store_dword v[64:65], v16, off offset:256
	v_cvt_pk_bf16_f32 v16, v16, s0
	global_store_short v[66:67], v16, off offset:128
	global_store_dword v[68:69], v17, off offset:256
; DI bfr f2bf(float a) { return (bfr)(pack2(a, 0.f) & 0xffffu); }
; DI int crow(int reg, int h) { return (reg & 3) + 8 * (reg >> 2) + 4 * h; }
; template <int lda, class Epi>
; DI void gemm_tile(const bfr* __restrict__ A, const bfr* __restrict__ Bt, int NB, int K, int m0, int n0, char* smem, Epi epi) {
;     ...
;   int tid3 = threadIdx.x;
;   asm volatile("" : "+v"(tid3));
;   const int lane = tid3 & 63, wid = tid3 >> 6, wr = wid >> 1, wc = wid & 1, r = lane & 31, hl = lane >> 5;
; #pragma unroll
;   for (int i = 0; i < 2; ++i)
; #pragma unroll
;     for (int j = 0; j < 4; ++j)
; #pragma unroll
;       for (int q = 0; q < 16; ++q) {
;         int row = m0 + wr * 64 + i * 32 + crow(q, hl);
;         int col = n0 + wc * 128 + j * 32 + r;
;         epi(row, col, acc[i][j][q]);
;       }
; DI void phase_gemm_in_even(const Params& p, char* smem) {
;     ...
;                   [=](int row, int col, float v) {
;                     o[(size_t)row * 1024 + col] = v;
;                     kb[(size_t)row * 1024 + col] = f2bf(v);
;                   });
	v_cvt_pk_bf16_f32 v16, v17, s0
	global_store_short v[48:49], v16, off offset:128
	global_store_dword v[70:71], v18, off offset:256
	v_cvt_pk_bf16_f32 v16, v18, s0
	global_store_short v[72:73], v16, off offset:128
	global_store_dword v[74:75], v19, off offset:256
	v_cvt_pk_bf16_f32 v16, v19, s0
	global_store_short v[50:51], v16, off offset:128
	global_store_dword v[76:77], v20, off offset:256
	v_cvt_pk_bf16_f32 v16, v20, s0
	global_store_short v[78:79], v16, off offset:128
	global_store_dword v[82:83], v21, off offset:256
	v_cvt_pk_bf16_f32 v16, v21, s0
	global_store_short v[52:53], v16, off offset:128
	global_store_dword v[84:85], v22, off offset:256
	v_cvt_pk_bf16_f32 v16, v22, s0
	global_store_short v[80:81], v16, off offset:128
	global_store_dword v[88:89], v23, off offset:256
	v_cvt_pk_bf16_f32 v16, v23, s0
	s_nop 0
	global_store_short v[54:55], v16, off offset:128
	global_store_dword v[90:91], v24, off offset:256
	v_cvt_pk_bf16_f32 v16, v24, s0
	global_store_short v[86:87], v16, off offset:128
	global_store_dword v[94:95], v25, off offset:256
	v_cvt_pk_bf16_f32 v16, v25, s0
	global_store_short v[56:57], v16, off offset:128
	global_store_dword v[96:97], v26, off offset:256
	v_cvt_pk_bf16_f32 v16, v26, s0
	global_store_short v[92:93], v16, off offset:128
	global_store_dword v[100:101], v27, off offset:256
	v_cvt_pk_bf16_f32 v16, v27, s0
	global_store_short v[58:59], v16, off offset:128
	global_store_dword v[102:103], v28, off offset:256
	v_cvt_pk_bf16_f32 v16, v28, s0
	global_store_short v[98:99], v16, off offset:128
	global_store_dword v[106:107], v29, off offset:256
	v_cvt_pk_bf16_f32 v16, v29, s0
	global_store_short v[60:61], v16, off offset:128
	global_store_dword v[108:109], v30, off offset:256
	v_cvt_pk_bf16_f32 v16, v30, s0
	global_store_short v[104:105], v16, off offset:128
	global_store_dword v[112:113], v31, off offset:256
	v_cvt_pk_bf16_f32 v16, v31, s0
	global_store_short v[62:63], v16, off offset:128
	global_store_dword v[64:65], v0, off offset:384
	v_cvt_pk_bf16_f32 v0, v0, s0
	global_store_short v[66:67], v0, off offset:192
	global_store_dword v[68:69], v1, off offset:384
	v_cvt_pk_bf16_f32 v0, v1, s0
	global_store_short v[48:49], v0, off offset:192
	global_store_dword v[70:71], v2, off offset:384
	v_cvt_pk_bf16_f32 v0, v2, s0
	global_store_short v[72:73], v0, off offset:192
	global_store_dword v[74:75], v3, off offset:384
	v_cvt_pk_bf16_f32 v0, v3, s0
	global_store_short v[50:51], v0, off offset:192
	global_store_dword v[76:77], v4, off offset:384
	v_cvt_pk_bf16_f32 v0, v4, s0
	global_store_short v[78:79], v0, off offset:192
	global_store_dword v[82:83], v5, off offset:384
	v_cvt_pk_bf16_f32 v0, v5, s0
	global_store_short v[52:53], v0, off offset:192
	global_store_dword v[84:85], v6, off offset:384
	v_cvt_pk_bf16_f32 v0, v6, s0
	global_store_short v[80:81], v0, off offset:192
	global_store_dword v[88:89], v7, off offset:384
	v_cvt_pk_bf16_f32 v0, v7, s0
	global_store_short v[54:55], v0, off offset:192
	global_store_dword v[90:91], v8, off offset:384
	v_cvt_pk_bf16_f32 v0, v8, s0
	global_store_short v[86:87], v0, off offset:192
	global_store_dword v[94:95], v9, off offset:384
	v_cvt_pk_bf16_f32 v0, v9, s0
	global_store_short v[56:57], v0, off offset:192
	global_store_dword v[96:97], v10, off offset:384
	v_cvt_pk_bf16_f32 v0, v10, s0
	global_store_short v[92:93], v0, off offset:192
	global_store_dword v[100:101], v11, off offset:384
	v_cvt_pk_bf16_f32 v0, v11, s0
	global_store_short v[58:59], v0, off offset:192
	global_store_dword v[102:103], v12, off offset:384
	v_cvt_pk_bf16_f32 v0, v12, s0
	global_store_short v[98:99], v0, off offset:192
	global_store_dword v[106:107], v13, off offset:384
	v_cvt_pk_bf16_f32 v0, v13, s0
	global_store_short v[60:61], v0, off offset:192
	global_store_dword v[108:109], v14, off offset:384
	v_cvt_pk_bf16_f32 v0, v14, s0
	global_store_short v[104:105], v0, off offset:192
	global_store_dword v[112:113], v15, off offset:384
	v_cvt_pk_bf16_f32 v0, v15, s0
	global_store_short v[62:63], v0, off offset:192
	s_mov_b64 s[0:1], 0
	s_branch .LBB0_151

; #define GA_LOAD(pr_) do { _Pragma("unroll") for (int i = 0; i < 4; ++i) ra[i] = *(const u32x4*)(Ab + (i * 32) * lda + (pr_) * 64); } while (0)
; #define GB_LOAD(kt_) do { const bfr* bk_ = Bb + (kt_) * NB * 32; \
;     _Pragma("unroll") for (int i = 0; i < 4; ++i) rb[i] = *(const u32x4*)(bk_ + (i * 64) * 32); } while (0)
; #define G_STORE(kt_) do { bfr* as_ = S0 + ((kt_) & 1) * GSTAGE; bfr* bs_ = as_ + 128 * 40; \
;     if (apar == ((kt_) & 1)) { _Pragma("unroll") for (int i = 0; i < 4; ++i) *(u32x4*)(as_ + asoff + i * 32 * 40) = ra[i]; } \
;     _Pragma("unroll") for (int i = 0; i < 4; ++i) *(u32x4*)(bs_ + bsoff + i * 64 * 40) = rb[i]; } while (0)
; template <int lda>
; DI void gemm_mainloop(const bfr* __restrict__ A, const bfr* __restrict__ Bt, int NB, int K, int m0, int n0, char* smem, f32x16 (&acc)[2][4]) {
;   bfr* S0 = (bfr*)smem;
;   int tid = threadIdx.x;
;   asm volatile("" : "+v"(tid));
;   const int lane = tid & 63, wid = tid >> 6, wr = wid >> 1, wc = wid & 1;
;   const int r = lane & 31, hl = lane >> 5;
; #pragma unroll
;   for (int i = 0; i < 2; ++i)
; #pragma unroll
;     for (int j = 0; j < 4; ++j)
; #pragma unroll
;       for (int q = 0; q < 16; ++q) acc[i][j][q] = 0.f;
;   u32x4 ra[4], rb[4];
;   const int nk = K >> 5;
;   const int arow = tid >> 3, ac8 = tid & 7, apar = ac8 >> 2;
;   const bfr* Ab = A + (m0 + arow) * lda + ac8 * 8;
;   const int asoff = arow * 40 + (ac8 & 3) * 8;
;   const int brow = tid >> 2, bc4 = tid & 3;
;   const bfr* Bb = Bt + (n0 + brow) * 32 + bc4 * 8;
;   const int bsoff = brow * 40 + bc4 * 8;
;     ...
;   GA_LOAD(0);
;   GB_LOAD(0);
;   G_STORE(0);
;   GB_LOAD(1);
;   __syncthreads();
; DI void phase_gemm_in_even(const Params& p, char* smem) {
;     ...
;   for (int t0 = blockIdx.x; t0 < NT1 + NT2; t0 += gridDim.x) {
;     const int t = (t0 < NT1 && (gridDim.x & 7) == 0) ? xcd_tile(t0, 14) : t0;
;     if (t < NT1) {
;       int mt = t / 14, nt = t % 14;
;       bfr* PB = p.PB;
;       gemm_tile<1024>(p.H, p.WtInE, 3712, 1024, mt * 128, nt * 256, smem,
.LBB0_151:
	s_andn2_b64 vcc, exec, s[0:1]
	s_cbranch_vccnz .LBB0_119
	s_mul_hi_i32 s0, s56, 0x92492493
	s_add_i32 s0, s0, s56
	s_lshr_b32 s1, s0, 31
	s_ashr_i32 s0, s0, 3
	s_add_i32 s0, s0, s1
	s_mul_i32 s1, s0, 14
	s_sub_i32 s1, s56, s1
	s_lshl_b32 s56, s0, 7
	s_lshl_b32 s2, s1, 8
	s_mov_b32 s57, 0
	s_mov_b64 s[30:31], 0
	s_lshl_b32 s98, s56, 11
	s_add_u32 s98, s16, s98
	s_addc_u32 s99, s17, 0
	s_lshl_b32 s100, s2, 6
	s_add_u32 s100, s10, s100
	s_addc_u32 s101, s11, 0
	v_writelane_b32 v188, s64, 0
	v_writelane_b32 v188, s65, 1
	v_writelane_b32 v188, s66, 2
	v_writelane_b32 v188, s67, 3
	v_writelane_b32 v188, s68, 4
	v_writelane_b32 v188, s69, 5
	v_writelane_b32 v188, s70, 6
	v_writelane_b32 v188, s71, 7
	v_writelane_b32 v188, s72, 8
	v_writelane_b32 v188, s73, 9
	v_writelane_b32 v188, s74, 10
	v_writelane_b32 v188, s75, 11
	v_writelane_b32 v188, s76, 12
	v_writelane_b32 v188, s77, 13
	v_writelane_b32 v188, s78, 14
	v_writelane_b32 v188, s79, 15
	v_lshrrev_b32_e32 v189, 6, v196
	v_and_b32_e32 v190, 63, v196
	v_readfirstlane_b32 s73, v189
	v_lshrrev_b32_e32 v191, 2, v190
	v_bfe_u32 v192, v190, 4, 2
	v_and_b32_e32 v189, 3, v190
	v_xor_b32_e32 v189, v189, v192
	v_lshlrev_b32_e32 v189, 4, v189
	v_lshl_add_u32 v160, v191, 11, v189
	v_add_u32_e32 v162, 0x8000, v160
	v_lshl_add_u32 v163, v191, 6, v189
	v_and_b32_e32 v191, 31, v190
	v_lshrrev_b32_e32 v192, 5, v190
	v_bfe_u32 v189, v190, 2, 2
	v_xor_b32_e32 v189, v189, v192
	v_lshlrev_b32_e32 v189, 4, v189
	v_lshl_add_u32 v180, v191, 6, v189
	s_lshr_b32 s74, s73, 1
	s_lshl_b32 s74, s74, 12
	s_and_b32 s75, s73, 1
	s_lshl_b32 s75, s75, 13
	v_add_u32_e32 v182, s75, v180
	v_add_u32_e32 v180, s74, v180
	v_xor_b32_e32 v183, 32, v182
	v_xor_b32_e32 v181, 32, v180
	s_lshl_b32 s74, s73, 16
	s_add_u32 s64, s98, s74
	s_addc_u32 s65, s99, 0
	s_lshl_b32 s74, s73, 12
	s_add_u32 s66, s100, s74
	s_addc_u32 s67, s101, 0
	s_lshl_b32 s68, s73, 11
	s_lshl_b32 s69, s73, 12
	s_mov_b32 s70, 0
	s_mov_b32 s71, 0
	s_mov_b32 s72, 0
	s_waitcnt lgkmcnt(0)
	s_barrier
	s_mul_i32 s74, s70, 0x6000
	s_add_u32 s75, s74, s68
	s_mov_b32 m0, s75
	s_add_u32 s76, s74, 0x2000
	s_cmp_eq_u32 s70, 2
	s_cselect_b32 s76, 0x10000, s76
	global_load_lds_dwordx4 v160, s[64:65]
	s_add_u32 m0, s75, 0x400
	s_add_u32 s76, s76, s69
	global_load_lds_dwordx4 v162, s[64:65]
	s_mov_b32 m0, s76
	s_add_u32 s64, s64, 64
	s_addc_u32 s65, s65, 0
	global_load_lds_dwordx4 v163, s[66:67]
	global_load_lds_dwordx4 v163, s[66:67] offset:1024
	global_load_lds_dwordx4 v163, s[66:67] offset:2048
	global_load_lds_dwordx4 v163, s[66:67] offset:3072
	s_add_u32 s66, s66, 0x3a000
	s_addc_u32 s67, s67, 0
	s_add_u32 s70, s70, 1
	s_cmp_eq_u32 s70, 3
	s_cselect_b32 s70, 0, s70
	s_mul_i32 s74, s70, 0x6000
	s_add_u32 s75, s74, s68
	s_mov_b32 m0, s75
	s_add_u32 s76, s74, 0x2000
	s_cmp_eq_u32 s70, 2
	s_cselect_b32 s76, 0x10000, s76
	global_load_lds_dwordx4 v160, s[64:65]
	s_add_u32 m0, s75, 0x400
	s_add_u32 s76, s76, s69
	global_load_lds_dwordx4 v162, s[64:65]
	s_mov_b32 m0, s76
	s_add_u32 s64, s64, 64
	s_addc_u32 s65, s65, 0
	global_load_lds_dwordx4 v163, s[66:67]
	global_load_lds_dwordx4 v163, s[66:67] offset:1024
	global_load_lds_dwordx4 v163, s[66:67] offset:2048
	global_load_lds_dwordx4 v163, s[66:67] offset:3072
	s_add_u32 s66, s66, 0x3a000
	s_addc_u32 s67, s67, 0
	s_add_u32 s70, s70, 1
	s_cmp_eq_u32 s70, 3
	s_cselect_b32 s70, 0, s70
	v_mov_b32_e32 v112, 0
	v_mov_b32_e32 v113, 0
	v_mov_b32_e32 v114, 0
	v_mov_b32_e32 v115, 0
	v_mov_b32_e32 v116, 0
	v_mov_b32_e32 v117, 0
	v_mov_b32_e32 v118, 0
	v_mov_b32_e32 v119, 0
	v_mov_b32_e32 v120, 0
	v_mov_b32_e32 v121, 0
	v_mov_b32_e32 v122, 0
	v_mov_b32_e32 v123, 0
	v_mov_b32_e32 v124, 0
	v_mov_b32_e32 v125, 0
	v_mov_b32_e32 v126, 0
	v_mov_b32_e32 v127, 0
	v_mov_b32_e32 v96, 0
	v_mov_b32_e32 v97, 0
	v_mov_b32_e32 v98, 0
	v_mov_b32_e32 v99, 0
	v_mov_b32_e32 v100, 0
	v_mov_b32_e32 v101, 0
	v_mov_b32_e32 v102, 0
	v_mov_b32_e32 v103, 0
	v_mov_b32_e32 v104, 0
	v_mov_b32_e32 v105, 0
	v_mov_b32_e32 v106, 0
	v_mov_b32_e32 v107, 0
	v_mov_b32_e32 v108, 0
	v_mov_b32_e32 v109, 0
	v_mov_b32_e32 v110, 0
	v_mov_b32_e32 v111, 0
	v_mov_b32_e32 v80, 0
	v_mov_b32_e32 v81, 0
	v_mov_b32_e32 v82, 0
	v_mov_b32_e32 v83, 0
	v_mov_b32_e32 v84, 0
	v_mov_b32_e32 v85, 0
	v_mov_b32_e32 v86, 0
	v_mov_b32_e32 v87, 0
	v_mov_b32_e32 v88, 0
	v_mov_b32_e32 v89, 0
	v_mov_b32_e32 v90, 0
	v_mov_b32_e32 v91, 0
	v_mov_b32_e32 v92, 0
	v_mov_b32_e32 v93, 0
	v_mov_b32_e32 v94, 0
	v_mov_b32_e32 v95, 0
	v_mov_b32_e32 v64, 0
	v_mov_b32_e32 v65, 0
	v_mov_b32_e32 v66, 0
	v_mov_b32_e32 v67, 0
	v_mov_b32_e32 v68, 0
	v_mov_b32_e32 v69, 0
	v_mov_b32_e32 v70, 0
	v_mov_b32_e32 v71, 0
	v_mov_b32_e32 v72, 0
	v_mov_b32_e32 v73, 0
	v_mov_b32_e32 v74, 0
	v_mov_b32_e32 v75, 0
	v_mov_b32_e32 v76, 0
	v_mov_b32_e32 v77, 0
	v_mov_b32_e32 v78, 0
	v_mov_b32_e32 v79, 0
	v_mov_b32_e32 v48, 0
	v_mov_b32_e32 v49, 0
	v_mov_b32_e32 v50, 0
	v_mov_b32_e32 v51, 0
	v_mov_b32_e32 v52, 0
	v_mov_b32_e32 v53, 0
	v_mov_b32_e32 v54, 0
	v_mov_b32_e32 v55, 0
	v_mov_b32_e32 v56, 0
	v_mov_b32_e32 v57, 0
	v_mov_b32_e32 v58, 0
	v_mov_b32_e32 v59, 0
	v_mov_b32_e32 v60, 0
	v_mov_b32_e32 v61, 0
	v_mov_b32_e32 v62, 0
	v_mov_b32_e32 v63, 0
	v_mov_b32_e32 v32, 0
	v_mov_b32_e32 v33, 0
	v_mov_b32_e32 v34, 0
	v_mov_b32_e32 v35, 0
	v_mov_b32_e32 v36, 0
	v_mov_b32_e32 v37, 0
	v_mov_b32_e32 v38, 0
	v_mov_b32_e32 v39, 0
	v_mov_b32_e32 v40, 0
	v_mov_b32_e32 v41, 0
	v_mov_b32_e32 v42, 0
	v_mov_b32_e32 v43, 0
	v_mov_b32_e32 v44, 0
	v_mov_b32_e32 v45, 0
	v_mov_b32_e32 v46, 0
	v_mov_b32_e32 v47, 0
	v_mov_b32_e32 v16, 0
	v_mov_b32_e32 v17, 0
	v_mov_b32_e32 v18, 0
	v_mov_b32_e32 v19, 0
	v_mov_b32_e32 v20, 0
	v_mov_b32_e32 v21, 0
	v_mov_b32_e32 v22, 0
	v_mov_b32_e32 v23, 0
	v_mov_b32_e32 v24, 0
	v_mov_b32_e32 v25, 0
	v_mov_b32_e32 v26, 0
	v_mov_b32_e32 v27, 0
	v_mov_b32_e32 v28, 0
	v_mov_b32_e32 v29, 0
	v_mov_b32_e32 v30, 0
	v_mov_b32_e32 v31, 0
	v_mov_b32_e32 v0, 0
	v_mov_b32_e32 v1, 0
	v_mov_b32_e32 v2, 0
	v_mov_b32_e32 v3, 0
	v_mov_b32_e32 v4, 0
	v_mov_b32_e32 v5, 0
	v_mov_b32_e32 v6, 0
	v_mov_b32_e32 v7, 0
	v_mov_b32_e32 v8, 0
	v_mov_b32_e32 v9, 0
	v_mov_b32_e32 v10, 0
	v_mov_b32_e32 v11, 0
	v_mov_b32_e32 v12, 0
	v_mov_b32_e32 v13, 0
	v_mov_b32_e32 v14, 0
	v_mov_b32_e32 v15, 0
; #define MFMA32(a, b, c) __builtin_amdgcn_mfma_f32_32x32x16_bf16((a), (b), (c), 0, 0, 0)
; #define GA_LOAD(pr_) do { _Pragma("unroll") for (int i = 0; i < 4; ++i) ra[i] = *(const u32x4*)(Ab + (i * 32) * lda + (pr_) * 64); } while (0)
; #define GB_LOAD(kt_) do { const bfr* bk_ = Bb + (kt_) * NB * 32; \
;     _Pragma("unroll") for (int i = 0; i < 4; ++i) rb[i] = *(const u32x4*)(bk_ + (i * 64) * 32); } while (0)
; #define G_STORE(kt_) do { bfr* as_ = S0 + ((kt_) & 1) * GSTAGE; bfr* bs_ = as_ + 128 * 40; \
;     if (apar == ((kt_) & 1)) { _Pragma("unroll") for (int i = 0; i < 4; ++i) *(u32x4*)(as_ + asoff + i * 32 * 40) = ra[i]; } \
;     _Pragma("unroll") for (int i = 0; i < 4; ++i) *(u32x4*)(bs_ + bsoff + i * 64 * 40) = rb[i]; } while (0)
; template <int lda>
; DI void gemm_mainloop(const bfr* __restrict__ A, const bfr* __restrict__ Bt, int NB, int K, int m0, int n0, char* smem, f32x16 (&acc)[2][4]) {
;     ...
;   for (int kt = 0; kt < nk; ++kt) {
;     if (kt + 1 < nk) G_STORE(kt + 1);
;     if (kt + 2 < nk) {
;       GB_LOAD(kt + 2);
;       if ((kt & 1) == 0) GA_LOAD((kt >> 1) + 1);
;     }
;     const bfr* As = S0 + (kt & 1) * GSTAGE;
;     const bfr* Bs = As + 128 * 40;
; #pragma unroll
;     for (int ks = 0; ks < 2; ++ks) {
;       bf16x8 af[2], bfg[4];
; #pragma unroll
;       for (int i = 0; i < 2; ++i) af[i] = *(const bf16x8*)(As + (wr * 64 + i * 32 + r) * 40 + ks * 16 + hl * 8);
; #pragma unroll
;       for (int j = 0; j < 4; ++j) bfg[j] = *(const bf16x8*)(Bs + (wc * 128 + j * 32 + r) * 40 + ks * 16 + hl * 8);
; #pragma unroll
;       for (int i = 0; i < 2; ++i)
; #pragma unroll
;         for (int j = 0; j < 4; ++j) acc[i][j] = MFMA32(af[i], bfg[j], acc[i][j]);
;     }
;     __syncthreads();
;   }
.Lp1e_loop:
	s_waitcnt vmcnt(6)
	s_barrier
	s_mul_i32 s74, s70, 0x6000
	s_add_u32 s75, s74, s68
	s_mov_b32 m0, s75
	s_add_u32 s76, s74, 0x2000
	s_cmp_eq_u32 s70, 2
	s_cselect_b32 s76, 0x10000, s76
	global_load_lds_dwordx4 v160, s[64:65]
	s_add_u32 m0, s75, 0x400
	s_add_u32 s76, s76, s69
	global_load_lds_dwordx4 v162, s[64:65]
	s_mov_b32 m0, s76
	s_add_u32 s64, s64, 64
	s_addc_u32 s65, s65, 0
	global_load_lds_dwordx4 v163, s[66:67]
	global_load_lds_dwordx4 v163, s[66:67] offset:1024
	global_load_lds_dwordx4 v163, s[66:67] offset:2048
	global_load_lds_dwordx4 v163, s[66:67] offset:3072
	s_add_u32 s66, s66, 0x3a000
	s_addc_u32 s67, s67, 0
	s_add_u32 s70, s70, 1
	s_cmp_eq_u32 s70, 3
	s_cselect_b32 s70, 0, s70
	s_mul_i32 s74, s71, 0x6000
	s_add_u32 s75, s74, 0x2000
	s_cmp_eq_u32 s71, 2
	s_cselect_b32 s75, 0x10000, s75
	v_add_u32_e32 v184, s74, v180
	v_add_u32_e32 v186, s75, v182
	v_add_u32_e32 v185, s74, v181
	v_add_u32_e32 v187, s75, v183
	ds_read_b128 v[128:131], v184
	ds_read_b128 v[144:147], v186
	ds_read_b128 v[148:151], v186 offset:2048
	ds_read_b128 v[152:155], v186 offset:4096
	ds_read_b128 v[156:159], v186 offset:6144
	ds_read_b128 v[132:135], v184 offset:2048
	ds_read_b128 v[136:139], v185
	ds_read_b128 v[164:167], v187
	ds_read_b128 v[168:171], v187 offset:2048
	ds_read_b128 v[172:175], v187 offset:4096
	ds_read_b128 v[176:179], v187 offset:6144
	ds_read_b128 v[140:143], v185 offset:2048
	s_add_u32 s71, s71, 1
	s_cmp_eq_u32 s71, 3
	s_cselect_b32 s71, 0, s71
	s_waitcnt lgkmcnt(10)
	v_mfma_f32_32x32x16_bf16 v[112:127], v[128:131], v[144:147], v[112:127]
	s_waitcnt lgkmcnt(9)
	v_mfma_f32_32x32x16_bf16 v[96:111], v[128:131], v[148:151], v[96:111]
	s_waitcnt lgkmcnt(8)
	v_mfma_f32_32x32x16_bf16 v[80:95], v[128:131], v[152:155], v[80:95]
	s_waitcnt lgkmcnt(7)
	v_mfma_f32_32x32x16_bf16 v[64:79], v[128:131], v[156:159], v[64:79]
	s_waitcnt lgkmcnt(6)
	v_mfma_f32_32x32x16_bf16 v[48:63], v[132:135], v[144:147], v[48:63]
	v_mfma_f32_32x32x16_bf16 v[32:47], v[132:135], v[148:151], v[32:47]
	v_mfma_f32_32x32x16_bf16 v[16:31], v[132:135], v[152:155], v[16:31]
	v_mfma_f32_32x32x16_bf16 v[0:15], v[132:135], v[156:159], v[0:15]
	s_waitcnt lgkmcnt(4)
	v_mfma_f32_32x32x16_bf16 v[112:127], v[136:139], v[164:167], v[112:127]
	s_waitcnt lgkmcnt(3)
	v_mfma_f32_32x32x16_bf16 v[96:111], v[136:139], v[168:171], v[96:111]
	s_waitcnt lgkmcnt(2)
	v_mfma_f32_32x32x16_bf16 v[80:95], v[136:139], v[172:175], v[80:95]
	s_waitcnt lgkmcnt(1)
	v_mfma_f32_32x32x16_bf16 v[64:79], v[136:139], v[176:179], v[64:79]
	s_waitcnt lgkmcnt(0)
	v_mfma_f32_32x32x16_bf16 v[48:63], v[140:143], v[164:167], v[48:63]
	v_mfma_f32_32x32x16_bf16 v[32:47], v[140:143], v[168:171], v[32:47]
	v_mfma_f32_32x32x16_bf16 v[16:31], v[140:143], v[172:175], v[16:31]
	v_mfma_f32_32x32x16_bf16 v[0:15], v[140:143], v[176:179], v[0:15]
	s_add_u32 s72, s72, 1
	s_cmp_lt_u32 s72, 30
	s_cbranch_scc1 .Lp1e_loop
	s_waitcnt vmcnt(6)
	s_barrier
; #define MFMA32(a, b, c) __builtin_amdgcn_mfma_f32_32x32x16_bf16((a), (b), (c), 0, 0, 0)
; #define GA_LOAD(pr_) do { _Pragma("unroll") for (int i = 0; i < 4; ++i) ra[i] = *(const u32x4*)(Ab + (i * 32) * lda + (pr_) * 64); } while (0)
; #define GB_LOAD(kt_) do { const bfr* bk_ = Bb + (kt_) * NB * 32; \
;     _Pragma("unroll") for (int i = 0; i < 4; ++i) rb[i] = *(const u32x4*)(bk_ + (i * 64) * 32); } while (0)
; #define G_STORE(kt_) do { bfr* as_ = S0 + ((kt_) & 1) * GSTAGE; bfr* bs_ = as_ + 128 * 40; \
;     if (apar == ((kt_) & 1)) { _Pragma("unroll") for (int i = 0; i < 4; ++i) *(u32x4*)(as_ + asoff + i * 32 * 40) = ra[i]; } \
;     _Pragma("unroll") for (int i = 0; i < 4; ++i) *(u32x4*)(bs_ + bsoff + i * 64 * 40) = rb[i]; } while (0)
; template <int lda>
; DI void gemm_mainloop(const bfr* __restrict__ A, const bfr* __restrict__ Bt, int NB, int K, int m0, int n0, char* smem, f32x16 (&acc)[2][4]) {
;     ...
;   for (int kt = 0; kt < nk; ++kt) {
;     if (kt + 1 < nk) G_STORE(kt + 1);
;     if (kt + 2 < nk) {
;       GB_LOAD(kt + 2);
;       if ((kt & 1) == 0) GA_LOAD((kt >> 1) + 1);
;     }
;     const bfr* As = S0 + (kt & 1) * GSTAGE;
;     const bfr* Bs = As + 128 * 40;
; #pragma unroll
;     for (int ks = 0; ks < 2; ++ks) {
;       bf16x8 af[2], bfg[4];
; #pragma unroll
;       for (int i = 0; i < 2; ++i) af[i] = *(const bf16x8*)(As + (wr * 64 + i * 32 + r) * 40 + ks * 16 + hl * 8);
; #pragma unroll
;       for (int j = 0; j < 4; ++j) bfg[j] = *(const bf16x8*)(Bs + (wc * 128 + j * 32 + r) * 40 + ks * 16 + hl * 8);
; #pragma unroll
;       for (int i = 0; i < 2; ++i)
; #pragma unroll
;         for (int j = 0; j < 4; ++j) acc[i][j] = MFMA32(af[i], bfg[j], acc[i][j]);
;     }
;     __syncthreads();
;   }
	s_mul_i32 s74, s71, 0x6000
	s_add_u32 s75, s74, 0x2000
	s_cmp_eq_u32 s71, 2
	s_cselect_b32 s75, 0x10000, s75
	v_add_u32_e32 v184, s74, v180
	v_add_u32_e32 v186, s75, v182
	v_add_u32_e32 v185, s74, v181
	v_add_u32_e32 v187, s75, v183
	ds_read_b128 v[128:131], v184
	ds_read_b128 v[144:147], v186
	ds_read_b128 v[148:151], v186 offset:2048
	ds_read_b128 v[152:155], v186 offset:4096
	ds_read_b128 v[156:159], v186 offset:6144
	ds_read_b128 v[132:135], v184 offset:2048
	ds_read_b128 v[136:139], v185
	ds_read_b128 v[164:167], v187
	ds_read_b128 v[168:171], v187 offset:2048
	ds_read_b128 v[172:175], v187 offset:4096
	ds_read_b128 v[176:179], v187 offset:6144
	ds_read_b128 v[140:143], v185 offset:2048
	s_add_u32 s71, s71, 1
	s_cmp_eq_u32 s71, 3
	s_cselect_b32 s71, 0, s71
	s_waitcnt lgkmcnt(10)
	v_mfma_f32_32x32x16_bf16 v[112:127], v[128:131], v[144:147], v[112:127]
	s_waitcnt lgkmcnt(9)
	v_mfma_f32_32x32x16_bf16 v[96:111], v[128:131], v[148:151], v[96:111]
	s_waitcnt lgkmcnt(8)
	v_mfma_f32_32x32x16_bf16 v[80:95], v[128:131], v[152:155], v[80:95]
	s_waitcnt lgkmcnt(7)
	v_mfma_f32_32x32x16_bf16 v[64:79], v[128:131], v[156:159], v[64:79]
	s_waitcnt lgkmcnt(6)
	v_mfma_f32_32x32x16_bf16 v[48:63], v[132:135], v[144:147], v[48:63]
	v_mfma_f32_32x32x16_bf16 v[32:47], v[132:135], v[148:151], v[32:47]
	v_mfma_f32_32x32x16_bf16 v[16:31], v[132:135], v[152:155], v[16:31]
	v_mfma_f32_32x32x16_bf16 v[0:15], v[132:135], v[156:159], v[0:15]
	s_waitcnt lgkmcnt(4)
	v_mfma_f32_32x32x16_bf16 v[112:127], v[136:139], v[164:167], v[112:127]
	s_waitcnt lgkmcnt(3)
	v_mfma_f32_32x32x16_bf16 v[96:111], v[136:139], v[168:171], v[96:111]
	s_waitcnt lgkmcnt(2)
	v_mfma_f32_32x32x16_bf16 v[80:95], v[136:139], v[172:175], v[80:95]
	s_waitcnt lgkmcnt(1)
	v_mfma_f32_32x32x16_bf16 v[64:79], v[136:139], v[176:179], v[64:79]
	s_waitcnt lgkmcnt(0)
	v_mfma_f32_32x32x16_bf16 v[48:63], v[140:143], v[164:167], v[48:63]
	v_mfma_f32_32x32x16_bf16 v[32:47], v[140:143], v[168:171], v[32:47]
	v_mfma_f32_32x32x16_bf16 v[16:31], v[140:143], v[172:175], v[16:31]
	v_mfma_f32_32x32x16_bf16 v[0:15], v[140:143], v[176:179], v[0:15]
	s_waitcnt vmcnt(0)
	s_barrier
	s_mul_i32 s74, s71, 0x6000
	s_add_u32 s75, s74, 0x2000
	s_cmp_eq_u32 s71, 2
	s_cselect_b32 s75, 0x10000, s75
	v_add_u32_e32 v184, s74, v180
	v_add_u32_e32 v186, s75, v182
	v_add_u32_e32 v185, s74, v181
	v_add_u32_e32 v187, s75, v183
	ds_read_b128 v[128:131], v184
	ds_read_b128 v[144:147], v186
	ds_read_b128 v[148:151], v186 offset:2048
	ds_read_b128 v[152:155], v186 offset:4096
	ds_read_b128 v[156:159], v186 offset:6144
	ds_read_b128 v[132:135], v184 offset:2048
	ds_read_b128 v[136:139], v185
	ds_read_b128 v[164:167], v187
	ds_read_b128 v[168:171], v187 offset:2048
	ds_read_b128 v[172:175], v187 offset:4096
	ds_read_b128 v[176:179], v187 offset:6144
	ds_read_b128 v[140:143], v185 offset:2048
	s_add_u32 s71, s71, 1
	s_cmp_eq_u32 s71, 3
	s_cselect_b32 s71, 0, s71
	s_waitcnt lgkmcnt(10)
	v_mfma_f32_32x32x16_bf16 v[112:127], v[128:131], v[144:147], v[112:127]
	s_waitcnt lgkmcnt(9)
	v_mfma_f32_32x32x16_bf16 v[96:111], v[128:131], v[148:151], v[96:111]
	s_waitcnt lgkmcnt(8)
	v_mfma_f32_32x32x16_bf16 v[80:95], v[128:131], v[152:155], v[80:95]
	s_waitcnt lgkmcnt(7)
	v_mfma_f32_32x32x16_bf16 v[64:79], v[128:131], v[156:159], v[64:79]
	s_waitcnt lgkmcnt(6)
	v_mfma_f32_32x32x16_bf16 v[48:63], v[132:135], v[144:147], v[48:63]
	v_mfma_f32_32x32x16_bf16 v[32:47], v[132:135], v[148:151], v[32:47]
	v_mfma_f32_32x32x16_bf16 v[16:31], v[132:135], v[152:155], v[16:31]
	v_mfma_f32_32x32x16_bf16 v[0:15], v[132:135], v[156:159], v[0:15]
	s_waitcnt lgkmcnt(4)
	v_mfma_f32_32x32x16_bf16 v[112:127], v[136:139], v[164:167], v[112:127]
	s_waitcnt lgkmcnt(3)
	v_mfma_f32_32x32x16_bf16 v[96:111], v[136:139], v[168:171], v[96:111]
	s_waitcnt lgkmcnt(2)
	v_mfma_f32_32x32x16_bf16 v[80:95], v[136:139], v[172:175], v[80:95]
	s_waitcnt lgkmcnt(1)
	v_mfma_f32_32x32x16_bf16 v[64:79], v[136:139], v[176:179], v[64:79]
	s_waitcnt lgkmcnt(0)
	v_mfma_f32_32x32x16_bf16 v[48:63], v[140:143], v[164:167], v[48:63]
	v_mfma_f32_32x32x16_bf16 v[32:47], v[140:143], v[168:171], v[32:47]
	v_mfma_f32_32x32x16_bf16 v[16:31], v[140:143], v[172:175], v[16:31]
	v_mfma_f32_32x32x16_bf16 v[0:15], v[140:143], v[176:179], v[0:15]
	s_nop 7
	v_readlane_b32 s64, v188, 0
	v_readlane_b32 s65, v188, 1
	v_readlane_b32 s66, v188, 2
	v_readlane_b32 s67, v188, 3
	v_readlane_b32 s68, v188, 4
	v_readlane_b32 s69, v188, 5
	v_readlane_b32 s70, v188, 6
	v_readlane_b32 s71, v188, 7
	v_readlane_b32 s72, v188, 8
	v_readlane_b32 s73, v188, 9
	v_readlane_b32 s74, v188, 10
	v_readlane_b32 s75, v188, 11
	v_readlane_b32 s76, v188, 12
	v_readlane_b32 s77, v188, 13
	v_readlane_b32 s78, v188, 14
	v_readlane_b32 s79, v188, 15
	s_nop 7
	s_branch .LBB0_118
